# DeltaNet DK: hand-written forward substitution and TW/TU store replacing the vectorised region (one v_fma per term, row reads 4 ahead)
# speedup vs baseline: 1.0081x; 1.0081x over previous
; __device__ __forceinline__ unsigned pk2(float lo, float hi) { const f32x2_cv v = {lo, hi}; const bf16x2_cv b = __builtin_convertvector(v, bf16x2_cv); return __builtin_bit_cast(unsigned, b); }
; __device__ __forceinline__ int crow16(int r, int hi) { return (r & 3) + 8 * (r >> 2) + 4 * hi; }
; __device__ __forceinline__ void dk_phase(const Frame& F, const bf16* QKrm, const unsigned char* KT, const unsigned char* VT, const float* BG, unsigned char* ITEMS) {
;     ...
;         {
;             bf16x8_t Qn[2][8];
; #pragma unroll
;             for (int mi = 0; mi < 2; ++mi)
; #pragma unroll
;                 for (int ks = 0; ks < 8; ++ks) Qn[mi][ks] = as_frag(*(const v4u*)(Qb + (size_t)(32 * mi + r32) * 4096 + 16 * ks));
; #pragma unroll
;             for (int ri = 0; ri < 2; ++ri) { const int r = 32 * ri + r32; const float gr = gamL[r];
; #pragma unroll
;                 for (int si = 0; si < 2; ++si) { f32x16_t p = f32x16_t{};
; #pragma unroll
;                     for (int ks = 0; ks < 8; ++ks) p = __builtin_amdgcn_mfma_f32_32x32x16_bf16(Kn[si][ks], Qn[ri][ks], p, 0, 0, 0);
;                     float pv[16];
; #pragma unroll
;                     for (int rg = 0; rg < 16; ++rg) { const int s = 32 * si + crow16(rg, hi); const float gs = gamL[s];
;                         const bool ok = dir ? (s >= r) : (s <= r);
;                         pv[rg] = ok ? p[rg] * __expf(gr - gs) : 0.f; }
; #pragma unroll
;                     for (int st = 0; st < 2; ++st) { v4u wv; wv.x = pk2(pv[8 * st + 0], pv[8 * st + 1]); wv.y = pk2(pv[8 * st + 2], pv[8 * st + 3]); wv.z = pk2(pv[8 * st + 4], pv[8 * st + 5]); wv.w = pk2(pv[8 * st + 6], pv[8 * st + 7]);
;                         *(v4u*)(item + ITEM_AQK + ((ri * 2 + si) * 2 + st) * 1024 + lane * 16) = wv; } } }
.LBB0_460:
	s_or_b64 exec, exec, s[20:21]
	v_add_u32_e32 v5, v20, v50
	ds_write_b32 v5, v4
	s_lshl_b32 s20, s46, 1
	s_add_u32 s42, s44, s20
	s_addc_u32 s43, s45, 0
	s_ashr_i32 s20, s52, 6
	v_lshl_add_u64 v[4:5], v[164:165], 1, s[42:43]
	v_lshlrev_b32_e32 v6, 1, v132
	v_mov_b32_e32 v7, v3
	v_lshl_add_u64 v[6:7], v[4:5], 0, v[6:7]
	global_load_dwordx4 v[160:163], v[6:7], off
	global_load_dwordx4 v[156:159], v[6:7], off offset:32
	global_load_dwordx4 v[152:155], v[6:7], off offset:64
	global_load_dwordx4 v[148:151], v[6:7], off offset:96
	global_load_dwordx4 v[144:147], v[6:7], off offset:128
	global_load_dwordx4 v[140:143], v[6:7], off offset:160
	global_load_dwordx4 v[132:135], v[6:7], off offset:192
	global_load_dwordx4 v[136:139], v[6:7], off offset:224
	v_lshl_add_u64 v[4:5], v[4:5], 0, v[2:3]
	s_waitcnt lgkmcnt(14)
	global_load_dwordx4 v[48:51], v[4:5], off
	global_load_dwordx4 v[44:47], v[4:5], off offset:32
	global_load_dwordx4 v[40:43], v[4:5], off offset:64
	global_load_dwordx4 v[36:39], v[4:5], off offset:96
	global_load_dwordx4 v[32:35], v[4:5], off offset:128
	global_load_dwordx4 v[28:31], v[4:5], off offset:160
	global_load_dwordx4 v[20:23], v[4:5], off offset:192
	global_load_dwordx4 v[24:27], v[4:5], off offset:224
	v_add_u32_e32 v2, 0x4400, v170
	ds_read2_b32 v[180:181], v2 offset1:32
	ds_read_b128 v[56:59], v226 offset:17408
	ds_read_b128 v[52:55], v226 offset:17440
	v_cmp_ge_i32_e64 s[42:43], v223, v186
	v_cmp_le_i32_e64 s[44:45], v223, v186
	v_cmp_lt_i32_e64 s[46:47], v223, v186
	v_cndmask_b32_e64 v61, 0, 1, s[42:43]
	v_cndmask_b32_e64 v60, 0, 1, s[44:45]
	v_cndmask_b32_e64 v60, v61, v60, s[40:41]
	v_and_b32_e32 v60, 1, v60
	v_cmp_eq_u32_e64 s[42:43], 1, v60
	s_waitcnt lgkmcnt(1)
	v_sub_f32_e32 v60, v180, v56
	v_mul_f32_e32 v60, 0x3fb8aa3b, v60
	v_exp_f32_e32 v60, v60
	v_cmp_ge_i32_e64 s[44:45], v225, v186
	v_cndmask_b32_e64 v165, 0, 1, s[46:47]
	v_cmp_le_i32_e64 s[46:47], v224, v186
	v_lshlrev_b32_e32 v168, 4, v185
	v_ashrrev_i32_e32 v169, 31, v168
	v_lshl_add_u64 v[166:167], s[18:19], 0, v[168:169]
	s_movk_i32 s21, 0xa000
	v_sub_f32_e32 v56, v181, v56
	v_mul_f32_e32 v56, 0x3fb8aa3b, v56
	v_exp_f32_e32 v56, v56
	v_mov_b32_e32 v2, s53
	s_waitcnt vmcnt(15)
	v_mfma_f32_32x32x16_bf16 v[4:19], v[124:127], v[160:163], 0
	s_waitcnt vmcnt(14)
	v_mfma_f32_32x32x16_bf16 v[4:19], v[120:123], v[156:159], v[4:19]
	s_waitcnt vmcnt(13)
	v_mfma_f32_32x32x16_bf16 v[4:19], v[128:131], v[152:155], v[4:19]
	s_waitcnt vmcnt(12)
	v_mfma_f32_32x32x16_bf16 v[4:19], v[116:119], v[148:151], v[4:19]
	s_waitcnt vmcnt(11)
	v_mfma_f32_32x32x16_bf16 v[4:19], v[112:115], v[144:147], v[4:19]
	s_waitcnt vmcnt(10)
	v_mfma_f32_32x32x16_bf16 v[4:19], v[108:111], v[140:143], v[4:19]
	s_waitcnt vmcnt(9)
	v_mfma_f32_32x32x16_bf16 v[4:19], v[104:107], v[132:135], v[4:19]
	s_waitcnt vmcnt(8)
	v_mfma_f32_32x32x16_bf16 v[4:19], v[100:103], v[136:139], v[4:19]
	s_nop 11
	v_mul_f32_e32 v4, v4, v60
	v_cndmask_b32_e64 v60, 0, 1, s[44:45]
	v_cndmask_b32_e64 v60, v60, v165, s[40:41]
	v_and_b32_e32 v60, 1, v60
	v_cmp_eq_u32_e64 s[44:45], 1, v60
	v_sub_f32_e32 v60, v180, v57
	v_mul_f32_e32 v60, 0x3fb8aa3b, v60
	v_exp_f32_e32 v60, v60
	v_cndmask_b32_e64 v4, 0, v4, s[42:43]
	v_mul_f32_e32 v5, v5, v60
	v_cndmask_b32_e64 v5, 0, v5, s[44:45]
	v_cmp_ge_i32_e64 s[44:45], v224, v186
	v_cndmask_b32_e64 v60, 0, 1, s[46:47]
	v_cmp_le_i32_e64 s[46:47], v222, v186
	v_cndmask_b32_e64 v61, 0, 1, s[44:45]
	v_cndmask_b32_e64 v60, v61, v60, s[40:41]
	v_and_b32_e32 v60, 1, v60
	v_cmp_eq_u32_e64 s[44:45], 1, v60
	v_sub_f32_e32 v60, v180, v58
	v_mul_f32_e32 v60, 0x3fb8aa3b, v60
	v_exp_f32_e32 v60, v60
	v_cvt_pk_bf16_f32 v4, v4, v5
	v_mul_f32_e32 v6, v6, v60
	v_cndmask_b32_e64 v6, 0, v6, s[44:45]
	v_cmp_ge_i32_e64 s[44:45], v222, v186
	v_cndmask_b32_e64 v60, 0, 1, s[46:47]
	v_cmp_le_i32_e64 s[46:47], v221, v186
	v_cndmask_b32_e64 v61, 0, 1, s[44:45]
	v_cndmask_b32_e64 v60, v61, v60, s[40:41]
	v_and_b32_e32 v60, 1, v60
	v_cmp_eq_u32_e64 s[44:45], 1, v60
	v_sub_f32_e32 v60, v180, v59
	v_mul_f32_e32 v60, 0x3fb8aa3b, v60
	v_exp_f32_e32 v60, v60
	s_nop 0
	v_mul_f32_e32 v7, v7, v60
	v_cndmask_b32_e64 v7, 0, v7, s[44:45]
	v_cmp_ge_i32_e64 s[44:45], v221, v186
	v_cndmask_b32_e64 v60, 0, 1, s[46:47]
	v_cmp_le_i32_e64 s[46:47], v220, v186
	v_cndmask_b32_e64 v61, 0, 1, s[44:45]
	v_cndmask_b32_e64 v60, v61, v60, s[40:41]
	v_and_b32_e32 v60, 1, v60
	v_cmp_eq_u32_e64 s[44:45], 1, v60
	s_waitcnt lgkmcnt(0)
	v_sub_f32_e32 v60, v180, v52
	v_mul_f32_e32 v60, 0x3fb8aa3b, v60
	v_exp_f32_e32 v60, v60
	v_cvt_pk_bf16_f32 v5, v6, v7
	v_sub_f32_e32 v52, v181, v52
	v_mul_f32_e32 v52, 0x3fb8aa3b, v52
	v_mul_f32_e32 v8, v8, v60
	v_cndmask_b32_e64 v8, 0, v8, s[44:45]
	v_cmp_ge_i32_e64 s[44:45], v220, v186
	v_cndmask_b32_e64 v60, 0, 1, s[46:47]
	v_cmp_le_i32_e64 s[46:47], v219, v186
	v_cndmask_b32_e64 v61, 0, 1, s[44:45]
	v_cndmask_b32_e64 v60, v61, v60, s[40:41]
	v_and_b32_e32 v60, 1, v60
	v_cmp_eq_u32_e64 s[44:45], 1, v60
	v_sub_f32_e32 v60, v180, v53
	v_mul_f32_e32 v60, 0x3fb8aa3b, v60
	v_exp_f32_e32 v60, v60
	v_exp_f32_e32 v52, v52
	v_mul_f32_e32 v9, v9, v60
	v_cndmask_b32_e64 v9, 0, v9, s[44:45]
	v_cmp_ge_i32_e64 s[44:45], v219, v186
	v_cndmask_b32_e64 v60, 0, 1, s[46:47]
	v_cmp_le_i32_e64 s[46:47], v218, v186
	v_cndmask_b32_e64 v61, 0, 1, s[44:45]
	v_cndmask_b32_e64 v60, v61, v60, s[40:41]
	v_and_b32_e32 v60, 1, v60
	v_cmp_eq_u32_e64 s[44:45], 1, v60
	v_sub_f32_e32 v60, v180, v54
	v_mul_f32_e32 v60, 0x3fb8aa3b, v60
	v_exp_f32_e32 v60, v60
	v_cvt_pk_bf16_f32 v6, v8, v9
	v_mul_f32_e32 v10, v10, v60
	v_cndmask_b32_e64 v10, 0, v10, s[44:45]
	v_cmp_ge_i32_e64 s[44:45], v218, v186
	v_cndmask_b32_e64 v60, 0, 1, s[46:47]
	v_cmp_le_i32_e64 s[46:47], v217, v186
	v_cndmask_b32_e64 v61, 0, 1, s[44:45]
	v_cndmask_b32_e64 v60, v61, v60, s[40:41]
	v_and_b32_e32 v60, 1, v60
	v_cmp_eq_u32_e64 s[44:45], 1, v60
	v_sub_f32_e32 v60, v180, v55
	v_mul_f32_e32 v60, 0x3fb8aa3b, v60
	v_exp_f32_e32 v60, v60
	v_cndmask_b32_e64 v64, 0, 1, s[46:47]
	v_cmp_le_i32_e64 s[46:47], v216, v186
	v_mul_f32_e32 v11, v11, v60
	ds_read_b128 v[60:63], v226 offset:17472
	v_cndmask_b32_e64 v11, 0, v11, s[44:45]
	v_cmp_ge_i32_e64 s[44:45], v217, v186
	v_cvt_pk_bf16_f32 v7, v10, v11
	s_nop 0
	v_cndmask_b32_e64 v65, 0, 1, s[44:45]
	v_cndmask_b32_e64 v64, v65, v64, s[40:41]
	v_and_b32_e32 v64, 1, v64
	v_cmp_eq_u32_e64 s[44:45], 1, v64
	s_waitcnt lgkmcnt(0)
; __device__ __forceinline__ unsigned pk2(float lo, float hi) { const f32x2_cv v = {lo, hi}; const bf16x2_cv b = __builtin_convertvector(v, bf16x2_cv); return __builtin_bit_cast(unsigned, b); }
; __device__ __forceinline__ int crow16(int r, int hi) { return (r & 3) + 8 * (r >> 2) + 4 * hi; }
; __device__ __forceinline__ void dk_phase(const Frame& F, const bf16* QKrm, const unsigned char* KT, const unsigned char* VT, const float* BG, unsigned char* ITEMS) {
;     ...
; #pragma unroll
;             for (int ri = 0; ri < 2; ++ri) { const int r = 32 * ri + r32; const float gr = gamL[r];
; #pragma unroll
;                 for (int si = 0; si < 2; ++si) { f32x16_t p = f32x16_t{};
; #pragma unroll
;                     for (int ks = 0; ks < 8; ++ks) p = __builtin_amdgcn_mfma_f32_32x32x16_bf16(Kn[si][ks], Qn[ri][ks], p, 0, 0, 0);
;                     float pv[16];
; #pragma unroll
;                     for (int rg = 0; rg < 16; ++rg) { const int s = 32 * si + crow16(rg, hi); const float gs = gamL[s];
;                         const bool ok = dir ? (s >= r) : (s <= r);
;                         pv[rg] = ok ? p[rg] * __expf(gr - gs) : 0.f; }
; #pragma unroll
;                     for (int st = 0; st < 2; ++st) { v4u wv; wv.x = pk2(pv[8 * st + 0], pv[8 * st + 1]); wv.y = pk2(pv[8 * st + 2], pv[8 * st + 3]); wv.z = pk2(pv[8 * st + 4], pv[8 * st + 5]); wv.w = pk2(pv[8 * st + 6], pv[8 * st + 7]);
;                         *(v4u*)(item + ITEM_AQK + ((ri * 2 + si) * 2 + st) * 1024 + lane * 16) = wv; } } }
	v_sub_f32_e32 v64, v180, v60
	v_mul_f32_e32 v64, 0x3fb8aa3b, v64
	v_exp_f32_e32 v64, v64
	s_nop 0
	v_mul_f32_e32 v12, v12, v64
	v_cndmask_b32_e64 v12, 0, v12, s[44:45]
	v_cmp_ge_i32_e64 s[44:45], v216, v186
	v_cndmask_b32_e64 v64, 0, 1, s[46:47]
	v_cmp_le_i32_e64 s[46:47], v215, v186
	v_cndmask_b32_e64 v65, 0, 1, s[44:45]
	v_cndmask_b32_e64 v64, v65, v64, s[40:41]
	v_and_b32_e32 v64, 1, v64
	v_cmp_eq_u32_e64 s[44:45], 1, v64
	v_sub_f32_e32 v64, v180, v61
	v_mul_f32_e32 v64, 0x3fb8aa3b, v64
	v_exp_f32_e32 v64, v64
	s_nop 0
	v_mul_f32_e32 v13, v13, v64
	v_cndmask_b32_e64 v13, 0, v13, s[44:45]
	v_cmp_ge_i32_e64 s[44:45], v215, v186
	v_cndmask_b32_e64 v64, 0, 1, s[46:47]
	v_cmp_le_i32_e64 s[46:47], v214, v186
	v_cndmask_b32_e64 v65, 0, 1, s[44:45]
	v_cndmask_b32_e64 v64, v65, v64, s[40:41]
	v_and_b32_e32 v64, 1, v64
	v_cmp_eq_u32_e64 s[44:45], 1, v64
	v_sub_f32_e32 v64, v180, v62
	v_mul_f32_e32 v64, 0x3fb8aa3b, v64
	v_exp_f32_e32 v64, v64
	s_nop 0
	v_mul_f32_e32 v14, v14, v64
	v_cndmask_b32_e64 v14, 0, v14, s[44:45]
	v_cmp_ge_i32_e64 s[44:45], v214, v186
	v_cndmask_b32_e64 v64, 0, 1, s[46:47]
	v_cmp_le_i32_e64 s[46:47], v213, v186
	v_cndmask_b32_e64 v65, 0, 1, s[44:45]
	v_cndmask_b32_e64 v64, v65, v64, s[40:41]
	v_and_b32_e32 v64, 1, v64
	v_cmp_eq_u32_e64 s[44:45], 1, v64
	v_sub_f32_e32 v64, v180, v63
	v_mul_f32_e32 v64, 0x3fb8aa3b, v64
	v_exp_f32_e32 v64, v64
	v_cndmask_b32_e64 v170, 0, 1, s[46:47]
	v_cmp_le_i32_e64 s[46:47], v203, v186
	v_mul_f32_e32 v15, v15, v64
	ds_read_b128 v[64:67], v226 offset:17504
	v_cndmask_b32_e64 v15, 0, v15, s[44:45]
	v_cmp_ge_i32_e64 s[44:45], v213, v186
	s_nop 1
	v_cndmask_b32_e64 v171, 0, 1, s[44:45]
	v_cndmask_b32_e64 v170, v171, v170, s[40:41]
	v_and_b32_e32 v170, 1, v170
	v_cmp_eq_u32_e64 s[44:45], 1, v170
	s_waitcnt lgkmcnt(0)
	v_sub_f32_e32 v170, v180, v64
	v_mul_f32_e32 v170, 0x3fb8aa3b, v170
	v_exp_f32_e32 v170, v170
	s_nop 0
	v_mul_f32_e32 v16, v16, v170
	v_cndmask_b32_e64 v16, 0, v16, s[44:45]
	v_cmp_ge_i32_e64 s[44:45], v203, v186
	v_cndmask_b32_e64 v170, 0, 1, s[46:47]
	v_cmp_le_i32_e64 s[46:47], v211, v186
	v_cndmask_b32_e64 v171, 0, 1, s[44:45]
	v_cndmask_b32_e64 v170, v171, v170, s[40:41]
	v_and_b32_e32 v170, 1, v170
	v_cmp_eq_u32_e64 s[44:45], 1, v170
	v_sub_f32_e32 v170, v180, v65
	v_mul_f32_e32 v170, 0x3fb8aa3b, v170
	v_exp_f32_e32 v170, v170
	s_nop 0
	v_mul_f32_e32 v17, v17, v170
	v_cndmask_b32_e64 v17, 0, v17, s[44:45]
	v_cmp_ge_i32_e64 s[44:45], v211, v186
	v_cndmask_b32_e64 v170, 0, 1, s[46:47]
	v_cmp_le_i32_e64 s[46:47], v212, v186
	v_cndmask_b32_e64 v171, 0, 1, s[44:45]
	v_cndmask_b32_e64 v170, v171, v170, s[40:41]
	v_and_b32_e32 v170, 1, v170
	v_cmp_eq_u32_e64 s[44:45], 1, v170
	v_sub_f32_e32 v170, v180, v66
	v_mul_f32_e32 v170, 0x3fb8aa3b, v170
	v_exp_f32_e32 v170, v170
	s_nop 0
	v_mul_f32_e32 v18, v18, v170
	v_cndmask_b32_e64 v18, 0, v18, s[44:45]
	v_cmp_ge_i32_e64 s[44:45], v212, v186
	v_cndmask_b32_e64 v170, 0, 1, s[46:47]
	v_cmp_le_i32_e64 s[46:47], v227, v186
	v_cndmask_b32_e64 v171, 0, 1, s[44:45]
	v_cndmask_b32_e64 v170, v171, v170, s[40:41]
	v_and_b32_e32 v170, 1, v170
	v_cmp_eq_u32_e64 s[44:45], 1, v170
	v_sub_f32_e32 v170, v180, v67
	v_mul_f32_e32 v170, 0x3fb8aa3b, v170
	v_exp_f32_e32 v170, v170
	s_nop 0
	v_mul_f32_e32 v19, v19, v170
	v_cndmask_b32_e64 v19, 0, v19, s[44:45]
	v_add_co_u32_e64 v170, s[44:45], s21, v166
	s_movk_i32 s21, 0xb000
	s_nop 0
	v_addc_co_u32_e64 v171, s[44:45], -1, v167, s[44:45]
	v_add_co_u32_e64 v182, s[44:45], s21, v166
	global_store_dwordx4 v[170:171], v[4:7], off offset:-512
	s_nop 0
	v_addc_co_u32_e64 v183, s[44:45], -1, v167, s[44:45]
	v_cvt_pk_bf16_f32 v4, v12, v13
	v_cvt_pk_bf16_f32 v5, v14, v15
	v_cvt_pk_bf16_f32 v6, v16, v17
	v_cvt_pk_bf16_f32 v7, v18, v19
	global_store_dwordx4 v[182:183], v[4:7], off offset:-3584
	v_cmp_ge_i32_e64 s[44:45], v227, v186
	s_nop 0
	v_mfma_f32_32x32x16_bf16 v[4:19], v[96:99], v[160:163], 0
	v_mfma_f32_32x32x16_bf16 v[4:19], v[88:91], v[156:159], v[4:19]
	v_mfma_f32_32x32x16_bf16 v[4:19], v[92:95], v[152:155], v[4:19]
	v_mfma_f32_32x32x16_bf16 v[4:19], v[84:87], v[148:151], v[4:19]
	v_mfma_f32_32x32x16_bf16 v[4:19], v[80:83], v[144:147], v[4:19]
	v_mfma_f32_32x32x16_bf16 v[4:19], v[76:79], v[140:143], v[4:19]
	v_cndmask_b32_e64 v140, 0, 1, s[46:47]
	v_cndmask_b32_e64 v141, 0, 1, s[44:45]
	v_cndmask_b32_e64 v140, v141, v140, s[40:41]
	v_and_b32_e32 v140, 1, v140
	v_cmp_eq_u32_e64 s[44:45], 1, v140
	v_cmp_lt_i32_e64 s[46:47], v227, v186
	v_mfma_f32_32x32x16_bf16 v[4:19], v[68:71], v[132:135], v[4:19]
	v_mfma_f32_32x32x16_bf16 v[4:19], v[72:75], v[136:139], v[4:19]
	ds_read_b128 v[136:139], v226 offset:17536
	ds_read_b128 v[132:135], v226 offset:17568
	s_waitcnt lgkmcnt(1)
	v_sub_f32_e32 v140, v180, v136
	v_mul_f32_e32 v140, 0x3fb8aa3b, v140
	v_exp_f32_e32 v140, v140
	s_nop 5
	v_mul_f32_e32 v4, v4, v140
	v_cndmask_b32_e64 v4, 0, v4, s[44:45]
	v_cmp_ge_i32_e64 s[44:45], v202, v186
	v_cndmask_b32_e64 v140, 0, 1, s[46:47]
	v_cmp_le_i32_e64 s[46:47], v201, v186
	v_cndmask_b32_e64 v141, 0, 1, s[44:45]
	v_cndmask_b32_e64 v140, v141, v140, s[40:41]
	v_and_b32_e32 v140, 1, v140
	v_cmp_eq_u32_e64 s[44:45], 1, v140
	v_sub_f32_e32 v140, v180, v137
	v_mul_f32_e32 v140, 0x3fb8aa3b, v140
	v_exp_f32_e32 v140, v140
	s_nop 0
	v_mul_f32_e32 v5, v5, v140
	v_cndmask_b32_e64 v5, 0, v5, s[44:45]
	v_cmp_ge_i32_e64 s[44:45], v201, v186
	v_cndmask_b32_e64 v140, 0, 1, s[46:47]
	v_cmp_le_i32_e64 s[46:47], v200, v186
	v_cndmask_b32_e64 v141, 0, 1, s[44:45]
	v_cndmask_b32_e64 v140, v141, v140, s[40:41]
	v_and_b32_e32 v140, 1, v140
	v_cmp_eq_u32_e64 s[44:45], 1, v140
	v_sub_f32_e32 v140, v180, v138
	v_mul_f32_e32 v140, 0x3fb8aa3b, v140
	v_exp_f32_e32 v140, v140
	v_cvt_pk_bf16_f32 v4, v4, v5
	v_mul_f32_e32 v6, v6, v140
	v_cndmask_b32_e64 v6, 0, v6, s[44:45]
	v_cmp_ge_i32_e64 s[44:45], v200, v186
	v_cndmask_b32_e64 v140, 0, 1, s[46:47]
	v_cmp_le_i32_e64 s[46:47], v199, v186
	v_cndmask_b32_e64 v141, 0, 1, s[44:45]
	v_cndmask_b32_e64 v140, v141, v140, s[40:41]
	v_and_b32_e32 v140, 1, v140
	v_cmp_eq_u32_e64 s[44:45], 1, v140
	v_sub_f32_e32 v140, v180, v139
	v_mul_f32_e32 v140, 0x3fb8aa3b, v140
	v_exp_f32_e32 v140, v140
	s_nop 0
	v_mul_f32_e32 v7, v7, v140
	v_cndmask_b32_e64 v7, 0, v7, s[44:45]
	v_cmp_ge_i32_e64 s[44:45], v199, v186
	v_cndmask_b32_e64 v140, 0, 1, s[46:47]
	v_cmp_le_i32_e64 s[46:47], v198, v186
	v_cndmask_b32_e64 v141, 0, 1, s[44:45]
	v_cndmask_b32_e64 v140, v141, v140, s[40:41]
	v_and_b32_e32 v140, 1, v140
	v_cmp_eq_u32_e64 s[44:45], 1, v140
	s_waitcnt lgkmcnt(0)
; __device__ __forceinline__ unsigned pk2(float lo, float hi) { const f32x2_cv v = {lo, hi}; const bf16x2_cv b = __builtin_convertvector(v, bf16x2_cv); return __builtin_bit_cast(unsigned, b); }
; __device__ __forceinline__ int crow16(int r, int hi) { return (r & 3) + 8 * (r >> 2) + 4 * hi; }
; __device__ __forceinline__ void dk_phase(const Frame& F, const bf16* QKrm, const unsigned char* KT, const unsigned char* VT, const float* BG, unsigned char* ITEMS) {
;     ...
; #pragma unroll
;             for (int ri = 0; ri < 2; ++ri) { const int r = 32 * ri + r32; const float gr = gamL[r];
; #pragma unroll
;                 for (int si = 0; si < 2; ++si) { f32x16_t p = f32x16_t{};
; #pragma unroll
;                     for (int ks = 0; ks < 8; ++ks) p = __builtin_amdgcn_mfma_f32_32x32x16_bf16(Kn[si][ks], Qn[ri][ks], p, 0, 0, 0);
;                     float pv[16];
; #pragma unroll
;                     for (int rg = 0; rg < 16; ++rg) { const int s = 32 * si + crow16(rg, hi); const float gs = gamL[s];
;                         const bool ok = dir ? (s >= r) : (s <= r);
;                         pv[rg] = ok ? p[rg] * __expf(gr - gs) : 0.f; }
; #pragma unroll
;                     for (int st = 0; st < 2; ++st) { v4u wv; wv.x = pk2(pv[8 * st + 0], pv[8 * st + 1]); wv.y = pk2(pv[8 * st + 2], pv[8 * st + 3]); wv.z = pk2(pv[8 * st + 4], pv[8 * st + 5]); wv.w = pk2(pv[8 * st + 6], pv[8 * st + 7]);
;                         *(v4u*)(item + ITEM_AQK + ((ri * 2 + si) * 2 + st) * 1024 + lane * 16) = wv; } } }
	v_sub_f32_e32 v140, v180, v132
	v_mul_f32_e32 v140, 0x3fb8aa3b, v140
	v_exp_f32_e32 v140, v140
	v_cvt_pk_bf16_f32 v5, v6, v7
	v_mul_f32_e32 v8, v8, v140
	v_cndmask_b32_e64 v8, 0, v8, s[44:45]
	v_cmp_ge_i32_e64 s[44:45], v198, v186
	v_cndmask_b32_e64 v140, 0, 1, s[46:47]
	v_cmp_le_i32_e64 s[46:47], v197, v186
	v_cndmask_b32_e64 v141, 0, 1, s[44:45]
	v_cndmask_b32_e64 v140, v141, v140, s[40:41]
	v_and_b32_e32 v140, 1, v140
	v_cmp_eq_u32_e64 s[44:45], 1, v140
	v_sub_f32_e32 v140, v180, v133
	v_mul_f32_e32 v140, 0x3fb8aa3b, v140
	v_exp_f32_e32 v140, v140
	s_nop 0
	v_mul_f32_e32 v9, v9, v140
	v_cndmask_b32_e64 v9, 0, v9, s[44:45]
	v_cmp_ge_i32_e64 s[44:45], v197, v186
	v_cndmask_b32_e64 v140, 0, 1, s[46:47]
	v_cmp_le_i32_e64 s[46:47], v196, v186
	v_cndmask_b32_e64 v141, 0, 1, s[44:45]
	v_cndmask_b32_e64 v140, v141, v140, s[40:41]
	v_and_b32_e32 v140, 1, v140
	v_cmp_eq_u32_e64 s[44:45], 1, v140
	v_sub_f32_e32 v140, v180, v134
	v_mul_f32_e32 v140, 0x3fb8aa3b, v140
	v_exp_f32_e32 v140, v140
	v_cvt_pk_bf16_f32 v6, v8, v9
	v_mul_f32_e32 v10, v10, v140
	v_cndmask_b32_e64 v10, 0, v10, s[44:45]
	v_cmp_ge_i32_e64 s[44:45], v196, v186
	v_cndmask_b32_e64 v140, 0, 1, s[46:47]
	v_cmp_le_i32_e64 s[46:47], v195, v186
	v_cndmask_b32_e64 v141, 0, 1, s[44:45]
	v_cndmask_b32_e64 v140, v141, v140, s[40:41]
	v_and_b32_e32 v140, 1, v140
	v_cmp_eq_u32_e64 s[44:45], 1, v140
	v_sub_f32_e32 v140, v180, v135
	v_mul_f32_e32 v140, 0x3fb8aa3b, v140
	v_exp_f32_e32 v140, v140
	v_cndmask_b32_e64 v144, 0, 1, s[46:47]
	v_cmp_le_i32_e64 s[46:47], v194, v186
	v_mul_f32_e32 v11, v11, v140
	ds_read_b128 v[140:143], v226 offset:17600
	v_cndmask_b32_e64 v11, 0, v11, s[44:45]
	v_cmp_ge_i32_e64 s[44:45], v195, v186
	v_cvt_pk_bf16_f32 v7, v10, v11
	global_store_dwordx4 v[182:183], v[4:7], off offset:-2560
	v_cndmask_b32_e64 v145, 0, 1, s[44:45]
	v_cndmask_b32_e64 v144, v145, v144, s[40:41]
	v_and_b32_e32 v144, 1, v144
	v_cmp_eq_u32_e64 s[44:45], 1, v144
	s_waitcnt lgkmcnt(0)
	v_sub_f32_e32 v144, v180, v140
	v_mul_f32_e32 v144, 0x3fb8aa3b, v144
	v_exp_f32_e32 v144, v144
	s_nop 0
	v_mul_f32_e32 v12, v12, v144
	v_cndmask_b32_e64 v12, 0, v12, s[44:45]
	v_cmp_ge_i32_e64 s[44:45], v194, v186
	v_cndmask_b32_e64 v144, 0, 1, s[46:47]
	v_cmp_le_i32_e64 s[46:47], v193, v186
	v_cndmask_b32_e64 v145, 0, 1, s[44:45]
	v_cndmask_b32_e64 v144, v145, v144, s[40:41]
	v_and_b32_e32 v144, 1, v144
	v_cmp_eq_u32_e64 s[44:45], 1, v144
	v_sub_f32_e32 v144, v180, v141
	v_mul_f32_e32 v144, 0x3fb8aa3b, v144
	v_exp_f32_e32 v144, v144
	s_nop 0
	v_mul_f32_e32 v13, v13, v144
	v_cndmask_b32_e64 v13, 0, v13, s[44:45]
	v_cmp_ge_i32_e64 s[44:45], v193, v186
	v_cndmask_b32_e64 v144, 0, 1, s[46:47]
	v_cmp_le_i32_e64 s[46:47], v192, v186
	v_cndmask_b32_e64 v145, 0, 1, s[44:45]
	v_cndmask_b32_e64 v144, v145, v144, s[40:41]
	v_and_b32_e32 v144, 1, v144
	v_cmp_eq_u32_e64 s[44:45], 1, v144
	v_sub_f32_e32 v144, v180, v142
	v_mul_f32_e32 v144, 0x3fb8aa3b, v144
	v_exp_f32_e32 v144, v144
	v_cvt_pk_bf16_f32 v4, v12, v13
	v_mul_f32_e32 v14, v14, v144
	v_cndmask_b32_e64 v14, 0, v14, s[44:45]
	v_cmp_ge_i32_e64 s[44:45], v192, v186
	v_cndmask_b32_e64 v144, 0, 1, s[46:47]
	v_cmp_le_i32_e64 s[46:47], v191, v186
	v_cndmask_b32_e64 v145, 0, 1, s[44:45]
	v_cndmask_b32_e64 v144, v145, v144, s[40:41]
	v_and_b32_e32 v144, 1, v144
	v_cmp_eq_u32_e64 s[44:45], 1, v144
	v_sub_f32_e32 v144, v180, v143
	v_mul_f32_e32 v144, 0x3fb8aa3b, v144
	v_exp_f32_e32 v144, v144
	v_cndmask_b32_e64 v148, 0, 1, s[46:47]
	v_cmp_le_i32_e64 s[46:47], v190, v186
	v_mul_f32_e32 v15, v15, v144
	ds_read_b128 v[144:147], v226 offset:17632
	v_cndmask_b32_e64 v15, 0, v15, s[44:45]
	v_cmp_ge_i32_e64 s[44:45], v191, v186
	v_cvt_pk_bf16_f32 v5, v14, v15
	s_nop 0
	v_cndmask_b32_e64 v149, 0, 1, s[44:45]
	v_cndmask_b32_e64 v148, v149, v148, s[40:41]
	v_and_b32_e32 v148, 1, v148
	v_cmp_eq_u32_e64 s[44:45], 1, v148
	s_waitcnt lgkmcnt(0)
	v_sub_f32_e32 v148, v180, v144
	v_mul_f32_e32 v148, 0x3fb8aa3b, v148
	v_exp_f32_e32 v148, v148
	s_nop 0
	v_mul_f32_e32 v16, v16, v148
	v_cndmask_b32_e64 v16, 0, v16, s[44:45]
	v_cmp_ge_i32_e64 s[44:45], v190, v186
	v_cndmask_b32_e64 v148, 0, 1, s[46:47]
	v_cmp_le_i32_e64 s[46:47], v189, v186
	v_cndmask_b32_e64 v149, 0, 1, s[44:45]
	v_cndmask_b32_e64 v148, v149, v148, s[40:41]
	v_and_b32_e32 v148, 1, v148
	v_cmp_eq_u32_e64 s[44:45], 1, v148
	v_sub_f32_e32 v148, v180, v145
	v_mul_f32_e32 v148, 0x3fb8aa3b, v148
	v_exp_f32_e32 v148, v148
	s_nop 0
	v_mul_f32_e32 v17, v17, v148
	v_cndmask_b32_e64 v17, 0, v17, s[44:45]
	v_cmp_ge_i32_e64 s[44:45], v189, v186
	v_cndmask_b32_e64 v148, 0, 1, s[46:47]
	v_cmp_le_i32_e64 s[46:47], v188, v186
	v_cndmask_b32_e64 v149, 0, 1, s[44:45]
	v_cndmask_b32_e64 v148, v149, v148, s[40:41]
	v_and_b32_e32 v148, 1, v148
	v_cmp_eq_u32_e64 s[44:45], 1, v148
	v_sub_f32_e32 v148, v180, v146
	v_mul_f32_e32 v148, 0x3fb8aa3b, v148
	v_exp_f32_e32 v148, v148
	v_cvt_pk_bf16_f32 v6, v16, v17
	v_mul_f32_e32 v18, v18, v148
	v_cndmask_b32_e64 v18, 0, v18, s[44:45]
	v_cmp_ge_i32_e64 s[44:45], v188, v186
	v_cndmask_b32_e64 v148, 0, 1, s[46:47]
	v_cmp_le_i32_e64 s[46:47], v223, v187
	v_cndmask_b32_e64 v149, 0, 1, s[44:45]
	v_cndmask_b32_e64 v148, v149, v148, s[40:41]
	v_and_b32_e32 v148, 1, v148
	v_cmp_eq_u32_e64 s[44:45], 1, v148
	v_sub_f32_e32 v148, v180, v147
	v_mul_f32_e32 v148, 0x3fb8aa3b, v148
	v_exp_f32_e32 v148, v148
	s_nop 0
	v_mul_f32_e32 v19, v19, v148
	v_cndmask_b32_e64 v19, 0, v19, s[44:45]
	v_cvt_pk_bf16_f32 v7, v18, v19
	global_store_dwordx4 v[182:183], v[4:7], off offset:-1536
	v_cmp_ge_i32_e64 s[44:45], v223, v187
	s_waitcnt vmcnt(11)
	v_mfma_f32_32x32x16_bf16 v[4:19], v[124:127], v[48:51], 0
	s_waitcnt vmcnt(10)
; __device__ __forceinline__ unsigned pk2(float lo, float hi) { const f32x2_cv v = {lo, hi}; const bf16x2_cv b = __builtin_convertvector(v, bf16x2_cv); return __builtin_bit_cast(unsigned, b); }
; __device__ __forceinline__ int crow16(int r, int hi) { return (r & 3) + 8 * (r >> 2) + 4 * hi; }
; __device__ __forceinline__ void dk_phase(const Frame& F, const bf16* QKrm, const unsigned char* KT, const unsigned char* VT, const float* BG, unsigned char* ITEMS) {
;     ...
; #pragma unroll
;             for (int ri = 0; ri < 2; ++ri) { const int r = 32 * ri + r32; const float gr = gamL[r];
; #pragma unroll
;                 for (int si = 0; si < 2; ++si) { f32x16_t p = f32x16_t{};
; #pragma unroll
;                     for (int ks = 0; ks < 8; ++ks) p = __builtin_amdgcn_mfma_f32_32x32x16_bf16(Kn[si][ks], Qn[ri][ks], p, 0, 0, 0);
;                     float pv[16];
; #pragma unroll
;                     for (int rg = 0; rg < 16; ++rg) { const int s = 32 * si + crow16(rg, hi); const float gs = gamL[s];
;                         const bool ok = dir ? (s >= r) : (s <= r);
;                         pv[rg] = ok ? p[rg] * __expf(gr - gs) : 0.f; }
; #pragma unroll
;                     for (int st = 0; st < 2; ++st) { v4u wv; wv.x = pk2(pv[8 * st + 0], pv[8 * st + 1]); wv.y = pk2(pv[8 * st + 2], pv[8 * st + 3]); wv.z = pk2(pv[8 * st + 4], pv[8 * st + 5]); wv.w = pk2(pv[8 * st + 6], pv[8 * st + 7]);
;                         *(v4u*)(item + ITEM_AQK + ((ri * 2 + si) * 2 + st) * 1024 + lane * 16) = wv; } } }
	v_mfma_f32_32x32x16_bf16 v[4:19], v[120:123], v[44:47], v[4:19]
	s_waitcnt vmcnt(9)
	v_mfma_f32_32x32x16_bf16 v[4:19], v[128:131], v[40:43], v[4:19]
	s_waitcnt vmcnt(8)
	v_mfma_f32_32x32x16_bf16 v[4:19], v[116:119], v[36:39], v[4:19]
	s_waitcnt vmcnt(7)
	v_mfma_f32_32x32x16_bf16 v[4:19], v[112:115], v[32:35], v[4:19]
	s_waitcnt vmcnt(6)
	v_mfma_f32_32x32x16_bf16 v[4:19], v[108:111], v[28:31], v[4:19]
	s_waitcnt vmcnt(5)
	v_mfma_f32_32x32x16_bf16 v[4:19], v[104:107], v[20:23], v[4:19]
	s_waitcnt vmcnt(4)
	v_mfma_f32_32x32x16_bf16 v[4:19], v[100:103], v[24:27], v[4:19]
	v_cndmask_b32_e64 v100, 0, 1, s[46:47]
	v_cndmask_b32_e64 v101, 0, 1, s[44:45]
	v_cndmask_b32_e64 v100, v101, v100, s[40:41]
	v_and_b32_e32 v100, 1, v100
	v_cmp_eq_u32_e64 s[44:45], 1, v100
	v_cmp_lt_i32_e64 s[46:47], v223, v187
	s_nop 5
	v_mul_f32_e32 v4, v56, v4
	v_cndmask_b32_e64 v4, 0, v4, s[44:45]
	v_cmp_ge_i32_e64 s[44:45], v225, v187
	v_cndmask_b32_e64 v56, 0, 1, s[46:47]
	v_cmp_le_i32_e64 s[46:47], v224, v187
	v_cndmask_b32_e64 v100, 0, 1, s[44:45]
	v_cndmask_b32_e64 v56, v100, v56, s[40:41]
	v_and_b32_e32 v56, 1, v56
	v_cmp_eq_u32_e64 s[44:45], 1, v56
	v_sub_f32_e32 v56, v181, v57
	v_mul_f32_e32 v56, 0x3fb8aa3b, v56
	v_exp_f32_e32 v56, v56
	v_mul_f32_e32 v8, v52, v8
	v_mul_f32_e32 v5, v56, v5
	v_cndmask_b32_e64 v5, 0, v5, s[44:45]
	v_cmp_ge_i32_e64 s[44:45], v224, v187
	v_cndmask_b32_e64 v56, 0, 1, s[46:47]
	v_cmp_le_i32_e64 s[46:47], v222, v187
	v_cndmask_b32_e64 v57, 0, 1, s[44:45]
	v_cndmask_b32_e64 v56, v57, v56, s[40:41]
	v_and_b32_e32 v56, 1, v56
	v_cmp_eq_u32_e64 s[44:45], 1, v56
	v_sub_f32_e32 v56, v181, v58
	v_mul_f32_e32 v56, 0x3fb8aa3b, v56
	v_exp_f32_e32 v56, v56
	v_cvt_pk_bf16_f32 v4, v4, v5
	v_mul_f32_e32 v6, v56, v6
	v_cndmask_b32_e64 v6, 0, v6, s[44:45]
	v_cmp_ge_i32_e64 s[44:45], v222, v187
	v_cndmask_b32_e64 v56, 0, 1, s[46:47]
	v_cmp_le_i32_e64 s[46:47], v221, v187
	v_cndmask_b32_e64 v57, 0, 1, s[44:45]
	v_cndmask_b32_e64 v56, v57, v56, s[40:41]
	v_and_b32_e32 v56, 1, v56
	v_cmp_eq_u32_e64 s[44:45], 1, v56
	v_sub_f32_e32 v56, v181, v59
	v_mul_f32_e32 v56, 0x3fb8aa3b, v56
	v_exp_f32_e32 v56, v56
	s_nop 0
	v_mul_f32_e32 v7, v56, v7
	v_cndmask_b32_e64 v7, 0, v7, s[44:45]
	v_cmp_ge_i32_e64 s[44:45], v221, v187
	v_cndmask_b32_e64 v56, 0, 1, s[46:47]
	v_cmp_le_i32_e64 s[46:47], v220, v187
	v_cndmask_b32_e64 v57, 0, 1, s[44:45]
	v_cndmask_b32_e64 v56, v57, v56, s[40:41]
	v_and_b32_e32 v56, 1, v56
	v_cmp_eq_u32_e64 s[44:45], 1, v56
	v_cndmask_b32_e64 v52, 0, 1, s[46:47]
	v_cmp_le_i32_e64 s[46:47], v219, v187
	v_cndmask_b32_e64 v8, 0, v8, s[44:45]
	v_cmp_ge_i32_e64 s[44:45], v220, v187
	v_cvt_pk_bf16_f32 v5, v6, v7
	s_nop 0
	v_cndmask_b32_e64 v56, 0, 1, s[44:45]
	v_cndmask_b32_e64 v52, v56, v52, s[40:41]
	v_and_b32_e32 v52, 1, v52
	v_cmp_eq_u32_e64 s[44:45], 1, v52
	v_sub_f32_e32 v52, v181, v53
	v_mul_f32_e32 v52, 0x3fb8aa3b, v52
	v_exp_f32_e32 v52, v52
	s_nop 0
	v_mul_f32_e32 v9, v52, v9
	v_cndmask_b32_e64 v9, 0, v9, s[44:45]
	v_cmp_ge_i32_e64 s[44:45], v219, v187
	v_cndmask_b32_e64 v52, 0, 1, s[46:47]
	v_cmp_le_i32_e64 s[46:47], v218, v187
	v_cndmask_b32_e64 v53, 0, 1, s[44:45]
	v_cndmask_b32_e64 v52, v53, v52, s[40:41]
	v_and_b32_e32 v52, 1, v52
	v_cmp_eq_u32_e64 s[44:45], 1, v52
	v_sub_f32_e32 v52, v181, v54
	v_mul_f32_e32 v52, 0x3fb8aa3b, v52
	v_exp_f32_e32 v52, v52
	v_cvt_pk_bf16_f32 v6, v8, v9
	v_mul_f32_e32 v10, v52, v10
	v_cndmask_b32_e64 v10, 0, v10, s[44:45]
	v_cmp_ge_i32_e64 s[44:45], v218, v187
	v_cndmask_b32_e64 v52, 0, 1, s[46:47]
	v_cmp_le_i32_e64 s[46:47], v217, v187
	v_cndmask_b32_e64 v53, 0, 1, s[44:45]
	v_cndmask_b32_e64 v52, v53, v52, s[40:41]
	v_and_b32_e32 v52, 1, v52
	v_cmp_eq_u32_e64 s[44:45], 1, v52
	v_sub_f32_e32 v52, v181, v55
	v_mul_f32_e32 v52, 0x3fb8aa3b, v52
	v_exp_f32_e32 v52, v52
	s_nop 0
	v_mul_f32_e32 v11, v52, v11
	v_cndmask_b32_e64 v11, 0, v11, s[44:45]
	v_cmp_ge_i32_e64 s[44:45], v217, v187
	v_cndmask_b32_e64 v52, 0, 1, s[46:47]
	v_cmp_le_i32_e64 s[46:47], v216, v187
	v_cndmask_b32_e64 v53, 0, 1, s[44:45]
	v_cndmask_b32_e64 v52, v53, v52, s[40:41]
	v_and_b32_e32 v52, 1, v52
	v_cmp_eq_u32_e64 s[44:45], 1, v52
	v_sub_f32_e32 v52, v181, v60
	v_mul_f32_e32 v52, 0x3fb8aa3b, v52
	v_exp_f32_e32 v52, v52
	v_cvt_pk_bf16_f32 v7, v10, v11
	global_store_dwordx4 v[182:183], v[4:7], off offset:-512
	v_mul_f32_e32 v12, v52, v12
	v_cndmask_b32_e64 v12, 0, v12, s[44:45]
	v_cmp_ge_i32_e64 s[44:45], v216, v187
	v_cndmask_b32_e64 v52, 0, 1, s[46:47]
	v_cmp_le_i32_e64 s[46:47], v215, v187
	v_cndmask_b32_e64 v53, 0, 1, s[44:45]
	v_cndmask_b32_e64 v52, v53, v52, s[40:41]
	v_and_b32_e32 v52, 1, v52
	v_cmp_eq_u32_e64 s[44:45], 1, v52
	v_sub_f32_e32 v52, v181, v61
	v_mul_f32_e32 v52, 0x3fb8aa3b, v52
	v_exp_f32_e32 v52, v52
	s_nop 0
	v_mul_f32_e32 v13, v52, v13
	v_cndmask_b32_e64 v13, 0, v13, s[44:45]
	v_cmp_ge_i32_e64 s[44:45], v215, v187
	v_cndmask_b32_e64 v52, 0, 1, s[46:47]
	v_cmp_le_i32_e64 s[46:47], v214, v187
	v_cndmask_b32_e64 v53, 0, 1, s[44:45]
	v_cndmask_b32_e64 v52, v53, v52, s[40:41]
	v_and_b32_e32 v52, 1, v52
	v_cmp_eq_u32_e64 s[44:45], 1, v52
	v_sub_f32_e32 v52, v181, v62
	v_mul_f32_e32 v52, 0x3fb8aa3b, v52
	v_exp_f32_e32 v52, v52
	v_cvt_pk_bf16_f32 v4, v12, v13
	v_mul_f32_e32 v14, v52, v14
	v_cndmask_b32_e64 v14, 0, v14, s[44:45]
	v_cmp_ge_i32_e64 s[44:45], v214, v187
	v_cndmask_b32_e64 v52, 0, 1, s[46:47]
	v_cmp_le_i32_e64 s[46:47], v213, v187
	v_cndmask_b32_e64 v53, 0, 1, s[44:45]
	v_cndmask_b32_e64 v52, v53, v52, s[40:41]
	v_and_b32_e32 v52, 1, v52
	v_cmp_eq_u32_e64 s[44:45], 1, v52
	v_sub_f32_e32 v52, v181, v63
	v_mul_f32_e32 v52, 0x3fb8aa3b, v52
	v_exp_f32_e32 v52, v52
	s_nop 0
	v_mul_f32_e32 v15, v52, v15
; __device__ __forceinline__ unsigned pk2(float lo, float hi) { const f32x2_cv v = {lo, hi}; const bf16x2_cv b = __builtin_convertvector(v, bf16x2_cv); return __builtin_bit_cast(unsigned, b); }
; __device__ __forceinline__ int crow16(int r, int hi) { return (r & 3) + 8 * (r >> 2) + 4 * hi; }
; __device__ __forceinline__ void dk_phase(const Frame& F, const bf16* QKrm, const unsigned char* KT, const unsigned char* VT, const float* BG, unsigned char* ITEMS) {
;     ...
; #pragma unroll
;             for (int ri = 0; ri < 2; ++ri) { const int r = 32 * ri + r32; const float gr = gamL[r];
; #pragma unroll
;                 for (int si = 0; si < 2; ++si) { f32x16_t p = f32x16_t{};
; #pragma unroll
;                     for (int ks = 0; ks < 8; ++ks) p = __builtin_amdgcn_mfma_f32_32x32x16_bf16(Kn[si][ks], Qn[ri][ks], p, 0, 0, 0);
;                     float pv[16];
; #pragma unroll
;                     for (int rg = 0; rg < 16; ++rg) { const int s = 32 * si + crow16(rg, hi); const float gs = gamL[s];
;                         const bool ok = dir ? (s >= r) : (s <= r);
;                         pv[rg] = ok ? p[rg] * __expf(gr - gs) : 0.f; }
; #pragma unroll
;                     for (int st = 0; st < 2; ++st) { v4u wv; wv.x = pk2(pv[8 * st + 0], pv[8 * st + 1]); wv.y = pk2(pv[8 * st + 2], pv[8 * st + 3]); wv.z = pk2(pv[8 * st + 4], pv[8 * st + 5]); wv.w = pk2(pv[8 * st + 6], pv[8 * st + 7]);
;                         *(v4u*)(item + ITEM_AQK + ((ri * 2 + si) * 2 + st) * 1024 + lane * 16) = wv; } } }
	v_cndmask_b32_e64 v15, 0, v15, s[44:45]
	v_cmp_ge_i32_e64 s[44:45], v213, v187
	v_cndmask_b32_e64 v52, 0, 1, s[46:47]
	v_cmp_le_i32_e64 s[46:47], v203, v187
	v_cndmask_b32_e64 v53, 0, 1, s[44:45]
	v_cndmask_b32_e64 v52, v53, v52, s[40:41]
	v_and_b32_e32 v52, 1, v52
	v_cmp_eq_u32_e64 s[44:45], 1, v52
	v_sub_f32_e32 v52, v181, v64
	v_mul_f32_e32 v52, 0x3fb8aa3b, v52
	v_exp_f32_e32 v52, v52
	v_cvt_pk_bf16_f32 v5, v14, v15
	v_mul_f32_e32 v16, v52, v16
	v_cndmask_b32_e64 v16, 0, v16, s[44:45]
	v_cmp_ge_i32_e64 s[44:45], v203, v187
	v_cndmask_b32_e64 v52, 0, 1, s[46:47]
	v_cmp_le_i32_e64 s[46:47], v211, v187
	v_cndmask_b32_e64 v53, 0, 1, s[44:45]
	v_cndmask_b32_e64 v52, v53, v52, s[40:41]
	v_and_b32_e32 v52, 1, v52
	v_cmp_eq_u32_e64 s[44:45], 1, v52
	v_sub_f32_e32 v52, v181, v65
	v_mul_f32_e32 v52, 0x3fb8aa3b, v52
	v_exp_f32_e32 v52, v52
	s_nop 0
	v_mul_f32_e32 v17, v52, v17
	v_cndmask_b32_e64 v17, 0, v17, s[44:45]
	v_cmp_ge_i32_e64 s[44:45], v211, v187
	v_cndmask_b32_e64 v52, 0, 1, s[46:47]
	v_cmp_le_i32_e64 s[46:47], v212, v187
	v_cndmask_b32_e64 v53, 0, 1, s[44:45]
	v_cndmask_b32_e64 v52, v53, v52, s[40:41]
	v_and_b32_e32 v52, 1, v52
	v_cmp_eq_u32_e64 s[44:45], 1, v52
	v_sub_f32_e32 v52, v181, v66
	v_mul_f32_e32 v52, 0x3fb8aa3b, v52
	v_exp_f32_e32 v52, v52
	v_cvt_pk_bf16_f32 v6, v16, v17
	v_mul_f32_e32 v18, v52, v18
	v_cndmask_b32_e64 v18, 0, v18, s[44:45]
	v_cmp_ge_i32_e64 s[44:45], v212, v187
	v_cndmask_b32_e64 v52, 0, 1, s[46:47]
	s_nop 0
	v_cndmask_b32_e64 v53, 0, 1, s[44:45]
	v_cndmask_b32_e64 v52, v53, v52, s[40:41]
	v_and_b32_e32 v52, 1, v52
	v_cmp_eq_u32_e64 s[44:45], 1, v52
	v_sub_f32_e32 v52, v181, v67
	v_mul_f32_e32 v52, 0x3fb8aa3b, v52
	v_exp_f32_e32 v52, v52
	s_nop 0
	v_mul_f32_e32 v19, v52, v19
	v_cndmask_b32_e64 v19, 0, v19, s[44:45]
	v_add_co_u32_e64 v52, s[44:45], s90, v166
	v_cvt_pk_bf16_f32 v7, v18, v19
	s_nop 0
	v_addc_co_u32_e64 v53, s[44:45], -1, v167, s[44:45]
	global_store_dwordx4 v[52:53], v[4:7], off offset:-3584
	v_cmp_le_i32_e64 s[44:45], v201, v187
	s_nop 0
	v_mfma_f32_32x32x16_bf16 v[4:19], v[96:99], v[48:51], 0
	v_mfma_f32_32x32x16_bf16 v[4:19], v[88:91], v[44:47], v[4:19]
	v_mfma_f32_32x32x16_bf16 v[4:19], v[92:95], v[40:43], v[4:19]
	v_mfma_f32_32x32x16_bf16 v[4:19], v[84:87], v[36:39], v[4:19]
	v_mfma_f32_32x32x16_bf16 v[4:19], v[80:83], v[32:35], v[4:19]
	v_mfma_f32_32x32x16_bf16 v[4:19], v[76:79], v[28:31], v[4:19]
	v_mfma_f32_32x32x16_bf16 v[4:19], v[68:71], v[20:23], v[4:19]
	v_sub_f32_e32 v20, v181, v136
	v_mul_f32_e32 v20, 0x3fb8aa3b, v20
	v_exp_f32_e32 v20, v20
	v_mfma_f32_32x32x16_bf16 v[4:19], v[72:75], v[24:27], v[4:19]
	s_nop 11
	v_mul_f32_e32 v4, v20, v4
	v_cndmask_b32_e64 v4, 0, v4, s[42:43]
	v_cmp_ge_i32_e64 s[42:43], v202, v187
	s_nop 1
	v_cndmask_b32_e64 v20, 0, 1, s[42:43]
	v_cndmask_b32_e64 v20, v20, v165, s[40:41]
	v_and_b32_e32 v20, 1, v20
	v_cmp_eq_u32_e64 s[42:43], 1, v20
	v_sub_f32_e32 v20, v181, v137
	v_mul_f32_e32 v20, 0x3fb8aa3b, v20
	v_exp_f32_e32 v20, v20
	s_nop 0
	v_mul_f32_e32 v5, v20, v5
	v_cndmask_b32_e64 v5, 0, v5, s[42:43]
	v_cmp_ge_i32_e64 s[42:43], v201, v187
	v_cndmask_b32_e64 v20, 0, 1, s[44:45]
	v_cmp_le_i32_e64 s[44:45], v200, v187
	v_cndmask_b32_e64 v21, 0, 1, s[42:43]
	v_cndmask_b32_e64 v20, v21, v20, s[40:41]
	v_and_b32_e32 v20, 1, v20
	v_cmp_eq_u32_e64 s[42:43], 1, v20
	v_sub_f32_e32 v20, v181, v138
	v_mul_f32_e32 v20, 0x3fb8aa3b, v20
	v_exp_f32_e32 v20, v20
	v_cvt_pk_bf16_f32 v4, v4, v5
	v_mul_f32_e32 v6, v20, v6
	v_cndmask_b32_e64 v6, 0, v6, s[42:43]
	v_cmp_ge_i32_e64 s[42:43], v200, v187
	v_cndmask_b32_e64 v20, 0, 1, s[44:45]
	v_cmp_le_i32_e64 s[44:45], v199, v187
	v_cndmask_b32_e64 v21, 0, 1, s[42:43]
	v_cndmask_b32_e64 v20, v21, v20, s[40:41]
	v_and_b32_e32 v20, 1, v20
	v_cmp_eq_u32_e64 s[42:43], 1, v20
	v_sub_f32_e32 v20, v181, v139
	v_mul_f32_e32 v20, 0x3fb8aa3b, v20
	v_exp_f32_e32 v20, v20
	s_nop 0
	v_mul_f32_e32 v7, v20, v7
	v_cndmask_b32_e64 v7, 0, v7, s[42:43]
	v_cmp_ge_i32_e64 s[42:43], v199, v187
	v_cndmask_b32_e64 v20, 0, 1, s[44:45]
	v_cmp_le_i32_e64 s[44:45], v198, v187
	v_cndmask_b32_e64 v21, 0, 1, s[42:43]
	v_cndmask_b32_e64 v20, v21, v20, s[40:41]
	v_and_b32_e32 v20, 1, v20
	v_cmp_eq_u32_e64 s[42:43], 1, v20
	v_sub_f32_e32 v20, v181, v132
	v_mul_f32_e32 v20, 0x3fb8aa3b, v20
	v_exp_f32_e32 v20, v20
	v_cvt_pk_bf16_f32 v5, v6, v7
	v_mul_f32_e32 v8, v20, v8
	v_cndmask_b32_e64 v8, 0, v8, s[42:43]
	v_cmp_ge_i32_e64 s[42:43], v198, v187
	v_cndmask_b32_e64 v20, 0, 1, s[44:45]
	v_cmp_le_i32_e64 s[44:45], v197, v187
	v_cndmask_b32_e64 v21, 0, 1, s[42:43]
	v_cndmask_b32_e64 v20, v21, v20, s[40:41]
	v_and_b32_e32 v20, 1, v20
	v_cmp_eq_u32_e64 s[42:43], 1, v20
	v_sub_f32_e32 v20, v181, v133
	v_mul_f32_e32 v20, 0x3fb8aa3b, v20
	v_exp_f32_e32 v20, v20
	s_nop 0
	v_mul_f32_e32 v9, v20, v9
	v_cndmask_b32_e64 v9, 0, v9, s[42:43]
	v_cmp_ge_i32_e64 s[42:43], v197, v187
	v_cndmask_b32_e64 v20, 0, 1, s[44:45]
	v_cmp_le_i32_e64 s[44:45], v196, v187
	v_cndmask_b32_e64 v21, 0, 1, s[42:43]
	v_cndmask_b32_e64 v20, v21, v20, s[40:41]
	v_and_b32_e32 v20, 1, v20
	v_cmp_eq_u32_e64 s[42:43], 1, v20
	v_sub_f32_e32 v20, v181, v134
	v_mul_f32_e32 v20, 0x3fb8aa3b, v20
	v_exp_f32_e32 v20, v20
	v_cvt_pk_bf16_f32 v6, v8, v9
	v_mul_f32_e32 v10, v20, v10
	v_cndmask_b32_e64 v10, 0, v10, s[42:43]
	v_cmp_ge_i32_e64 s[42:43], v196, v187
	v_cndmask_b32_e64 v20, 0, 1, s[44:45]
	v_cmp_le_i32_e64 s[44:45], v195, v187
	v_cndmask_b32_e64 v21, 0, 1, s[42:43]
	v_cndmask_b32_e64 v20, v21, v20, s[40:41]
	v_and_b32_e32 v20, 1, v20
	v_cmp_eq_u32_e64 s[42:43], 1, v20
	v_sub_f32_e32 v20, v181, v135
	v_mul_f32_e32 v20, 0x3fb8aa3b, v20
	v_exp_f32_e32 v20, v20
	s_nop 0
	v_mul_f32_e32 v11, v20, v11
; #define LAS __attribute__((address_space(3)))
; #define LDS_WAIT() asm volatile("s_waitcnt lgkmcnt(0)" ::: "memory")
; __device__ __forceinline__ unsigned pk2(float lo, float hi) { const f32x2_cv v = {lo, hi}; const bf16x2_cv b = __builtin_convertvector(v, bf16x2_cv); return __builtin_bit_cast(unsigned, b); }
; __device__ __forceinline__ int crow16(int r, int hi) { return (r & 3) + 8 * (r >> 2) + 4 * hi; }
; __device__ __forceinline__ void dk_phase(const Frame& F, const bf16* QKrm, const unsigned char* KT, const unsigned char* VT, const float* BG, unsigned char* ITEMS) {
;     ...
;                     float pv[16];
; #pragma unroll
;                     for (int rg = 0; rg < 16; ++rg) { const int s = 32 * si + crow16(rg, hi); const float gs = gamL[s];
;                         const bool ok = dir ? (s >= r) : (s <= r);
;                         pv[rg] = ok ? p[rg] * __expf(gr - gs) : 0.f; }
; #pragma unroll
;                     for (int st = 0; st < 2; ++st) { v4u wv; wv.x = pk2(pv[8 * st + 0], pv[8 * st + 1]); wv.y = pk2(pv[8 * st + 2], pv[8 * st + 3]); wv.z = pk2(pv[8 * st + 4], pv[8 * st + 5]); wv.w = pk2(pv[8 * st + 6], pv[8 * st + 7]);
;                         *(v4u*)(item + ITEM_AQK + ((ri * 2 + si) * 2 + st) * 1024 + lane * 16) = wv; } } }
;         }
;         LDS_WAIT();
;         asm volatile("" ::: "memory"); __builtin_amdgcn_sched_barrier(0);
;         float t[64];
; #pragma unroll
;         for (int r = 0; r < 64; ++r) {
;             float acc = (lane == r) ? 1.f : 0.f;
; #pragma unroll
;             for (int s4 = 0; s4 < (r + 3) / 4; ++s4) { const f32x4 a = *(const LAS f32x4*)(Amat + r * 64 + 4 * s4);
;                 if (4 * s4 + 0 < r) acc -= a.x * t[4 * s4 + 0]; if (4 * s4 + 1 < r) acc -= a.y * t[4 * s4 + 1];
;                 if (4 * s4 + 2 < r) acc -= a.z * t[4 * s4 + 2]; if (4 * s4 + 3 < r) acc -= a.w * t[4 * s4 + 3]; }
;             t[r] = acc;
;         }
	v_cndmask_b32_e64 v11, 0, v11, s[42:43]
	v_cmp_ge_i32_e64 s[42:43], v195, v187
	v_cndmask_b32_e64 v20, 0, 1, s[44:45]
	v_cmp_le_i32_e64 s[44:45], v194, v187
	v_cndmask_b32_e64 v21, 0, 1, s[42:43]
	v_cndmask_b32_e64 v20, v21, v20, s[40:41]
	v_and_b32_e32 v20, 1, v20
	v_cmp_eq_u32_e64 s[42:43], 1, v20
	v_sub_f32_e32 v20, v181, v140
	v_mul_f32_e32 v20, 0x3fb8aa3b, v20
	v_exp_f32_e32 v20, v20
	v_cvt_pk_bf16_f32 v7, v10, v11
	global_store_dwordx4 v[52:53], v[4:7], off offset:-2560
	v_mul_f32_e32 v12, v20, v12
	v_cndmask_b32_e64 v12, 0, v12, s[42:43]
	v_cmp_ge_i32_e64 s[42:43], v194, v187
	v_cndmask_b32_e64 v20, 0, 1, s[44:45]
	v_cmp_le_i32_e64 s[44:45], v193, v187
	v_cndmask_b32_e64 v21, 0, 1, s[42:43]
	v_cndmask_b32_e64 v20, v21, v20, s[40:41]
	v_and_b32_e32 v20, 1, v20
	v_cmp_eq_u32_e64 s[42:43], 1, v20
	v_sub_f32_e32 v20, v181, v141
	v_mul_f32_e32 v20, 0x3fb8aa3b, v20
	v_exp_f32_e32 v20, v20
	s_nop 0
	v_mul_f32_e32 v13, v20, v13
	v_cndmask_b32_e64 v13, 0, v13, s[42:43]
	v_cmp_ge_i32_e64 s[42:43], v193, v187
	v_cndmask_b32_e64 v20, 0, 1, s[44:45]
	v_cmp_le_i32_e64 s[44:45], v192, v187
	v_cndmask_b32_e64 v21, 0, 1, s[42:43]
	v_cndmask_b32_e64 v20, v21, v20, s[40:41]
	v_and_b32_e32 v20, 1, v20
	v_cmp_eq_u32_e64 s[42:43], 1, v20
	v_sub_f32_e32 v20, v181, v142
	v_mul_f32_e32 v20, 0x3fb8aa3b, v20
	v_exp_f32_e32 v20, v20
	v_cvt_pk_bf16_f32 v4, v12, v13
	v_mul_f32_e32 v14, v20, v14
	v_cndmask_b32_e64 v14, 0, v14, s[42:43]
	v_cmp_ge_i32_e64 s[42:43], v192, v187
	v_cndmask_b32_e64 v20, 0, 1, s[44:45]
	v_cmp_le_i32_e64 s[44:45], v191, v187
	v_cndmask_b32_e64 v21, 0, 1, s[42:43]
	v_cndmask_b32_e64 v20, v21, v20, s[40:41]
	v_and_b32_e32 v20, 1, v20
	v_cmp_eq_u32_e64 s[42:43], 1, v20
	v_sub_f32_e32 v20, v181, v143
	v_mul_f32_e32 v20, 0x3fb8aa3b, v20
	v_exp_f32_e32 v20, v20
	s_nop 0
	v_mul_f32_e32 v15, v20, v15
	v_cndmask_b32_e64 v15, 0, v15, s[42:43]
	v_cmp_ge_i32_e64 s[42:43], v191, v187
	v_cndmask_b32_e64 v20, 0, 1, s[44:45]
	v_cmp_le_i32_e64 s[44:45], v190, v187
	v_cndmask_b32_e64 v21, 0, 1, s[42:43]
	v_cndmask_b32_e64 v20, v21, v20, s[40:41]
	v_and_b32_e32 v20, 1, v20
	v_cmp_eq_u32_e64 s[42:43], 1, v20
	v_sub_f32_e32 v20, v181, v144
	v_mul_f32_e32 v20, 0x3fb8aa3b, v20
	v_exp_f32_e32 v20, v20
	v_cvt_pk_bf16_f32 v5, v14, v15
	v_mul_f32_e32 v16, v20, v16
	v_cndmask_b32_e64 v16, 0, v16, s[42:43]
	v_cmp_ge_i32_e64 s[42:43], v190, v187
	v_cndmask_b32_e64 v20, 0, 1, s[44:45]
	v_cmp_le_i32_e64 s[44:45], v189, v187
	v_cndmask_b32_e64 v21, 0, 1, s[42:43]
	v_cndmask_b32_e64 v20, v21, v20, s[40:41]
	v_and_b32_e32 v20, 1, v20
	v_cmp_eq_u32_e64 s[42:43], 1, v20
	v_sub_f32_e32 v20, v181, v145
	v_mul_f32_e32 v20, 0x3fb8aa3b, v20
	v_exp_f32_e32 v20, v20
	s_nop 0
	v_mul_f32_e32 v17, v20, v17
	v_cndmask_b32_e64 v17, 0, v17, s[42:43]
	v_cmp_ge_i32_e64 s[42:43], v189, v187
	v_cndmask_b32_e64 v20, 0, 1, s[44:45]
	v_cmp_le_i32_e64 s[44:45], v188, v187
	v_cndmask_b32_e64 v21, 0, 1, s[42:43]
	v_cndmask_b32_e64 v20, v21, v20, s[40:41]
	v_and_b32_e32 v20, 1, v20
	v_cmp_eq_u32_e64 s[42:43], 1, v20
	v_sub_f32_e32 v20, v181, v146
	v_mul_f32_e32 v20, 0x3fb8aa3b, v20
	v_exp_f32_e32 v20, v20
	v_cvt_pk_bf16_f32 v6, v16, v17
	v_mul_f32_e32 v18, v20, v18
	v_cndmask_b32_e64 v18, 0, v18, s[42:43]
	v_cmp_ge_i32_e64 s[42:43], v188, v187
	v_cndmask_b32_e64 v20, 0, 1, s[44:45]
	s_nop 0
	v_cndmask_b32_e64 v21, 0, 1, s[42:43]
	v_cndmask_b32_e64 v20, v21, v20, s[40:41]
	v_and_b32_e32 v20, 1, v20
	v_cmp_eq_u32_e64 s[42:43], 1, v20
	v_sub_f32_e32 v20, v181, v147
	v_mul_f32_e32 v20, 0x3fb8aa3b, v20
	v_exp_f32_e32 v20, v20
	s_nop 0
	v_mul_f32_e32 v19, v20, v19
	v_cndmask_b32_e64 v19, 0, v19, s[42:43]
	v_cvt_pk_bf16_f32 v7, v18, v19
	global_store_dwordx4 v[52:53], v[4:7], off offset:-1536
	s_waitcnt lgkmcnt(0)
	s_mov_b64 s[42:43], 1
	v_cndmask_b32_e64 v64, 0, 1.0, s[42:43]
	ds_read_b128 v[4:7], v2 offset:256
	ds_read_b128 v[8:11], v2 offset:512
	ds_read_b128 v[12:15], v2 offset:768
	ds_read_b128 v[16:19], v2 offset:1024
	ds_read_b128 v[20:23], v2 offset:1280
	ds_read_b128 v[24:27], v2 offset:1296
	ds_read_b128 v[28:31], v2 offset:1536
	ds_read_b128 v[32:35], v2 offset:1552
	s_waitcnt lgkmcnt(6)
	s_lshl_b64 s[42:43], 1, 1
	v_cndmask_b32_e64 v65, 0, 1.0, s[42:43]
	v_fma_f32 v65, -v4, v64, v65
	s_lshl_b64 s[42:43], 1, 2
	v_cndmask_b32_e64 v66, 0, 1.0, s[42:43]
	v_fma_f32 v66, -v8, v64, v66
	v_fma_f32 v66, -v9, v65, v66
	ds_read_b128 v[4:7], v2 offset:1792
	ds_read_b128 v[8:11], v2 offset:1808
	s_waitcnt lgkmcnt(6)
	s_lshl_b64 s[42:43], 1, 3
	v_cndmask_b32_e64 v67, 0, 1.0, s[42:43]
	v_fma_f32 v67, -v12, v64, v67
	v_fma_f32 v67, -v13, v65, v67
	v_fma_f32 v67, -v14, v66, v67
	s_lshl_b64 s[42:43], 1, 4
	v_cndmask_b32_e64 v68, 0, 1.0, s[42:43]
	v_fma_f32 v68, -v16, v64, v68
	v_fma_f32 v68, -v17, v65, v68
	v_fma_f32 v68, -v18, v66, v68
	v_fma_f32 v68, -v19, v67, v68
	ds_read_b128 v[12:15], v2 offset:2048
	ds_read_b128 v[16:19], v2 offset:2064
	s_waitcnt lgkmcnt(6)
	s_lshl_b64 s[42:43], 1, 5
	v_cndmask_b32_e64 v69, 0, 1.0, s[42:43]
	v_fma_f32 v69, -v20, v64, v69
	v_fma_f32 v69, -v21, v65, v69
	v_fma_f32 v69, -v22, v66, v69
	v_fma_f32 v69, -v23, v67, v69
	v_fma_f32 v69, -v24, v68, v69
	ds_read_b128 v[20:23], v2 offset:2304
	ds_read_b128 v[24:27], v2 offset:2320
	s_waitcnt lgkmcnt(6)
	s_lshl_b64 s[42:43], 1, 6
	v_cndmask_b32_e64 v70, 0, 1.0, s[42:43]
	v_fma_f32 v70, -v28, v64, v70
	v_fma_f32 v70, -v29, v65, v70
	v_fma_f32 v70, -v30, v66, v70
	v_fma_f32 v70, -v31, v67, v70
	v_fma_f32 v70, -v32, v68, v70
	v_fma_f32 v70, -v33, v69, v70
	ds_read_b128 v[28:31], v2 offset:2336
	ds_read_b128 v[32:35], v2 offset:2560
	s_waitcnt lgkmcnt(6)
; #define LAS __attribute__((address_space(3)))
; __device__ __forceinline__ void dk_phase(const Frame& F, const bf16* QKrm, const unsigned char* KT, const unsigned char* VT, const float* BG, unsigned char* ITEMS) {
;     ...
;         float t[64];
; #pragma unroll
;         for (int r = 0; r < 64; ++r) {
;             float acc = (lane == r) ? 1.f : 0.f;
; #pragma unroll
;             for (int s4 = 0; s4 < (r + 3) / 4; ++s4) { const f32x4 a = *(const LAS f32x4*)(Amat + r * 64 + 4 * s4);
;                 if (4 * s4 + 0 < r) acc -= a.x * t[4 * s4 + 0]; if (4 * s4 + 1 < r) acc -= a.y * t[4 * s4 + 1];
;                 if (4 * s4 + 2 < r) acc -= a.z * t[4 * s4 + 2]; if (4 * s4 + 3 < r) acc -= a.w * t[4 * s4 + 3]; }
;             t[r] = acc;
;         }
	s_lshl_b64 s[42:43], 1, 7
	v_cndmask_b32_e64 v71, 0, 1.0, s[42:43]
	v_fma_f32 v71, -v4, v64, v71
	v_fma_f32 v71, -v5, v65, v71
	v_fma_f32 v71, -v6, v66, v71
	v_fma_f32 v71, -v7, v67, v71
	v_fma_f32 v71, -v8, v68, v71
	v_fma_f32 v71, -v9, v69, v71
	v_fma_f32 v71, -v10, v70, v71
	ds_read_b128 v[4:7], v2 offset:2576
	ds_read_b128 v[8:11], v2 offset:2592
	s_waitcnt lgkmcnt(6)
	s_lshl_b64 s[42:43], 1, 8
	v_cndmask_b32_e64 v72, 0, 1.0, s[42:43]
	v_fma_f32 v72, -v12, v64, v72
	v_fma_f32 v72, -v13, v65, v72
	v_fma_f32 v72, -v14, v66, v72
	v_fma_f32 v72, -v15, v67, v72
	v_fma_f32 v72, -v16, v68, v72
	v_fma_f32 v72, -v17, v69, v72
	v_fma_f32 v72, -v18, v70, v72
	v_fma_f32 v72, -v19, v71, v72
	ds_read_b128 v[12:15], v2 offset:2816
	ds_read_b128 v[16:19], v2 offset:2832
	s_waitcnt lgkmcnt(6)
	s_lshl_b64 s[42:43], 1, 9
	v_cndmask_b32_e64 v73, 0, 1.0, s[42:43]
	v_fma_f32 v73, -v20, v64, v73
	v_fma_f32 v73, -v21, v65, v73
	v_fma_f32 v73, -v22, v66, v73
	v_fma_f32 v73, -v23, v67, v73
	v_fma_f32 v73, -v24, v68, v73
	v_fma_f32 v73, -v25, v69, v73
	v_fma_f32 v73, -v26, v70, v73
	v_fma_f32 v73, -v27, v71, v73
	ds_read_b128 v[20:23], v2 offset:2848
	ds_read_b128 v[24:27], v2 offset:3072
	s_waitcnt lgkmcnt(6)
	v_fma_f32 v73, -v28, v72, v73
	s_lshl_b64 s[42:43], 1, 10
	v_cndmask_b32_e64 v74, 0, 1.0, s[42:43]
	v_fma_f32 v74, -v32, v64, v74
	v_fma_f32 v74, -v33, v65, v74
	v_fma_f32 v74, -v34, v66, v74
	v_fma_f32 v74, -v35, v67, v74
	ds_read_b128 v[28:31], v2 offset:3088
	ds_read_b128 v[32:35], v2 offset:3104
	s_waitcnt lgkmcnt(6)
	v_fma_f32 v74, -v4, v68, v74
	v_fma_f32 v74, -v5, v69, v74
	v_fma_f32 v74, -v6, v70, v74
	v_fma_f32 v74, -v7, v71, v74
	v_fma_f32 v74, -v8, v72, v74
	v_fma_f32 v74, -v9, v73, v74
	ds_read_b128 v[4:7], v2 offset:3328
	ds_read_b128 v[8:11], v2 offset:3344
	s_waitcnt lgkmcnt(6)
	s_lshl_b64 s[42:43], 1, 11
	v_cndmask_b32_e64 v75, 0, 1.0, s[42:43]
	v_fma_f32 v75, -v12, v64, v75
	v_fma_f32 v75, -v13, v65, v75
	v_fma_f32 v75, -v14, v66, v75
	v_fma_f32 v75, -v15, v67, v75
	v_fma_f32 v75, -v16, v68, v75
	v_fma_f32 v75, -v17, v69, v75
	v_fma_f32 v75, -v18, v70, v75
	v_fma_f32 v75, -v19, v71, v75
	ds_read_b128 v[12:15], v2 offset:3360
	ds_read_b128 v[16:19], v2 offset:3376
	s_waitcnt lgkmcnt(6)
	v_fma_f32 v75, -v20, v72, v75
	v_fma_f32 v75, -v21, v73, v75
	v_fma_f32 v75, -v22, v74, v75
	s_lshl_b64 s[42:43], 1, 12
	v_cndmask_b32_e64 v76, 0, 1.0, s[42:43]
	v_fma_f32 v76, -v24, v64, v76
	v_fma_f32 v76, -v25, v65, v76
	v_fma_f32 v76, -v26, v66, v76
	v_fma_f32 v76, -v27, v67, v76
	ds_read_b128 v[20:23], v2 offset:3584
	ds_read_b128 v[24:27], v2 offset:3600
	s_waitcnt lgkmcnt(6)
	v_fma_f32 v76, -v28, v68, v76
	v_fma_f32 v76, -v29, v69, v76
	v_fma_f32 v76, -v30, v70, v76
	v_fma_f32 v76, -v31, v71, v76
	v_fma_f32 v76, -v32, v72, v76
	v_fma_f32 v76, -v33, v73, v76
	v_fma_f32 v76, -v34, v74, v76
	v_fma_f32 v76, -v35, v75, v76
	ds_read_b128 v[28:31], v2 offset:3616
	ds_read_b128 v[32:35], v2 offset:3632
	s_waitcnt lgkmcnt(6)
	s_lshl_b64 s[42:43], 1, 13
	v_cndmask_b32_e64 v77, 0, 1.0, s[42:43]
	v_fma_f32 v77, -v4, v64, v77
	v_fma_f32 v77, -v5, v65, v77
	v_fma_f32 v77, -v6, v66, v77
	v_fma_f32 v77, -v7, v67, v77
	v_fma_f32 v77, -v8, v68, v77
	v_fma_f32 v77, -v9, v69, v77
	v_fma_f32 v77, -v10, v70, v77
	v_fma_f32 v77, -v11, v71, v77
	ds_read_b128 v[4:7], v2 offset:3840
	ds_read_b128 v[8:11], v2 offset:3856
	s_waitcnt lgkmcnt(6)
	v_fma_f32 v77, -v12, v72, v77
	v_fma_f32 v77, -v13, v73, v77
	v_fma_f32 v77, -v14, v74, v77
	v_fma_f32 v77, -v15, v75, v77
	v_fma_f32 v77, -v16, v76, v77
	ds_read_b128 v[12:15], v2 offset:3872
	ds_read_b128 v[16:19], v2 offset:3888
	s_waitcnt lgkmcnt(6)
	s_lshl_b64 s[42:43], 1, 14
	v_cndmask_b32_e64 v78, 0, 1.0, s[42:43]
	v_fma_f32 v78, -v20, v64, v78
	v_fma_f32 v78, -v21, v65, v78
	v_fma_f32 v78, -v22, v66, v78
	v_fma_f32 v78, -v23, v67, v78
	v_fma_f32 v78, -v24, v68, v78
	v_fma_f32 v78, -v25, v69, v78
	v_fma_f32 v78, -v26, v70, v78
	v_fma_f32 v78, -v27, v71, v78
	ds_read_b128 v[20:23], v2 offset:4096
	ds_read_b128 v[24:27], v2 offset:4112
	s_waitcnt lgkmcnt(6)
	v_fma_f32 v78, -v28, v72, v78
	v_fma_f32 v78, -v29, v73, v78
	v_fma_f32 v78, -v30, v74, v78
	v_fma_f32 v78, -v31, v75, v78
	v_fma_f32 v78, -v32, v76, v78
	v_fma_f32 v78, -v33, v77, v78
	ds_read_b128 v[28:31], v2 offset:4128
	ds_read_b128 v[32:35], v2 offset:4144
	s_waitcnt lgkmcnt(6)
	s_lshl_b64 s[42:43], 1, 15
	v_cndmask_b32_e64 v79, 0, 1.0, s[42:43]
	v_fma_f32 v79, -v4, v64, v79
	v_fma_f32 v79, -v5, v65, v79
	v_fma_f32 v79, -v6, v66, v79
	v_fma_f32 v79, -v7, v67, v79
	v_fma_f32 v79, -v8, v68, v79
	v_fma_f32 v79, -v9, v69, v79
	v_fma_f32 v79, -v10, v70, v79
	v_fma_f32 v79, -v11, v71, v79
	ds_read_b128 v[4:7], v2 offset:4352
	ds_read_b128 v[8:11], v2 offset:4368
	s_waitcnt lgkmcnt(6)
	v_fma_f32 v79, -v12, v72, v79
	v_fma_f32 v79, -v13, v73, v79
	v_fma_f32 v79, -v14, v74, v79
	v_fma_f32 v79, -v15, v75, v79
	v_fma_f32 v79, -v16, v76, v79
	v_fma_f32 v79, -v17, v77, v79
	v_fma_f32 v79, -v18, v78, v79
	ds_read_b128 v[12:15], v2 offset:4384
	ds_read_b128 v[16:19], v2 offset:4400
	s_waitcnt lgkmcnt(6)
	s_lshl_b64 s[42:43], 1, 16
	v_cndmask_b32_e64 v80, 0, 1.0, s[42:43]
	v_fma_f32 v80, -v20, v64, v80
	v_fma_f32 v80, -v21, v65, v80
	v_fma_f32 v80, -v22, v66, v80
	v_fma_f32 v80, -v23, v67, v80
	v_fma_f32 v80, -v24, v68, v80
	v_fma_f32 v80, -v25, v69, v80
	v_fma_f32 v80, -v26, v70, v80
	v_fma_f32 v80, -v27, v71, v80
	ds_read_b128 v[20:23], v2 offset:4416
	ds_read_b128 v[24:27], v2 offset:4608
	s_waitcnt lgkmcnt(6)
; #define LAS __attribute__((address_space(3)))
; __device__ __forceinline__ void dk_phase(const Frame& F, const bf16* QKrm, const unsigned char* KT, const unsigned char* VT, const float* BG, unsigned char* ITEMS) {
;     ...
;         float t[64];
; #pragma unroll
;         for (int r = 0; r < 64; ++r) {
;             float acc = (lane == r) ? 1.f : 0.f;
; #pragma unroll
;             for (int s4 = 0; s4 < (r + 3) / 4; ++s4) { const f32x4 a = *(const LAS f32x4*)(Amat + r * 64 + 4 * s4);
;                 if (4 * s4 + 0 < r) acc -= a.x * t[4 * s4 + 0]; if (4 * s4 + 1 < r) acc -= a.y * t[4 * s4 + 1];
;                 if (4 * s4 + 2 < r) acc -= a.z * t[4 * s4 + 2]; if (4 * s4 + 3 < r) acc -= a.w * t[4 * s4 + 3]; }
;             t[r] = acc;
;         }
	v_fma_f32 v80, -v28, v72, v80
	v_fma_f32 v80, -v29, v73, v80
	v_fma_f32 v80, -v30, v74, v80
	v_fma_f32 v80, -v31, v75, v80
	v_fma_f32 v80, -v32, v76, v80
	v_fma_f32 v80, -v33, v77, v80
	v_fma_f32 v80, -v34, v78, v80
	v_fma_f32 v80, -v35, v79, v80
	ds_read_b128 v[28:31], v2 offset:4624
	ds_read_b128 v[32:35], v2 offset:4640
	s_waitcnt lgkmcnt(6)
	s_lshl_b64 s[42:43], 1, 17
	v_cndmask_b32_e64 v81, 0, 1.0, s[42:43]
	v_fma_f32 v81, -v4, v64, v81
	v_fma_f32 v81, -v5, v65, v81
	v_fma_f32 v81, -v6, v66, v81
	v_fma_f32 v81, -v7, v67, v81
	v_fma_f32 v81, -v8, v68, v81
	v_fma_f32 v81, -v9, v69, v81
	v_fma_f32 v81, -v10, v70, v81
	v_fma_f32 v81, -v11, v71, v81
	ds_read_b128 v[4:7], v2 offset:4656
	ds_read_b128 v[8:11], v2 offset:4672
	s_waitcnt lgkmcnt(6)
	v_fma_f32 v81, -v12, v72, v81
	v_fma_f32 v81, -v13, v73, v81
	v_fma_f32 v81, -v14, v74, v81
	v_fma_f32 v81, -v15, v75, v81
	v_fma_f32 v81, -v16, v76, v81
	v_fma_f32 v81, -v17, v77, v81
	v_fma_f32 v81, -v18, v78, v81
	v_fma_f32 v81, -v19, v79, v81
	ds_read_b128 v[12:15], v2 offset:4864
	ds_read_b128 v[16:19], v2 offset:4880
	s_waitcnt lgkmcnt(6)
	v_fma_f32 v81, -v20, v80, v81
	s_lshl_b64 s[42:43], 1, 18
	v_cndmask_b32_e64 v82, 0, 1.0, s[42:43]
	v_fma_f32 v82, -v24, v64, v82
	v_fma_f32 v82, -v25, v65, v82
	v_fma_f32 v82, -v26, v66, v82
	v_fma_f32 v82, -v27, v67, v82
	ds_read_b128 v[20:23], v2 offset:4896
	ds_read_b128 v[24:27], v2 offset:4912
	s_waitcnt lgkmcnt(6)
	v_fma_f32 v82, -v28, v68, v82
	v_fma_f32 v82, -v29, v69, v82
	v_fma_f32 v82, -v30, v70, v82
	v_fma_f32 v82, -v31, v71, v82
	v_fma_f32 v82, -v32, v72, v82
	v_fma_f32 v82, -v33, v73, v82
	v_fma_f32 v82, -v34, v74, v82
	v_fma_f32 v82, -v35, v75, v82
	ds_read_b128 v[28:31], v2 offset:4928
	ds_read_b128 v[32:35], v2 offset:5120
	s_waitcnt lgkmcnt(6)
	v_fma_f32 v82, -v4, v76, v82
	v_fma_f32 v82, -v5, v77, v82
	v_fma_f32 v82, -v6, v78, v82
	v_fma_f32 v82, -v7, v79, v82
	v_fma_f32 v82, -v8, v80, v82
	v_fma_f32 v82, -v9, v81, v82
	ds_read_b128 v[4:7], v2 offset:5136
	ds_read_b128 v[8:11], v2 offset:5152
	s_waitcnt lgkmcnt(6)
	s_lshl_b64 s[42:43], 1, 19
	v_cndmask_b32_e64 v83, 0, 1.0, s[42:43]
	v_fma_f32 v83, -v12, v64, v83
	v_fma_f32 v83, -v13, v65, v83
	v_fma_f32 v83, -v14, v66, v83
	v_fma_f32 v83, -v15, v67, v83
	v_fma_f32 v83, -v16, v68, v83
	v_fma_f32 v83, -v17, v69, v83
	v_fma_f32 v83, -v18, v70, v83
	v_fma_f32 v83, -v19, v71, v83
	ds_read_b128 v[12:15], v2 offset:5168
	ds_read_b128 v[16:19], v2 offset:5184
	s_waitcnt lgkmcnt(6)
	v_fma_f32 v83, -v20, v72, v83
	v_fma_f32 v83, -v21, v73, v83
	v_fma_f32 v83, -v22, v74, v83
	v_fma_f32 v83, -v23, v75, v83
	v_fma_f32 v83, -v24, v76, v83
	v_fma_f32 v83, -v25, v77, v83
	v_fma_f32 v83, -v26, v78, v83
	v_fma_f32 v83, -v27, v79, v83
	ds_read_b128 v[20:23], v2 offset:5376
	ds_read_b128 v[24:27], v2 offset:5392
	s_waitcnt lgkmcnt(6)
	v_fma_f32 v83, -v28, v80, v83
	v_fma_f32 v83, -v29, v81, v83
	v_fma_f32 v83, -v30, v82, v83
	s_lshl_b64 s[42:43], 1, 20
	v_cndmask_b32_e64 v84, 0, 1.0, s[42:43]
	v_fma_f32 v84, -v32, v64, v84
	v_fma_f32 v84, -v33, v65, v84
	v_fma_f32 v84, -v34, v66, v84
	v_fma_f32 v84, -v35, v67, v84
	ds_read_b128 v[28:31], v2 offset:5408
	ds_read_b128 v[32:35], v2 offset:5424
	s_waitcnt lgkmcnt(6)
	v_fma_f32 v84, -v4, v68, v84
	v_fma_f32 v84, -v5, v69, v84
	v_fma_f32 v84, -v6, v70, v84
	v_fma_f32 v84, -v7, v71, v84
	v_fma_f32 v84, -v8, v72, v84
	v_fma_f32 v84, -v9, v73, v84
	v_fma_f32 v84, -v10, v74, v84
	v_fma_f32 v84, -v11, v75, v84
	ds_read_b128 v[4:7], v2 offset:5440
	ds_read_b128 v[8:11], v2 offset:5456
	s_waitcnt lgkmcnt(6)
	v_fma_f32 v84, -v12, v76, v84
	v_fma_f32 v84, -v13, v77, v84
	v_fma_f32 v84, -v14, v78, v84
	v_fma_f32 v84, -v15, v79, v84
	v_fma_f32 v84, -v16, v80, v84
	v_fma_f32 v84, -v17, v81, v84
	v_fma_f32 v84, -v18, v82, v84
	v_fma_f32 v84, -v19, v83, v84
	ds_read_b128 v[12:15], v2 offset:5632
	ds_read_b128 v[16:19], v2 offset:5648
	s_waitcnt lgkmcnt(6)
	s_lshl_b64 s[42:43], 1, 21
	v_cndmask_b32_e64 v85, 0, 1.0, s[42:43]
	v_fma_f32 v85, -v20, v64, v85
	v_fma_f32 v85, -v21, v65, v85
	v_fma_f32 v85, -v22, v66, v85
	v_fma_f32 v85, -v23, v67, v85
	v_fma_f32 v85, -v24, v68, v85
	v_fma_f32 v85, -v25, v69, v85
	v_fma_f32 v85, -v26, v70, v85
	v_fma_f32 v85, -v27, v71, v85
	ds_read_b128 v[20:23], v2 offset:5664
	ds_read_b128 v[24:27], v2 offset:5680
	s_waitcnt lgkmcnt(6)
	v_fma_f32 v85, -v28, v72, v85
	v_fma_f32 v85, -v29, v73, v85
	v_fma_f32 v85, -v30, v74, v85
	v_fma_f32 v85, -v31, v75, v85
	v_fma_f32 v85, -v32, v76, v85
	v_fma_f32 v85, -v33, v77, v85
	v_fma_f32 v85, -v34, v78, v85
	v_fma_f32 v85, -v35, v79, v85
	ds_read_b128 v[28:31], v2 offset:5696
	ds_read_b128 v[32:35], v2 offset:5712
	s_waitcnt lgkmcnt(6)
	v_fma_f32 v85, -v4, v80, v85
	v_fma_f32 v85, -v5, v81, v85
	v_fma_f32 v85, -v6, v82, v85
	v_fma_f32 v85, -v7, v83, v85
	v_fma_f32 v85, -v8, v84, v85
	ds_read_b128 v[4:7], v2 offset:5888
	ds_read_b128 v[8:11], v2 offset:5904
	s_waitcnt lgkmcnt(6)
	s_lshl_b64 s[42:43], 1, 22
	v_cndmask_b32_e64 v86, 0, 1.0, s[42:43]
	v_fma_f32 v86, -v12, v64, v86
	v_fma_f32 v86, -v13, v65, v86
	v_fma_f32 v86, -v14, v66, v86
	v_fma_f32 v86, -v15, v67, v86
	v_fma_f32 v86, -v16, v68, v86
	v_fma_f32 v86, -v17, v69, v86
	v_fma_f32 v86, -v18, v70, v86
	v_fma_f32 v86, -v19, v71, v86
	ds_read_b128 v[12:15], v2 offset:5920
	ds_read_b128 v[16:19], v2 offset:5936
	s_waitcnt lgkmcnt(6)
	v_fma_f32 v86, -v20, v72, v86
	v_fma_f32 v86, -v21, v73, v86
	v_fma_f32 v86, -v22, v74, v86
	v_fma_f32 v86, -v23, v75, v86
	v_fma_f32 v86, -v24, v76, v86
	v_fma_f32 v86, -v25, v77, v86
	v_fma_f32 v86, -v26, v78, v86
	v_fma_f32 v86, -v27, v79, v86
	ds_read_b128 v[20:23], v2 offset:5952
	ds_read_b128 v[24:27], v2 offset:5968
	s_waitcnt lgkmcnt(6)
; #define LAS __attribute__((address_space(3)))
; __device__ __forceinline__ void dk_phase(const Frame& F, const bf16* QKrm, const unsigned char* KT, const unsigned char* VT, const float* BG, unsigned char* ITEMS) {
;     ...
;         float t[64];
; #pragma unroll
;         for (int r = 0; r < 64; ++r) {
;             float acc = (lane == r) ? 1.f : 0.f;
; #pragma unroll
;             for (int s4 = 0; s4 < (r + 3) / 4; ++s4) { const f32x4 a = *(const LAS f32x4*)(Amat + r * 64 + 4 * s4);
;                 if (4 * s4 + 0 < r) acc -= a.x * t[4 * s4 + 0]; if (4 * s4 + 1 < r) acc -= a.y * t[4 * s4 + 1];
;                 if (4 * s4 + 2 < r) acc -= a.z * t[4 * s4 + 2]; if (4 * s4 + 3 < r) acc -= a.w * t[4 * s4 + 3]; }
;             t[r] = acc;
;         }
	v_fma_f32 v86, -v28, v80, v86
	v_fma_f32 v86, -v29, v81, v86
	v_fma_f32 v86, -v30, v82, v86
	v_fma_f32 v86, -v31, v83, v86
	v_fma_f32 v86, -v32, v84, v86
	v_fma_f32 v86, -v33, v85, v86
	ds_read_b128 v[28:31], v2 offset:6144
	ds_read_b128 v[32:35], v2 offset:6160
	s_waitcnt lgkmcnt(6)
	s_lshl_b64 s[42:43], 1, 23
	v_cndmask_b32_e64 v87, 0, 1.0, s[42:43]
	v_fma_f32 v87, -v4, v64, v87
	v_fma_f32 v87, -v5, v65, v87
	v_fma_f32 v87, -v6, v66, v87
	v_fma_f32 v87, -v7, v67, v87
	v_fma_f32 v87, -v8, v68, v87
	v_fma_f32 v87, -v9, v69, v87
	v_fma_f32 v87, -v10, v70, v87
	v_fma_f32 v87, -v11, v71, v87
	ds_read_b128 v[4:7], v2 offset:6176
	ds_read_b128 v[8:11], v2 offset:6192
	s_waitcnt lgkmcnt(6)
	v_fma_f32 v87, -v12, v72, v87
	v_fma_f32 v87, -v13, v73, v87
	v_fma_f32 v87, -v14, v74, v87
	v_fma_f32 v87, -v15, v75, v87
	v_fma_f32 v87, -v16, v76, v87
	v_fma_f32 v87, -v17, v77, v87
	v_fma_f32 v87, -v18, v78, v87
	v_fma_f32 v87, -v19, v79, v87
	ds_read_b128 v[12:15], v2 offset:6208
	ds_read_b128 v[16:19], v2 offset:6224
	s_waitcnt lgkmcnt(6)
	v_fma_f32 v87, -v20, v80, v87
	v_fma_f32 v87, -v21, v81, v87
	v_fma_f32 v87, -v22, v82, v87
	v_fma_f32 v87, -v23, v83, v87
	v_fma_f32 v87, -v24, v84, v87
	v_fma_f32 v87, -v25, v85, v87
	v_fma_f32 v87, -v26, v86, v87
	ds_read_b128 v[20:23], v2 offset:6400
	ds_read_b128 v[24:27], v2 offset:6416
	s_waitcnt lgkmcnt(6)
	s_lshl_b64 s[42:43], 1, 24
	v_cndmask_b32_e64 v88, 0, 1.0, s[42:43]
	v_fma_f32 v88, -v28, v64, v88
	v_fma_f32 v88, -v29, v65, v88
	v_fma_f32 v88, -v30, v66, v88
	v_fma_f32 v88, -v31, v67, v88
	v_fma_f32 v88, -v32, v68, v88
	v_fma_f32 v88, -v33, v69, v88
	v_fma_f32 v88, -v34, v70, v88
	v_fma_f32 v88, -v35, v71, v88
	ds_read_b128 v[28:31], v2 offset:6432
	ds_read_b128 v[32:35], v2 offset:6448
	s_waitcnt lgkmcnt(6)
	v_fma_f32 v88, -v4, v72, v88
	v_fma_f32 v88, -v5, v73, v88
	v_fma_f32 v88, -v6, v74, v88
	v_fma_f32 v88, -v7, v75, v88
	v_fma_f32 v88, -v8, v76, v88
	v_fma_f32 v88, -v9, v77, v88
	v_fma_f32 v88, -v10, v78, v88
	v_fma_f32 v88, -v11, v79, v88
	ds_read_b128 v[4:7], v2 offset:6464
	ds_read_b128 v[8:11], v2 offset:6480
	s_waitcnt lgkmcnt(6)
	v_fma_f32 v88, -v12, v80, v88
	v_fma_f32 v88, -v13, v81, v88
	v_fma_f32 v88, -v14, v82, v88
	v_fma_f32 v88, -v15, v83, v88
	v_fma_f32 v88, -v16, v84, v88
	v_fma_f32 v88, -v17, v85, v88
	v_fma_f32 v88, -v18, v86, v88
	v_fma_f32 v88, -v19, v87, v88
	ds_read_b128 v[12:15], v2 offset:6496
	ds_read_b128 v[16:19], v2 offset:6656
	s_waitcnt lgkmcnt(6)
	s_lshl_b64 s[42:43], 1, 25
	v_cndmask_b32_e64 v89, 0, 1.0, s[42:43]
	v_fma_f32 v89, -v20, v64, v89
	v_fma_f32 v89, -v21, v65, v89
	v_fma_f32 v89, -v22, v66, v89
	v_fma_f32 v89, -v23, v67, v89
	v_fma_f32 v89, -v24, v68, v89
	v_fma_f32 v89, -v25, v69, v89
	v_fma_f32 v89, -v26, v70, v89
	v_fma_f32 v89, -v27, v71, v89
	ds_read_b128 v[20:23], v2 offset:6672
	ds_read_b128 v[24:27], v2 offset:6688
	s_waitcnt lgkmcnt(6)
	v_fma_f32 v89, -v28, v72, v89
	v_fma_f32 v89, -v29, v73, v89
	v_fma_f32 v89, -v30, v74, v89
	v_fma_f32 v89, -v31, v75, v89
	v_fma_f32 v89, -v32, v76, v89
	v_fma_f32 v89, -v33, v77, v89
	v_fma_f32 v89, -v34, v78, v89
	v_fma_f32 v89, -v35, v79, v89
	ds_read_b128 v[28:31], v2 offset:6704
	ds_read_b128 v[32:35], v2 offset:6720
	s_waitcnt lgkmcnt(6)
	v_fma_f32 v89, -v4, v80, v89
	v_fma_f32 v89, -v5, v81, v89
	v_fma_f32 v89, -v6, v82, v89
	v_fma_f32 v89, -v7, v83, v89
	v_fma_f32 v89, -v8, v84, v89
	v_fma_f32 v89, -v9, v85, v89
	v_fma_f32 v89, -v10, v86, v89
	v_fma_f32 v89, -v11, v87, v89
	ds_read_b128 v[4:7], v2 offset:6736
	ds_read_b128 v[8:11], v2 offset:6752
	s_waitcnt lgkmcnt(6)
	v_fma_f32 v89, -v12, v88, v89
	s_lshl_b64 s[42:43], 1, 26
	v_cndmask_b32_e64 v90, 0, 1.0, s[42:43]
	v_fma_f32 v90, -v16, v64, v90
	v_fma_f32 v90, -v17, v65, v90
	v_fma_f32 v90, -v18, v66, v90
	v_fma_f32 v90, -v19, v67, v90
	ds_read_b128 v[12:15], v2 offset:6912
	ds_read_b128 v[16:19], v2 offset:6928
	s_waitcnt lgkmcnt(6)
	v_fma_f32 v90, -v20, v68, v90
	v_fma_f32 v90, -v21, v69, v90
	v_fma_f32 v90, -v22, v70, v90
	v_fma_f32 v90, -v23, v71, v90
	v_fma_f32 v90, -v24, v72, v90
	v_fma_f32 v90, -v25, v73, v90
	v_fma_f32 v90, -v26, v74, v90
	v_fma_f32 v90, -v27, v75, v90
	ds_read_b128 v[20:23], v2 offset:6944
	ds_read_b128 v[24:27], v2 offset:6960
	s_waitcnt lgkmcnt(6)
	v_fma_f32 v90, -v28, v76, v90
	v_fma_f32 v90, -v29, v77, v90
	v_fma_f32 v90, -v30, v78, v90
	v_fma_f32 v90, -v31, v79, v90
	v_fma_f32 v90, -v32, v80, v90
	v_fma_f32 v90, -v33, v81, v90
	v_fma_f32 v90, -v34, v82, v90
	v_fma_f32 v90, -v35, v83, v90
	ds_read_b128 v[28:31], v2 offset:6976
	ds_read_b128 v[32:35], v2 offset:6992
	s_waitcnt lgkmcnt(6)
	v_fma_f32 v90, -v4, v84, v90
	v_fma_f32 v90, -v5, v85, v90
	v_fma_f32 v90, -v6, v86, v90
	v_fma_f32 v90, -v7, v87, v90
	v_fma_f32 v90, -v8, v88, v90
	v_fma_f32 v90, -v9, v89, v90
	ds_read_b128 v[4:7], v2 offset:7008
	ds_read_b128 v[8:11], v2 offset:7168
	s_waitcnt lgkmcnt(6)
	s_lshl_b64 s[42:43], 1, 27
	v_cndmask_b32_e64 v91, 0, 1.0, s[42:43]
	v_fma_f32 v91, -v12, v64, v91
	v_fma_f32 v91, -v13, v65, v91
	v_fma_f32 v91, -v14, v66, v91
	v_fma_f32 v91, -v15, v67, v91
	v_fma_f32 v91, -v16, v68, v91
	v_fma_f32 v91, -v17, v69, v91
	v_fma_f32 v91, -v18, v70, v91
	v_fma_f32 v91, -v19, v71, v91
	ds_read_b128 v[12:15], v2 offset:7184
	ds_read_b128 v[16:19], v2 offset:7200
	s_waitcnt lgkmcnt(6)
	v_fma_f32 v91, -v20, v72, v91
	v_fma_f32 v91, -v21, v73, v91
	v_fma_f32 v91, -v22, v74, v91
	v_fma_f32 v91, -v23, v75, v91
	v_fma_f32 v91, -v24, v76, v91
	v_fma_f32 v91, -v25, v77, v91
	v_fma_f32 v91, -v26, v78, v91
	v_fma_f32 v91, -v27, v79, v91
	ds_read_b128 v[20:23], v2 offset:7216
	ds_read_b128 v[24:27], v2 offset:7232
	s_waitcnt lgkmcnt(6)
; #define LAS __attribute__((address_space(3)))
; __device__ __forceinline__ void dk_phase(const Frame& F, const bf16* QKrm, const unsigned char* KT, const unsigned char* VT, const float* BG, unsigned char* ITEMS) {
;     ...
;         float t[64];
; #pragma unroll
;         for (int r = 0; r < 64; ++r) {
;             float acc = (lane == r) ? 1.f : 0.f;
; #pragma unroll
;             for (int s4 = 0; s4 < (r + 3) / 4; ++s4) { const f32x4 a = *(const LAS f32x4*)(Amat + r * 64 + 4 * s4);
;                 if (4 * s4 + 0 < r) acc -= a.x * t[4 * s4 + 0]; if (4 * s4 + 1 < r) acc -= a.y * t[4 * s4 + 1];
;                 if (4 * s4 + 2 < r) acc -= a.z * t[4 * s4 + 2]; if (4 * s4 + 3 < r) acc -= a.w * t[4 * s4 + 3]; }
;             t[r] = acc;
;         }
	v_fma_f32 v91, -v28, v80, v91
	v_fma_f32 v91, -v29, v81, v91
	v_fma_f32 v91, -v30, v82, v91
	v_fma_f32 v91, -v31, v83, v91
	v_fma_f32 v91, -v32, v84, v91
	v_fma_f32 v91, -v33, v85, v91
	v_fma_f32 v91, -v34, v86, v91
	v_fma_f32 v91, -v35, v87, v91
	ds_read_b128 v[28:31], v2 offset:7248
	ds_read_b128 v[32:35], v2 offset:7264
	s_waitcnt lgkmcnt(6)
	v_fma_f32 v91, -v4, v88, v91
	v_fma_f32 v91, -v5, v89, v91
	v_fma_f32 v91, -v6, v90, v91
	s_lshl_b64 s[42:43], 1, 28
	v_cndmask_b32_e64 v92, 0, 1.0, s[42:43]
	v_fma_f32 v92, -v8, v64, v92
	v_fma_f32 v92, -v9, v65, v92
	v_fma_f32 v92, -v10, v66, v92
	v_fma_f32 v92, -v11, v67, v92
	ds_read_b128 v[4:7], v2 offset:7424
	ds_read_b128 v[8:11], v2 offset:7440
	s_waitcnt lgkmcnt(6)
	v_fma_f32 v92, -v12, v68, v92
	v_fma_f32 v92, -v13, v69, v92
	v_fma_f32 v92, -v14, v70, v92
	v_fma_f32 v92, -v15, v71, v92
	v_fma_f32 v92, -v16, v72, v92
	v_fma_f32 v92, -v17, v73, v92
	v_fma_f32 v92, -v18, v74, v92
	v_fma_f32 v92, -v19, v75, v92
	ds_read_b128 v[12:15], v2 offset:7456
	ds_read_b128 v[16:19], v2 offset:7472
	s_waitcnt lgkmcnt(6)
	v_fma_f32 v92, -v20, v76, v92
	v_fma_f32 v92, -v21, v77, v92
	v_fma_f32 v92, -v22, v78, v92
	v_fma_f32 v92, -v23, v79, v92
	v_fma_f32 v92, -v24, v80, v92
	v_fma_f32 v92, -v25, v81, v92
	v_fma_f32 v92, -v26, v82, v92
	v_fma_f32 v92, -v27, v83, v92
	ds_read_b128 v[20:23], v2 offset:7488
	ds_read_b128 v[24:27], v2 offset:7504
	s_waitcnt lgkmcnt(6)
	v_fma_f32 v92, -v28, v84, v92
	v_fma_f32 v92, -v29, v85, v92
	v_fma_f32 v92, -v30, v86, v92
	v_fma_f32 v92, -v31, v87, v92
	v_fma_f32 v92, -v32, v88, v92
	v_fma_f32 v92, -v33, v89, v92
	v_fma_f32 v92, -v34, v90, v92
	v_fma_f32 v92, -v35, v91, v92
	ds_read_b128 v[28:31], v2 offset:7520
	ds_read_b128 v[32:35], v2 offset:7536
	s_waitcnt lgkmcnt(6)
	s_lshl_b64 s[42:43], 1, 29
	v_cndmask_b32_e64 v93, 0, 1.0, s[42:43]
	v_fma_f32 v93, -v4, v64, v93
	v_fma_f32 v93, -v5, v65, v93
	v_fma_f32 v93, -v6, v66, v93
	v_fma_f32 v93, -v7, v67, v93
	v_fma_f32 v93, -v8, v68, v93
	v_fma_f32 v93, -v9, v69, v93
	v_fma_f32 v93, -v10, v70, v93
	v_fma_f32 v93, -v11, v71, v93
	ds_read_b128 v[4:7], v2 offset:7680
	ds_read_b128 v[8:11], v2 offset:7696
	s_waitcnt lgkmcnt(6)
	v_fma_f32 v93, -v12, v72, v93
	v_fma_f32 v93, -v13, v73, v93
	v_fma_f32 v93, -v14, v74, v93
	v_fma_f32 v93, -v15, v75, v93
	v_fma_f32 v93, -v16, v76, v93
	v_fma_f32 v93, -v17, v77, v93
	v_fma_f32 v93, -v18, v78, v93
	v_fma_f32 v93, -v19, v79, v93
	ds_read_b128 v[12:15], v2 offset:7712
	ds_read_b128 v[16:19], v2 offset:7728
	s_waitcnt lgkmcnt(6)
	v_fma_f32 v93, -v20, v80, v93
	v_fma_f32 v93, -v21, v81, v93
	v_fma_f32 v93, -v22, v82, v93
	v_fma_f32 v93, -v23, v83, v93
	v_fma_f32 v93, -v24, v84, v93
	v_fma_f32 v93, -v25, v85, v93
	v_fma_f32 v93, -v26, v86, v93
	v_fma_f32 v93, -v27, v87, v93
	ds_read_b128 v[20:23], v2 offset:7744
	ds_read_b128 v[24:27], v2 offset:7760
	s_waitcnt lgkmcnt(6)
	v_fma_f32 v93, -v28, v88, v93
	v_fma_f32 v93, -v29, v89, v93
	v_fma_f32 v93, -v30, v90, v93
	v_fma_f32 v93, -v31, v91, v93
	v_fma_f32 v93, -v32, v92, v93
	ds_read_b128 v[28:31], v2 offset:7776
	ds_read_b128 v[32:35], v2 offset:7792
	s_waitcnt lgkmcnt(6)
	s_lshl_b64 s[42:43], 1, 30
	v_cndmask_b32_e64 v94, 0, 1.0, s[42:43]
	v_fma_f32 v94, -v4, v64, v94
	v_fma_f32 v94, -v5, v65, v94
	v_fma_f32 v94, -v6, v66, v94
	v_fma_f32 v94, -v7, v67, v94
	v_fma_f32 v94, -v8, v68, v94
	v_fma_f32 v94, -v9, v69, v94
	v_fma_f32 v94, -v10, v70, v94
	v_fma_f32 v94, -v11, v71, v94
	ds_read_b128 v[4:7], v2 offset:7936
	ds_read_b128 v[8:11], v2 offset:7952
	s_waitcnt lgkmcnt(6)
	v_fma_f32 v94, -v12, v72, v94
	v_fma_f32 v94, -v13, v73, v94
	v_fma_f32 v94, -v14, v74, v94
	v_fma_f32 v94, -v15, v75, v94
	v_fma_f32 v94, -v16, v76, v94
	v_fma_f32 v94, -v17, v77, v94
	v_fma_f32 v94, -v18, v78, v94
	v_fma_f32 v94, -v19, v79, v94
	ds_read_b128 v[12:15], v2 offset:7968
	ds_read_b128 v[16:19], v2 offset:7984
	s_waitcnt lgkmcnt(6)
	v_fma_f32 v94, -v20, v80, v94
	v_fma_f32 v94, -v21, v81, v94
	v_fma_f32 v94, -v22, v82, v94
	v_fma_f32 v94, -v23, v83, v94
	v_fma_f32 v94, -v24, v84, v94
	v_fma_f32 v94, -v25, v85, v94
	v_fma_f32 v94, -v26, v86, v94
	v_fma_f32 v94, -v27, v87, v94
	ds_read_b128 v[20:23], v2 offset:8000
	ds_read_b128 v[24:27], v2 offset:8016
	s_waitcnt lgkmcnt(6)
	v_fma_f32 v94, -v28, v88, v94
	v_fma_f32 v94, -v29, v89, v94
	v_fma_f32 v94, -v30, v90, v94
	v_fma_f32 v94, -v31, v91, v94
	v_fma_f32 v94, -v32, v92, v94
	v_fma_f32 v94, -v33, v93, v94
	ds_read_b128 v[28:31], v2 offset:8032
	ds_read_b128 v[32:35], v2 offset:8048
	s_waitcnt lgkmcnt(6)
	s_lshl_b64 s[42:43], 1, 31
	v_cndmask_b32_e64 v95, 0, 1.0, s[42:43]
	v_fma_f32 v95, -v4, v64, v95
	v_fma_f32 v95, -v5, v65, v95
	v_fma_f32 v95, -v6, v66, v95
	v_fma_f32 v95, -v7, v67, v95
	v_fma_f32 v95, -v8, v68, v95
	v_fma_f32 v95, -v9, v69, v95
	v_fma_f32 v95, -v10, v70, v95
	v_fma_f32 v95, -v11, v71, v95
	ds_read_b128 v[4:7], v2 offset:8192
	ds_read_b128 v[8:11], v2 offset:8208
	s_waitcnt lgkmcnt(6)
	v_fma_f32 v95, -v12, v72, v95
	v_fma_f32 v95, -v13, v73, v95
	v_fma_f32 v95, -v14, v74, v95
	v_fma_f32 v95, -v15, v75, v95
	v_fma_f32 v95, -v16, v76, v95
	v_fma_f32 v95, -v17, v77, v95
	v_fma_f32 v95, -v18, v78, v95
	v_fma_f32 v95, -v19, v79, v95
	ds_read_b128 v[12:15], v2 offset:8224
	ds_read_b128 v[16:19], v2 offset:8240
	s_waitcnt lgkmcnt(6)
	v_fma_f32 v95, -v20, v80, v95
	v_fma_f32 v95, -v21, v81, v95
	v_fma_f32 v95, -v22, v82, v95
	v_fma_f32 v95, -v23, v83, v95
	v_fma_f32 v95, -v24, v84, v95
	v_fma_f32 v95, -v25, v85, v95
	v_fma_f32 v95, -v26, v86, v95
	v_fma_f32 v95, -v27, v87, v95
	ds_read_b128 v[20:23], v2 offset:8256
	ds_read_b128 v[24:27], v2 offset:8272
	s_waitcnt lgkmcnt(6)
; #define LAS __attribute__((address_space(3)))
; __device__ __forceinline__ void dk_phase(const Frame& F, const bf16* QKrm, const unsigned char* KT, const unsigned char* VT, const float* BG, unsigned char* ITEMS) {
;     ...
;         float t[64];
; #pragma unroll
;         for (int r = 0; r < 64; ++r) {
;             float acc = (lane == r) ? 1.f : 0.f;
; #pragma unroll
;             for (int s4 = 0; s4 < (r + 3) / 4; ++s4) { const f32x4 a = *(const LAS f32x4*)(Amat + r * 64 + 4 * s4);
;                 if (4 * s4 + 0 < r) acc -= a.x * t[4 * s4 + 0]; if (4 * s4 + 1 < r) acc -= a.y * t[4 * s4 + 1];
;                 if (4 * s4 + 2 < r) acc -= a.z * t[4 * s4 + 2]; if (4 * s4 + 3 < r) acc -= a.w * t[4 * s4 + 3]; }
;             t[r] = acc;
;         }
	v_fma_f32 v95, -v28, v88, v95
	v_fma_f32 v95, -v29, v89, v95
	v_fma_f32 v95, -v30, v90, v95
	v_fma_f32 v95, -v31, v91, v95
	v_fma_f32 v95, -v32, v92, v95
	v_fma_f32 v95, -v33, v93, v95
	v_fma_f32 v95, -v34, v94, v95
	ds_read_b128 v[28:31], v2 offset:8288
	ds_read_b128 v[32:35], v2 offset:8304
	s_waitcnt lgkmcnt(6)
	s_lshl_b64 s[42:43], 1, 32
	v_cndmask_b32_e64 v96, 0, 1.0, s[42:43]
	v_fma_f32 v96, -v4, v64, v96
	v_fma_f32 v96, -v5, v65, v96
	v_fma_f32 v96, -v6, v66, v96
	v_fma_f32 v96, -v7, v67, v96
	v_fma_f32 v96, -v8, v68, v96
	v_fma_f32 v96, -v9, v69, v96
	v_fma_f32 v96, -v10, v70, v96
	v_fma_f32 v96, -v11, v71, v96
	ds_read_b128 v[4:7], v2 offset:8448
	ds_read_b128 v[8:11], v2 offset:8464
	s_waitcnt lgkmcnt(6)
	v_fma_f32 v96, -v12, v72, v96
	v_fma_f32 v96, -v13, v73, v96
	v_fma_f32 v96, -v14, v74, v96
	v_fma_f32 v96, -v15, v75, v96
	v_fma_f32 v96, -v16, v76, v96
	v_fma_f32 v96, -v17, v77, v96
	v_fma_f32 v96, -v18, v78, v96
	v_fma_f32 v96, -v19, v79, v96
	ds_read_b128 v[12:15], v2 offset:8480
	ds_read_b128 v[16:19], v2 offset:8496
	s_waitcnt lgkmcnt(6)
	v_fma_f32 v96, -v20, v80, v96
	v_fma_f32 v96, -v21, v81, v96
	v_fma_f32 v96, -v22, v82, v96
	v_fma_f32 v96, -v23, v83, v96
	v_fma_f32 v96, -v24, v84, v96
	v_fma_f32 v96, -v25, v85, v96
	v_fma_f32 v96, -v26, v86, v96
	v_fma_f32 v96, -v27, v87, v96
	ds_read_b128 v[20:23], v2 offset:8512
	ds_read_b128 v[24:27], v2 offset:8528
	s_waitcnt lgkmcnt(6)
	v_fma_f32 v96, -v28, v88, v96
	v_fma_f32 v96, -v29, v89, v96
	v_fma_f32 v96, -v30, v90, v96
	v_fma_f32 v96, -v31, v91, v96
	v_fma_f32 v96, -v32, v92, v96
	v_fma_f32 v96, -v33, v93, v96
	v_fma_f32 v96, -v34, v94, v96
	v_fma_f32 v96, -v35, v95, v96
	ds_read_b128 v[28:31], v2 offset:8544
	ds_read_b128 v[32:35], v2 offset:8560
	s_waitcnt lgkmcnt(6)
	s_lshl_b64 s[42:43], 1, 33
	v_cndmask_b32_e64 v97, 0, 1.0, s[42:43]
	v_fma_f32 v97, -v4, v64, v97
	v_fma_f32 v97, -v5, v65, v97
	v_fma_f32 v97, -v6, v66, v97
	v_fma_f32 v97, -v7, v67, v97
	v_fma_f32 v97, -v8, v68, v97
	v_fma_f32 v97, -v9, v69, v97
	v_fma_f32 v97, -v10, v70, v97
	v_fma_f32 v97, -v11, v71, v97
	ds_read_b128 v[4:7], v2 offset:8576
	ds_read_b128 v[8:11], v2 offset:8704
	s_waitcnt lgkmcnt(6)
	v_fma_f32 v97, -v12, v72, v97
	v_fma_f32 v97, -v13, v73, v97
	v_fma_f32 v97, -v14, v74, v97
	v_fma_f32 v97, -v15, v75, v97
	v_fma_f32 v97, -v16, v76, v97
	v_fma_f32 v97, -v17, v77, v97
	v_fma_f32 v97, -v18, v78, v97
	v_fma_f32 v97, -v19, v79, v97
	ds_read_b128 v[12:15], v2 offset:8720
	ds_read_b128 v[16:19], v2 offset:8736
	s_waitcnt lgkmcnt(6)
	v_fma_f32 v97, -v20, v80, v97
	v_fma_f32 v97, -v21, v81, v97
	v_fma_f32 v97, -v22, v82, v97
	v_fma_f32 v97, -v23, v83, v97
	v_fma_f32 v97, -v24, v84, v97
	v_fma_f32 v97, -v25, v85, v97
	v_fma_f32 v97, -v26, v86, v97
	v_fma_f32 v97, -v27, v87, v97
	ds_read_b128 v[20:23], v2 offset:8752
	ds_read_b128 v[24:27], v2 offset:8768
	s_waitcnt lgkmcnt(6)
	v_fma_f32 v97, -v28, v88, v97
	v_fma_f32 v97, -v29, v89, v97
	v_fma_f32 v97, -v30, v90, v97
	v_fma_f32 v97, -v31, v91, v97
	v_fma_f32 v97, -v32, v92, v97
	v_fma_f32 v97, -v33, v93, v97
	v_fma_f32 v97, -v34, v94, v97
	v_fma_f32 v97, -v35, v95, v97
	ds_read_b128 v[28:31], v2 offset:8784
	ds_read_b128 v[32:35], v2 offset:8800
	s_waitcnt lgkmcnt(6)
	v_fma_f32 v97, -v4, v96, v97
	s_lshl_b64 s[42:43], 1, 34
	v_cndmask_b32_e64 v98, 0, 1.0, s[42:43]
	v_fma_f32 v98, -v8, v64, v98
	v_fma_f32 v98, -v9, v65, v98
	v_fma_f32 v98, -v10, v66, v98
	v_fma_f32 v98, -v11, v67, v98
	ds_read_b128 v[4:7], v2 offset:8816
	ds_read_b128 v[8:11], v2 offset:8832
	s_waitcnt lgkmcnt(6)
	v_fma_f32 v98, -v12, v68, v98
	v_fma_f32 v98, -v13, v69, v98
	v_fma_f32 v98, -v14, v70, v98
	v_fma_f32 v98, -v15, v71, v98
	v_fma_f32 v98, -v16, v72, v98
	v_fma_f32 v98, -v17, v73, v98
	v_fma_f32 v98, -v18, v74, v98
	v_fma_f32 v98, -v19, v75, v98
	ds_read_b128 v[12:15], v2 offset:8960
	ds_read_b128 v[16:19], v2 offset:8976
	s_waitcnt lgkmcnt(6)
	v_fma_f32 v98, -v20, v76, v98
	v_fma_f32 v98, -v21, v77, v98
	v_fma_f32 v98, -v22, v78, v98
	v_fma_f32 v98, -v23, v79, v98
	v_fma_f32 v98, -v24, v80, v98
	v_fma_f32 v98, -v25, v81, v98
	v_fma_f32 v98, -v26, v82, v98
	v_fma_f32 v98, -v27, v83, v98
	ds_read_b128 v[20:23], v2 offset:8992
	ds_read_b128 v[24:27], v2 offset:9008
	s_waitcnt lgkmcnt(6)
	v_fma_f32 v98, -v28, v84, v98
	v_fma_f32 v98, -v29, v85, v98
	v_fma_f32 v98, -v30, v86, v98
	v_fma_f32 v98, -v31, v87, v98
	v_fma_f32 v98, -v32, v88, v98
	v_fma_f32 v98, -v33, v89, v98
	v_fma_f32 v98, -v34, v90, v98
	v_fma_f32 v98, -v35, v91, v98
	ds_read_b128 v[28:31], v2 offset:9024
	ds_read_b128 v[32:35], v2 offset:9040
	s_waitcnt lgkmcnt(6)
	v_fma_f32 v98, -v4, v92, v98
	v_fma_f32 v98, -v5, v93, v98
	v_fma_f32 v98, -v6, v94, v98
	v_fma_f32 v98, -v7, v95, v98
	v_fma_f32 v98, -v8, v96, v98
	v_fma_f32 v98, -v9, v97, v98
	ds_read_b128 v[4:7], v2 offset:9056
	ds_read_b128 v[8:11], v2 offset:9072
	s_waitcnt lgkmcnt(6)
	s_lshl_b64 s[42:43], 1, 35
	v_cndmask_b32_e64 v99, 0, 1.0, s[42:43]
	v_fma_f32 v99, -v12, v64, v99
	v_fma_f32 v99, -v13, v65, v99
	v_fma_f32 v99, -v14, v66, v99
	v_fma_f32 v99, -v15, v67, v99
	v_fma_f32 v99, -v16, v68, v99
	v_fma_f32 v99, -v17, v69, v99
	v_fma_f32 v99, -v18, v70, v99
	v_fma_f32 v99, -v19, v71, v99
	ds_read_b128 v[12:15], v2 offset:9088
	ds_read_b128 v[16:19], v2 offset:9216
	s_waitcnt lgkmcnt(6)
	v_fma_f32 v99, -v20, v72, v99
	v_fma_f32 v99, -v21, v73, v99
	v_fma_f32 v99, -v22, v74, v99
	v_fma_f32 v99, -v23, v75, v99
	v_fma_f32 v99, -v24, v76, v99
	v_fma_f32 v99, -v25, v77, v99
	v_fma_f32 v99, -v26, v78, v99
	v_fma_f32 v99, -v27, v79, v99
	ds_read_b128 v[20:23], v2 offset:9232
	ds_read_b128 v[24:27], v2 offset:9248
	s_waitcnt lgkmcnt(6)
; #define LAS __attribute__((address_space(3)))
; __device__ __forceinline__ void dk_phase(const Frame& F, const bf16* QKrm, const unsigned char* KT, const unsigned char* VT, const float* BG, unsigned char* ITEMS) {
;     ...
;         float t[64];
; #pragma unroll
;         for (int r = 0; r < 64; ++r) {
;             float acc = (lane == r) ? 1.f : 0.f;
; #pragma unroll
;             for (int s4 = 0; s4 < (r + 3) / 4; ++s4) { const f32x4 a = *(const LAS f32x4*)(Amat + r * 64 + 4 * s4);
;                 if (4 * s4 + 0 < r) acc -= a.x * t[4 * s4 + 0]; if (4 * s4 + 1 < r) acc -= a.y * t[4 * s4 + 1];
;                 if (4 * s4 + 2 < r) acc -= a.z * t[4 * s4 + 2]; if (4 * s4 + 3 < r) acc -= a.w * t[4 * s4 + 3]; }
;             t[r] = acc;
;         }
	v_fma_f32 v99, -v28, v80, v99
	v_fma_f32 v99, -v29, v81, v99
	v_fma_f32 v99, -v30, v82, v99
	v_fma_f32 v99, -v31, v83, v99
	v_fma_f32 v99, -v32, v84, v99
	v_fma_f32 v99, -v33, v85, v99
	v_fma_f32 v99, -v34, v86, v99
	v_fma_f32 v99, -v35, v87, v99
	ds_read_b128 v[28:31], v2 offset:9264
	ds_read_b128 v[32:35], v2 offset:9280
	s_waitcnt lgkmcnt(6)
	v_fma_f32 v99, -v4, v88, v99
	v_fma_f32 v99, -v5, v89, v99
	v_fma_f32 v99, -v6, v90, v99
	v_fma_f32 v99, -v7, v91, v99
	v_fma_f32 v99, -v8, v92, v99
	v_fma_f32 v99, -v9, v93, v99
	v_fma_f32 v99, -v10, v94, v99
	v_fma_f32 v99, -v11, v95, v99
	ds_read_b128 v[4:7], v2 offset:9296
	ds_read_b128 v[8:11], v2 offset:9312
	s_waitcnt lgkmcnt(6)
	v_fma_f32 v99, -v12, v96, v99
	v_fma_f32 v99, -v13, v97, v99
	v_fma_f32 v99, -v14, v98, v99
	s_lshl_b64 s[42:43], 1, 36
	v_cndmask_b32_e64 v100, 0, 1.0, s[42:43]
	v_fma_f32 v100, -v16, v64, v100
	v_fma_f32 v100, -v17, v65, v100
	v_fma_f32 v100, -v18, v66, v100
	v_fma_f32 v100, -v19, v67, v100
	ds_read_b128 v[12:15], v2 offset:9328
	ds_read_b128 v[16:19], v2 offset:9344
	s_waitcnt lgkmcnt(6)
	v_fma_f32 v100, -v20, v68, v100
	v_fma_f32 v100, -v21, v69, v100
	v_fma_f32 v100, -v22, v70, v100
	v_fma_f32 v100, -v23, v71, v100
	v_fma_f32 v100, -v24, v72, v100
	v_fma_f32 v100, -v25, v73, v100
	v_fma_f32 v100, -v26, v74, v100
	v_fma_f32 v100, -v27, v75, v100
	ds_read_b128 v[20:23], v2 offset:9472
	ds_read_b128 v[24:27], v2 offset:9488
	s_waitcnt lgkmcnt(6)
	v_fma_f32 v100, -v28, v76, v100
	v_fma_f32 v100, -v29, v77, v100
	v_fma_f32 v100, -v30, v78, v100
	v_fma_f32 v100, -v31, v79, v100
	v_fma_f32 v100, -v32, v80, v100
	v_fma_f32 v100, -v33, v81, v100
	v_fma_f32 v100, -v34, v82, v100
	v_fma_f32 v100, -v35, v83, v100
	ds_read_b128 v[28:31], v2 offset:9504
	ds_read_b128 v[32:35], v2 offset:9520
	s_waitcnt lgkmcnt(6)
	v_fma_f32 v100, -v4, v84, v100
	v_fma_f32 v100, -v5, v85, v100
	v_fma_f32 v100, -v6, v86, v100
	v_fma_f32 v100, -v7, v87, v100
	v_fma_f32 v100, -v8, v88, v100
	v_fma_f32 v100, -v9, v89, v100
	v_fma_f32 v100, -v10, v90, v100
	v_fma_f32 v100, -v11, v91, v100
	ds_read_b128 v[4:7], v2 offset:9536
	ds_read_b128 v[8:11], v2 offset:9552
	s_waitcnt lgkmcnt(6)
	v_fma_f32 v100, -v12, v92, v100
	v_fma_f32 v100, -v13, v93, v100
	v_fma_f32 v100, -v14, v94, v100
	v_fma_f32 v100, -v15, v95, v100
	v_fma_f32 v100, -v16, v96, v100
	v_fma_f32 v100, -v17, v97, v100
	v_fma_f32 v100, -v18, v98, v100
	v_fma_f32 v100, -v19, v99, v100
	ds_read_b128 v[12:15], v2 offset:9568
	ds_read_b128 v[16:19], v2 offset:9584
	s_waitcnt lgkmcnt(6)
	s_lshl_b64 s[42:43], 1, 37
	v_cndmask_b32_e64 v101, 0, 1.0, s[42:43]
	v_fma_f32 v101, -v20, v64, v101
	v_fma_f32 v101, -v21, v65, v101
	v_fma_f32 v101, -v22, v66, v101
	v_fma_f32 v101, -v23, v67, v101
	v_fma_f32 v101, -v24, v68, v101
	v_fma_f32 v101, -v25, v69, v101
	v_fma_f32 v101, -v26, v70, v101
	v_fma_f32 v101, -v27, v71, v101
	ds_read_b128 v[20:23], v2 offset:9600
	ds_read_b128 v[24:27], v2 offset:9616
	s_waitcnt lgkmcnt(6)
	v_fma_f32 v101, -v28, v72, v101
	v_fma_f32 v101, -v29, v73, v101
	v_fma_f32 v101, -v30, v74, v101
	v_fma_f32 v101, -v31, v75, v101
	v_fma_f32 v101, -v32, v76, v101
	v_fma_f32 v101, -v33, v77, v101
	v_fma_f32 v101, -v34, v78, v101
	v_fma_f32 v101, -v35, v79, v101
	ds_read_b128 v[28:31], v2 offset:9728
	ds_read_b128 v[32:35], v2 offset:9744
	s_waitcnt lgkmcnt(6)
	v_fma_f32 v101, -v4, v80, v101
	v_fma_f32 v101, -v5, v81, v101
	v_fma_f32 v101, -v6, v82, v101
	v_fma_f32 v101, -v7, v83, v101
	v_fma_f32 v101, -v8, v84, v101
	v_fma_f32 v101, -v9, v85, v101
	v_fma_f32 v101, -v10, v86, v101
	v_fma_f32 v101, -v11, v87, v101
	ds_read_b128 v[4:7], v2 offset:9760
	ds_read_b128 v[8:11], v2 offset:9776
	s_waitcnt lgkmcnt(6)
	v_fma_f32 v101, -v12, v88, v101
	v_fma_f32 v101, -v13, v89, v101
	v_fma_f32 v101, -v14, v90, v101
	v_fma_f32 v101, -v15, v91, v101
	v_fma_f32 v101, -v16, v92, v101
	v_fma_f32 v101, -v17, v93, v101
	v_fma_f32 v101, -v18, v94, v101
	v_fma_f32 v101, -v19, v95, v101
	ds_read_b128 v[12:15], v2 offset:9792
	ds_read_b128 v[16:19], v2 offset:9808
	s_waitcnt lgkmcnt(6)
	v_fma_f32 v101, -v20, v96, v101
	v_fma_f32 v101, -v21, v97, v101
	v_fma_f32 v101, -v22, v98, v101
	v_fma_f32 v101, -v23, v99, v101
	v_fma_f32 v101, -v24, v100, v101
	ds_read_b128 v[20:23], v2 offset:9824
	ds_read_b128 v[24:27], v2 offset:9840
	s_waitcnt lgkmcnt(6)
	s_lshl_b64 s[42:43], 1, 38
	v_cndmask_b32_e64 v102, 0, 1.0, s[42:43]
	v_fma_f32 v102, -v28, v64, v102
	v_fma_f32 v102, -v29, v65, v102
	v_fma_f32 v102, -v30, v66, v102
	v_fma_f32 v102, -v31, v67, v102
	v_fma_f32 v102, -v32, v68, v102
	v_fma_f32 v102, -v33, v69, v102
	v_fma_f32 v102, -v34, v70, v102
	v_fma_f32 v102, -v35, v71, v102
	ds_read_b128 v[28:31], v2 offset:9856
	ds_read_b128 v[32:35], v2 offset:9872
	s_waitcnt lgkmcnt(6)
	v_fma_f32 v102, -v4, v72, v102
	v_fma_f32 v102, -v5, v73, v102
	v_fma_f32 v102, -v6, v74, v102
	v_fma_f32 v102, -v7, v75, v102
	v_fma_f32 v102, -v8, v76, v102
	v_fma_f32 v102, -v9, v77, v102
	v_fma_f32 v102, -v10, v78, v102
	v_fma_f32 v102, -v11, v79, v102
	ds_read_b128 v[4:7], v2 offset:9984
	ds_read_b128 v[8:11], v2 offset:10000
	s_waitcnt lgkmcnt(6)
	v_fma_f32 v102, -v12, v80, v102
	v_fma_f32 v102, -v13, v81, v102
	v_fma_f32 v102, -v14, v82, v102
	v_fma_f32 v102, -v15, v83, v102
	v_fma_f32 v102, -v16, v84, v102
	v_fma_f32 v102, -v17, v85, v102
	v_fma_f32 v102, -v18, v86, v102
	v_fma_f32 v102, -v19, v87, v102
	ds_read_b128 v[12:15], v2 offset:10016
	ds_read_b128 v[16:19], v2 offset:10032
	s_waitcnt lgkmcnt(6)
; #define LAS __attribute__((address_space(3)))
; __device__ __forceinline__ void dk_phase(const Frame& F, const bf16* QKrm, const unsigned char* KT, const unsigned char* VT, const float* BG, unsigned char* ITEMS) {
;     ...
;         float t[64];
; #pragma unroll
;         for (int r = 0; r < 64; ++r) {
;             float acc = (lane == r) ? 1.f : 0.f;
; #pragma unroll
;             for (int s4 = 0; s4 < (r + 3) / 4; ++s4) { const f32x4 a = *(const LAS f32x4*)(Amat + r * 64 + 4 * s4);
;                 if (4 * s4 + 0 < r) acc -= a.x * t[4 * s4 + 0]; if (4 * s4 + 1 < r) acc -= a.y * t[4 * s4 + 1];
;                 if (4 * s4 + 2 < r) acc -= a.z * t[4 * s4 + 2]; if (4 * s4 + 3 < r) acc -= a.w * t[4 * s4 + 3]; }
;             t[r] = acc;
;         }
	v_fma_f32 v102, -v20, v88, v102
	v_fma_f32 v102, -v21, v89, v102
	v_fma_f32 v102, -v22, v90, v102
	v_fma_f32 v102, -v23, v91, v102
	v_fma_f32 v102, -v24, v92, v102
	v_fma_f32 v102, -v25, v93, v102
	v_fma_f32 v102, -v26, v94, v102
	v_fma_f32 v102, -v27, v95, v102
	ds_read_b128 v[20:23], v2 offset:10048
	ds_read_b128 v[24:27], v2 offset:10064
	s_waitcnt lgkmcnt(6)
	v_fma_f32 v102, -v28, v96, v102
	v_fma_f32 v102, -v29, v97, v102
	v_fma_f32 v102, -v30, v98, v102
	v_fma_f32 v102, -v31, v99, v102
	v_fma_f32 v102, -v32, v100, v102
	v_fma_f32 v102, -v33, v101, v102
	ds_read_b128 v[28:31], v2 offset:10080
	ds_read_b128 v[32:35], v2 offset:10096
	s_waitcnt lgkmcnt(6)
	s_lshl_b64 s[42:43], 1, 39
	v_cndmask_b32_e64 v103, 0, 1.0, s[42:43]
	v_fma_f32 v103, -v4, v64, v103
	v_fma_f32 v103, -v5, v65, v103
	v_fma_f32 v103, -v6, v66, v103
	v_fma_f32 v103, -v7, v67, v103
	v_fma_f32 v103, -v8, v68, v103
	v_fma_f32 v103, -v9, v69, v103
	v_fma_f32 v103, -v10, v70, v103
	v_fma_f32 v103, -v11, v71, v103
	ds_read_b128 v[4:7], v2 offset:10112
	ds_read_b128 v[8:11], v2 offset:10128
	s_waitcnt lgkmcnt(6)
	v_fma_f32 v103, -v12, v72, v103
	v_fma_f32 v103, -v13, v73, v103
	v_fma_f32 v103, -v14, v74, v103
	v_fma_f32 v103, -v15, v75, v103
	v_fma_f32 v103, -v16, v76, v103
	v_fma_f32 v103, -v17, v77, v103
	v_fma_f32 v103, -v18, v78, v103
	v_fma_f32 v103, -v19, v79, v103
	ds_read_b128 v[12:15], v2 offset:10240
	ds_read_b128 v[16:19], v2 offset:10256
	s_waitcnt lgkmcnt(6)
	v_fma_f32 v103, -v20, v80, v103
	v_fma_f32 v103, -v21, v81, v103
	v_fma_f32 v103, -v22, v82, v103
	v_fma_f32 v103, -v23, v83, v103
	v_fma_f32 v103, -v24, v84, v103
	v_fma_f32 v103, -v25, v85, v103
	v_fma_f32 v103, -v26, v86, v103
	v_fma_f32 v103, -v27, v87, v103
	ds_read_b128 v[20:23], v2 offset:10272
	ds_read_b128 v[24:27], v2 offset:10288
	s_waitcnt lgkmcnt(6)
	v_fma_f32 v103, -v28, v88, v103
	v_fma_f32 v103, -v29, v89, v103
	v_fma_f32 v103, -v30, v90, v103
	v_fma_f32 v103, -v31, v91, v103
	v_fma_f32 v103, -v32, v92, v103
	v_fma_f32 v103, -v33, v93, v103
	v_fma_f32 v103, -v34, v94, v103
	v_fma_f32 v103, -v35, v95, v103
	ds_read_b128 v[28:31], v2 offset:10304
	ds_read_b128 v[32:35], v2 offset:10320
	s_waitcnt lgkmcnt(6)
	v_fma_f32 v103, -v4, v96, v103
	v_fma_f32 v103, -v5, v97, v103
	v_fma_f32 v103, -v6, v98, v103
	v_fma_f32 v103, -v7, v99, v103
	v_fma_f32 v103, -v8, v100, v103
	v_fma_f32 v103, -v9, v101, v103
	v_fma_f32 v103, -v10, v102, v103
	ds_read_b128 v[4:7], v2 offset:10336
	ds_read_b128 v[8:11], v2 offset:10352
	s_waitcnt lgkmcnt(6)
	s_lshl_b64 s[42:43], 1, 40
	v_cndmask_b32_e64 v104, 0, 1.0, s[42:43]
	v_fma_f32 v104, -v12, v64, v104
	v_fma_f32 v104, -v13, v65, v104
	v_fma_f32 v104, -v14, v66, v104
	v_fma_f32 v104, -v15, v67, v104
	v_fma_f32 v104, -v16, v68, v104
	v_fma_f32 v104, -v17, v69, v104
	v_fma_f32 v104, -v18, v70, v104
	v_fma_f32 v104, -v19, v71, v104
	ds_read_b128 v[12:15], v2 offset:10368
	ds_read_b128 v[16:19], v2 offset:10384
	s_waitcnt lgkmcnt(6)
	v_fma_f32 v104, -v20, v72, v104
	v_fma_f32 v104, -v21, v73, v104
	v_fma_f32 v104, -v22, v74, v104
	v_fma_f32 v104, -v23, v75, v104
	v_fma_f32 v104, -v24, v76, v104
	v_fma_f32 v104, -v25, v77, v104
	v_fma_f32 v104, -v26, v78, v104
	v_fma_f32 v104, -v27, v79, v104
	ds_read_b128 v[20:23], v2 offset:10496
	ds_read_b128 v[24:27], v2 offset:10512
	s_waitcnt lgkmcnt(6)
	v_fma_f32 v104, -v28, v80, v104
	v_fma_f32 v104, -v29, v81, v104
	v_fma_f32 v104, -v30, v82, v104
	v_fma_f32 v104, -v31, v83, v104
	v_fma_f32 v104, -v32, v84, v104
	v_fma_f32 v104, -v33, v85, v104
	v_fma_f32 v104, -v34, v86, v104
	v_fma_f32 v104, -v35, v87, v104
	ds_read_b128 v[28:31], v2 offset:10528
	ds_read_b128 v[32:35], v2 offset:10544
	s_waitcnt lgkmcnt(6)
	v_fma_f32 v104, -v4, v88, v104
	v_fma_f32 v104, -v5, v89, v104
	v_fma_f32 v104, -v6, v90, v104
	v_fma_f32 v104, -v7, v91, v104
	v_fma_f32 v104, -v8, v92, v104
	v_fma_f32 v104, -v9, v93, v104
	v_fma_f32 v104, -v10, v94, v104
	v_fma_f32 v104, -v11, v95, v104
	ds_read_b128 v[4:7], v2 offset:10560
	ds_read_b128 v[8:11], v2 offset:10576
	s_waitcnt lgkmcnt(6)
	v_fma_f32 v104, -v12, v96, v104
	v_fma_f32 v104, -v13, v97, v104
	v_fma_f32 v104, -v14, v98, v104
	v_fma_f32 v104, -v15, v99, v104
	v_fma_f32 v104, -v16, v100, v104
	v_fma_f32 v104, -v17, v101, v104
	v_fma_f32 v104, -v18, v102, v104
	v_fma_f32 v104, -v19, v103, v104
	ds_read_b128 v[12:15], v2 offset:10592
	ds_read_b128 v[16:19], v2 offset:10608
	s_waitcnt lgkmcnt(6)
	s_lshl_b64 s[42:43], 1, 41
	v_cndmask_b32_e64 v105, 0, 1.0, s[42:43]
	v_fma_f32 v105, -v20, v64, v105
	v_fma_f32 v105, -v21, v65, v105
	v_fma_f32 v105, -v22, v66, v105
	v_fma_f32 v105, -v23, v67, v105
	v_fma_f32 v105, -v24, v68, v105
	v_fma_f32 v105, -v25, v69, v105
	v_fma_f32 v105, -v26, v70, v105
	v_fma_f32 v105, -v27, v71, v105
	ds_read_b128 v[20:23], v2 offset:10624
	ds_read_b128 v[24:27], v2 offset:10640
	s_waitcnt lgkmcnt(6)
	v_fma_f32 v105, -v28, v72, v105
	v_fma_f32 v105, -v29, v73, v105
	v_fma_f32 v105, -v30, v74, v105
	v_fma_f32 v105, -v31, v75, v105
	v_fma_f32 v105, -v32, v76, v105
	v_fma_f32 v105, -v33, v77, v105
	v_fma_f32 v105, -v34, v78, v105
	v_fma_f32 v105, -v35, v79, v105
	ds_read_b128 v[28:31], v2 offset:10656
	ds_read_b128 v[32:35], v2 offset:10752
	s_waitcnt lgkmcnt(6)
	v_fma_f32 v105, -v4, v80, v105
	v_fma_f32 v105, -v5, v81, v105
	v_fma_f32 v105, -v6, v82, v105
	v_fma_f32 v105, -v7, v83, v105
	v_fma_f32 v105, -v8, v84, v105
	v_fma_f32 v105, -v9, v85, v105
	v_fma_f32 v105, -v10, v86, v105
	v_fma_f32 v105, -v11, v87, v105
	ds_read_b128 v[4:7], v2 offset:10768
	ds_read_b128 v[8:11], v2 offset:10784
	s_waitcnt lgkmcnt(6)
; #define LAS __attribute__((address_space(3)))
; __device__ __forceinline__ void dk_phase(const Frame& F, const bf16* QKrm, const unsigned char* KT, const unsigned char* VT, const float* BG, unsigned char* ITEMS) {
;     ...
;         float t[64];
; #pragma unroll
;         for (int r = 0; r < 64; ++r) {
;             float acc = (lane == r) ? 1.f : 0.f;
; #pragma unroll
;             for (int s4 = 0; s4 < (r + 3) / 4; ++s4) { const f32x4 a = *(const LAS f32x4*)(Amat + r * 64 + 4 * s4);
;                 if (4 * s4 + 0 < r) acc -= a.x * t[4 * s4 + 0]; if (4 * s4 + 1 < r) acc -= a.y * t[4 * s4 + 1];
;                 if (4 * s4 + 2 < r) acc -= a.z * t[4 * s4 + 2]; if (4 * s4 + 3 < r) acc -= a.w * t[4 * s4 + 3]; }
;             t[r] = acc;
;         }
	v_fma_f32 v105, -v12, v88, v105
	v_fma_f32 v105, -v13, v89, v105
	v_fma_f32 v105, -v14, v90, v105
	v_fma_f32 v105, -v15, v91, v105
	v_fma_f32 v105, -v16, v92, v105
	v_fma_f32 v105, -v17, v93, v105
	v_fma_f32 v105, -v18, v94, v105
	v_fma_f32 v105, -v19, v95, v105
	ds_read_b128 v[12:15], v2 offset:10800
	ds_read_b128 v[16:19], v2 offset:10816
	s_waitcnt lgkmcnt(6)
	v_fma_f32 v105, -v20, v96, v105
	v_fma_f32 v105, -v21, v97, v105
	v_fma_f32 v105, -v22, v98, v105
	v_fma_f32 v105, -v23, v99, v105
	v_fma_f32 v105, -v24, v100, v105
	v_fma_f32 v105, -v25, v101, v105
	v_fma_f32 v105, -v26, v102, v105
	v_fma_f32 v105, -v27, v103, v105
	ds_read_b128 v[20:23], v2 offset:10832
	ds_read_b128 v[24:27], v2 offset:10848
	s_waitcnt lgkmcnt(6)
	v_fma_f32 v105, -v28, v104, v105
	s_lshl_b64 s[42:43], 1, 42
	v_cndmask_b32_e64 v106, 0, 1.0, s[42:43]
	v_fma_f32 v106, -v32, v64, v106
	v_fma_f32 v106, -v33, v65, v106
	v_fma_f32 v106, -v34, v66, v106
	v_fma_f32 v106, -v35, v67, v106
	ds_read_b128 v[28:31], v2 offset:10864
	ds_read_b128 v[32:35], v2 offset:10880
	s_waitcnt lgkmcnt(6)
	v_fma_f32 v106, -v4, v68, v106
	v_fma_f32 v106, -v5, v69, v106
	v_fma_f32 v106, -v6, v70, v106
	v_fma_f32 v106, -v7, v71, v106
	v_fma_f32 v106, -v8, v72, v106
	v_fma_f32 v106, -v9, v73, v106
	v_fma_f32 v106, -v10, v74, v106
	v_fma_f32 v106, -v11, v75, v106
	ds_read_b128 v[4:7], v2 offset:10896
	ds_read_b128 v[8:11], v2 offset:10912
	s_waitcnt lgkmcnt(6)
	v_fma_f32 v106, -v12, v76, v106
	v_fma_f32 v106, -v13, v77, v106
	v_fma_f32 v106, -v14, v78, v106
	v_fma_f32 v106, -v15, v79, v106
	v_fma_f32 v106, -v16, v80, v106
	v_fma_f32 v106, -v17, v81, v106
	v_fma_f32 v106, -v18, v82, v106
	v_fma_f32 v106, -v19, v83, v106
	ds_read_b128 v[12:15], v2 offset:11008
	ds_read_b128 v[16:19], v2 offset:11024
	s_waitcnt lgkmcnt(6)
	v_fma_f32 v106, -v20, v84, v106
	v_fma_f32 v106, -v21, v85, v106
	v_fma_f32 v106, -v22, v86, v106
	v_fma_f32 v106, -v23, v87, v106
	v_fma_f32 v106, -v24, v88, v106
	v_fma_f32 v106, -v25, v89, v106
	v_fma_f32 v106, -v26, v90, v106
	v_fma_f32 v106, -v27, v91, v106
	ds_read_b128 v[20:23], v2 offset:11040
	ds_read_b128 v[24:27], v2 offset:11056
	s_waitcnt lgkmcnt(6)
	v_fma_f32 v106, -v28, v92, v106
	v_fma_f32 v106, -v29, v93, v106
	v_fma_f32 v106, -v30, v94, v106
	v_fma_f32 v106, -v31, v95, v106
	v_fma_f32 v106, -v32, v96, v106
	v_fma_f32 v106, -v33, v97, v106
	v_fma_f32 v106, -v34, v98, v106
	v_fma_f32 v106, -v35, v99, v106
	ds_read_b128 v[28:31], v2 offset:11072
	ds_read_b128 v[32:35], v2 offset:11088
	s_waitcnt lgkmcnt(6)
	v_fma_f32 v106, -v4, v100, v106
	v_fma_f32 v106, -v5, v101, v106
	v_fma_f32 v106, -v6, v102, v106
	v_fma_f32 v106, -v7, v103, v106
	v_fma_f32 v106, -v8, v104, v106
	v_fma_f32 v106, -v9, v105, v106
	ds_read_b128 v[4:7], v2 offset:11104
	ds_read_b128 v[8:11], v2 offset:11120
	s_waitcnt lgkmcnt(6)
	s_lshl_b64 s[42:43], 1, 43
	v_cndmask_b32_e64 v107, 0, 1.0, s[42:43]
	v_fma_f32 v107, -v12, v64, v107
	v_fma_f32 v107, -v13, v65, v107
	v_fma_f32 v107, -v14, v66, v107
	v_fma_f32 v107, -v15, v67, v107
	v_fma_f32 v107, -v16, v68, v107
	v_fma_f32 v107, -v17, v69, v107
	v_fma_f32 v107, -v18, v70, v107
	v_fma_f32 v107, -v19, v71, v107
	ds_read_b128 v[12:15], v2 offset:11136
	ds_read_b128 v[16:19], v2 offset:11152
	s_waitcnt lgkmcnt(6)
	v_fma_f32 v107, -v20, v72, v107
	v_fma_f32 v107, -v21, v73, v107
	v_fma_f32 v107, -v22, v74, v107
	v_fma_f32 v107, -v23, v75, v107
	v_fma_f32 v107, -v24, v76, v107
	v_fma_f32 v107, -v25, v77, v107
	v_fma_f32 v107, -v26, v78, v107
	v_fma_f32 v107, -v27, v79, v107
	ds_read_b128 v[20:23], v2 offset:11168
	ds_read_b128 v[24:27], v2 offset:11264
	s_waitcnt lgkmcnt(6)
	v_fma_f32 v107, -v28, v80, v107
	v_fma_f32 v107, -v29, v81, v107
	v_fma_f32 v107, -v30, v82, v107
	v_fma_f32 v107, -v31, v83, v107
	v_fma_f32 v107, -v32, v84, v107
	v_fma_f32 v107, -v33, v85, v107
	v_fma_f32 v107, -v34, v86, v107
	v_fma_f32 v107, -v35, v87, v107
	ds_read_b128 v[28:31], v2 offset:11280
	ds_read_b128 v[32:35], v2 offset:11296
	s_waitcnt lgkmcnt(6)
	v_fma_f32 v107, -v4, v88, v107
	v_fma_f32 v107, -v5, v89, v107
	v_fma_f32 v107, -v6, v90, v107
	v_fma_f32 v107, -v7, v91, v107
	v_fma_f32 v107, -v8, v92, v107
	v_fma_f32 v107, -v9, v93, v107
	v_fma_f32 v107, -v10, v94, v107
	v_fma_f32 v107, -v11, v95, v107
	ds_read_b128 v[4:7], v2 offset:11312
	ds_read_b128 v[8:11], v2 offset:11328
	s_waitcnt lgkmcnt(6)
	v_fma_f32 v107, -v12, v96, v107
	v_fma_f32 v107, -v13, v97, v107
	v_fma_f32 v107, -v14, v98, v107
	v_fma_f32 v107, -v15, v99, v107
	v_fma_f32 v107, -v16, v100, v107
	v_fma_f32 v107, -v17, v101, v107
	v_fma_f32 v107, -v18, v102, v107
	v_fma_f32 v107, -v19, v103, v107
	ds_read_b128 v[12:15], v2 offset:11344
	ds_read_b128 v[16:19], v2 offset:11360
	s_waitcnt lgkmcnt(6)
	v_fma_f32 v107, -v20, v104, v107
	v_fma_f32 v107, -v21, v105, v107
	v_fma_f32 v107, -v22, v106, v107
	s_lshl_b64 s[42:43], 1, 44
	v_cndmask_b32_e64 v108, 0, 1.0, s[42:43]
	v_fma_f32 v108, -v24, v64, v108
	v_fma_f32 v108, -v25, v65, v108
	v_fma_f32 v108, -v26, v66, v108
	v_fma_f32 v108, -v27, v67, v108
	ds_read_b128 v[20:23], v2 offset:11376
	ds_read_b128 v[24:27], v2 offset:11392
	s_waitcnt lgkmcnt(6)
	v_fma_f32 v108, -v28, v68, v108
	v_fma_f32 v108, -v29, v69, v108
	v_fma_f32 v108, -v30, v70, v108
	v_fma_f32 v108, -v31, v71, v108
	v_fma_f32 v108, -v32, v72, v108
	v_fma_f32 v108, -v33, v73, v108
	v_fma_f32 v108, -v34, v74, v108
	v_fma_f32 v108, -v35, v75, v108
	ds_read_b128 v[28:31], v2 offset:11408
	ds_read_b128 v[32:35], v2 offset:11424
	s_waitcnt lgkmcnt(6)
; #define LAS __attribute__((address_space(3)))
; __device__ __forceinline__ void dk_phase(const Frame& F, const bf16* QKrm, const unsigned char* KT, const unsigned char* VT, const float* BG, unsigned char* ITEMS) {
;     ...
;         float t[64];
; #pragma unroll
;         for (int r = 0; r < 64; ++r) {
;             float acc = (lane == r) ? 1.f : 0.f;
; #pragma unroll
;             for (int s4 = 0; s4 < (r + 3) / 4; ++s4) { const f32x4 a = *(const LAS f32x4*)(Amat + r * 64 + 4 * s4);
;                 if (4 * s4 + 0 < r) acc -= a.x * t[4 * s4 + 0]; if (4 * s4 + 1 < r) acc -= a.y * t[4 * s4 + 1];
;                 if (4 * s4 + 2 < r) acc -= a.z * t[4 * s4 + 2]; if (4 * s4 + 3 < r) acc -= a.w * t[4 * s4 + 3]; }
;             t[r] = acc;
;         }
	v_fma_f32 v108, -v4, v76, v108
	v_fma_f32 v108, -v5, v77, v108
	v_fma_f32 v108, -v6, v78, v108
	v_fma_f32 v108, -v7, v79, v108
	v_fma_f32 v108, -v8, v80, v108
	v_fma_f32 v108, -v9, v81, v108
	v_fma_f32 v108, -v10, v82, v108
	v_fma_f32 v108, -v11, v83, v108
	ds_read_b128 v[4:7], v2 offset:11520
	ds_read_b128 v[8:11], v2 offset:11536
	s_waitcnt lgkmcnt(6)
	v_fma_f32 v108, -v12, v84, v108
	v_fma_f32 v108, -v13, v85, v108
	v_fma_f32 v108, -v14, v86, v108
	v_fma_f32 v108, -v15, v87, v108
	v_fma_f32 v108, -v16, v88, v108
	v_fma_f32 v108, -v17, v89, v108
	v_fma_f32 v108, -v18, v90, v108
	v_fma_f32 v108, -v19, v91, v108
	ds_read_b128 v[12:15], v2 offset:11552
	ds_read_b128 v[16:19], v2 offset:11568
	s_waitcnt lgkmcnt(6)
	v_fma_f32 v108, -v20, v92, v108
	v_fma_f32 v108, -v21, v93, v108
	v_fma_f32 v108, -v22, v94, v108
	v_fma_f32 v108, -v23, v95, v108
	v_fma_f32 v108, -v24, v96, v108
	v_fma_f32 v108, -v25, v97, v108
	v_fma_f32 v108, -v26, v98, v108
	v_fma_f32 v108, -v27, v99, v108
	ds_read_b128 v[20:23], v2 offset:11584
	ds_read_b128 v[24:27], v2 offset:11600
	s_waitcnt lgkmcnt(6)
	v_fma_f32 v108, -v28, v100, v108
	v_fma_f32 v108, -v29, v101, v108
	v_fma_f32 v108, -v30, v102, v108
	v_fma_f32 v108, -v31, v103, v108
	v_fma_f32 v108, -v32, v104, v108
	v_fma_f32 v108, -v33, v105, v108
	v_fma_f32 v108, -v34, v106, v108
	v_fma_f32 v108, -v35, v107, v108
	ds_read_b128 v[28:31], v2 offset:11616
	ds_read_b128 v[32:35], v2 offset:11632
	s_waitcnt lgkmcnt(6)
	s_lshl_b64 s[42:43], 1, 45
	v_cndmask_b32_e64 v109, 0, 1.0, s[42:43]
	v_fma_f32 v109, -v4, v64, v109
	v_fma_f32 v109, -v5, v65, v109
	v_fma_f32 v109, -v6, v66, v109
	v_fma_f32 v109, -v7, v67, v109
	v_fma_f32 v109, -v8, v68, v109
	v_fma_f32 v109, -v9, v69, v109
	v_fma_f32 v109, -v10, v70, v109
	v_fma_f32 v109, -v11, v71, v109
	ds_read_b128 v[4:7], v2 offset:11648
	ds_read_b128 v[8:11], v2 offset:11664
	s_waitcnt lgkmcnt(6)
	v_fma_f32 v109, -v12, v72, v109
	v_fma_f32 v109, -v13, v73, v109
	v_fma_f32 v109, -v14, v74, v109
	v_fma_f32 v109, -v15, v75, v109
	v_fma_f32 v109, -v16, v76, v109
	v_fma_f32 v109, -v17, v77, v109
	v_fma_f32 v109, -v18, v78, v109
	v_fma_f32 v109, -v19, v79, v109
	ds_read_b128 v[12:15], v2 offset:11680
	ds_read_b128 v[16:19], v2 offset:11696
	s_waitcnt lgkmcnt(6)
	v_fma_f32 v109, -v20, v80, v109
	v_fma_f32 v109, -v21, v81, v109
	v_fma_f32 v109, -v22, v82, v109
	v_fma_f32 v109, -v23, v83, v109
	v_fma_f32 v109, -v24, v84, v109
	v_fma_f32 v109, -v25, v85, v109
	v_fma_f32 v109, -v26, v86, v109
	v_fma_f32 v109, -v27, v87, v109
	ds_read_b128 v[20:23], v2 offset:11776
	ds_read_b128 v[24:27], v2 offset:11792
	s_waitcnt lgkmcnt(6)
	v_fma_f32 v109, -v28, v88, v109
	v_fma_f32 v109, -v29, v89, v109
	v_fma_f32 v109, -v30, v90, v109
	v_fma_f32 v109, -v31, v91, v109
	v_fma_f32 v109, -v32, v92, v109
	v_fma_f32 v109, -v33, v93, v109
	v_fma_f32 v109, -v34, v94, v109
	v_fma_f32 v109, -v35, v95, v109
	ds_read_b128 v[28:31], v2 offset:11808
	ds_read_b128 v[32:35], v2 offset:11824
	s_waitcnt lgkmcnt(6)
	v_fma_f32 v109, -v4, v96, v109
	v_fma_f32 v109, -v5, v97, v109
	v_fma_f32 v109, -v6, v98, v109
	v_fma_f32 v109, -v7, v99, v109
	v_fma_f32 v109, -v8, v100, v109
	v_fma_f32 v109, -v9, v101, v109
	v_fma_f32 v109, -v10, v102, v109
	v_fma_f32 v109, -v11, v103, v109
	ds_read_b128 v[4:7], v2 offset:11840
	ds_read_b128 v[8:11], v2 offset:11856
	s_waitcnt lgkmcnt(6)
	v_fma_f32 v109, -v12, v104, v109
	v_fma_f32 v109, -v13, v105, v109
	v_fma_f32 v109, -v14, v106, v109
	v_fma_f32 v109, -v15, v107, v109
	v_fma_f32 v109, -v16, v108, v109
	ds_read_b128 v[12:15], v2 offset:11872
	ds_read_b128 v[16:19], v2 offset:11888
	s_waitcnt lgkmcnt(6)
	s_lshl_b64 s[42:43], 1, 46
	v_cndmask_b32_e64 v110, 0, 1.0, s[42:43]
	v_fma_f32 v110, -v20, v64, v110
	v_fma_f32 v110, -v21, v65, v110
	v_fma_f32 v110, -v22, v66, v110
	v_fma_f32 v110, -v23, v67, v110
	v_fma_f32 v110, -v24, v68, v110
	v_fma_f32 v110, -v25, v69, v110
	v_fma_f32 v110, -v26, v70, v110
	v_fma_f32 v110, -v27, v71, v110
	ds_read_b128 v[20:23], v2 offset:11904
	ds_read_b128 v[24:27], v2 offset:11920
	s_waitcnt lgkmcnt(6)
	v_fma_f32 v110, -v28, v72, v110
	v_fma_f32 v110, -v29, v73, v110
	v_fma_f32 v110, -v30, v74, v110
	v_fma_f32 v110, -v31, v75, v110
	v_fma_f32 v110, -v32, v76, v110
	v_fma_f32 v110, -v33, v77, v110
	v_fma_f32 v110, -v34, v78, v110
	v_fma_f32 v110, -v35, v79, v110
	ds_read_b128 v[28:31], v2 offset:11936
	ds_read_b128 v[32:35], v2 offset:11952
	s_waitcnt lgkmcnt(6)
	v_fma_f32 v110, -v4, v80, v110
	v_fma_f32 v110, -v5, v81, v110
	v_fma_f32 v110, -v6, v82, v110
	v_fma_f32 v110, -v7, v83, v110
	v_fma_f32 v110, -v8, v84, v110
	v_fma_f32 v110, -v9, v85, v110
	v_fma_f32 v110, -v10, v86, v110
	v_fma_f32 v110, -v11, v87, v110
	ds_read_b128 v[4:7], v2 offset:12032
	ds_read_b128 v[8:11], v2 offset:12048
	s_waitcnt lgkmcnt(6)
	v_fma_f32 v110, -v12, v88, v110
	v_fma_f32 v110, -v13, v89, v110
	v_fma_f32 v110, -v14, v90, v110
	v_fma_f32 v110, -v15, v91, v110
	v_fma_f32 v110, -v16, v92, v110
	v_fma_f32 v110, -v17, v93, v110
	v_fma_f32 v110, -v18, v94, v110
	v_fma_f32 v110, -v19, v95, v110
	ds_read_b128 v[12:15], v2 offset:12064
	ds_read_b128 v[16:19], v2 offset:12080
	s_waitcnt lgkmcnt(6)
	v_fma_f32 v110, -v20, v96, v110
	v_fma_f32 v110, -v21, v97, v110
	v_fma_f32 v110, -v22, v98, v110
	v_fma_f32 v110, -v23, v99, v110
	v_fma_f32 v110, -v24, v100, v110
	v_fma_f32 v110, -v25, v101, v110
	v_fma_f32 v110, -v26, v102, v110
	v_fma_f32 v110, -v27, v103, v110
	ds_read_b128 v[20:23], v2 offset:12096
	ds_read_b128 v[24:27], v2 offset:12112
	s_waitcnt lgkmcnt(6)
; #define LAS __attribute__((address_space(3)))
; __device__ __forceinline__ void dk_phase(const Frame& F, const bf16* QKrm, const unsigned char* KT, const unsigned char* VT, const float* BG, unsigned char* ITEMS) {
;     ...
;         float t[64];
; #pragma unroll
;         for (int r = 0; r < 64; ++r) {
;             float acc = (lane == r) ? 1.f : 0.f;
; #pragma unroll
;             for (int s4 = 0; s4 < (r + 3) / 4; ++s4) { const f32x4 a = *(const LAS f32x4*)(Amat + r * 64 + 4 * s4);
;                 if (4 * s4 + 0 < r) acc -= a.x * t[4 * s4 + 0]; if (4 * s4 + 1 < r) acc -= a.y * t[4 * s4 + 1];
;                 if (4 * s4 + 2 < r) acc -= a.z * t[4 * s4 + 2]; if (4 * s4 + 3 < r) acc -= a.w * t[4 * s4 + 3]; }
;             t[r] = acc;
;         }
	v_fma_f32 v110, -v28, v104, v110
	v_fma_f32 v110, -v29, v105, v110
	v_fma_f32 v110, -v30, v106, v110
	v_fma_f32 v110, -v31, v107, v110
	v_fma_f32 v110, -v32, v108, v110
	v_fma_f32 v110, -v33, v109, v110
	ds_read_b128 v[28:31], v2 offset:12128
	ds_read_b128 v[32:35], v2 offset:12144
	s_waitcnt lgkmcnt(6)
	s_lshl_b64 s[42:43], 1, 47
	v_cndmask_b32_e64 v111, 0, 1.0, s[42:43]
	v_fma_f32 v111, -v4, v64, v111
	v_fma_f32 v111, -v5, v65, v111
	v_fma_f32 v111, -v6, v66, v111
	v_fma_f32 v111, -v7, v67, v111
	v_fma_f32 v111, -v8, v68, v111
	v_fma_f32 v111, -v9, v69, v111
	v_fma_f32 v111, -v10, v70, v111
	v_fma_f32 v111, -v11, v71, v111
	ds_read_b128 v[4:7], v2 offset:12160
	ds_read_b128 v[8:11], v2 offset:12176
	s_waitcnt lgkmcnt(6)
	v_fma_f32 v111, -v12, v72, v111
	v_fma_f32 v111, -v13, v73, v111
	v_fma_f32 v111, -v14, v74, v111
	v_fma_f32 v111, -v15, v75, v111
	v_fma_f32 v111, -v16, v76, v111
	v_fma_f32 v111, -v17, v77, v111
	v_fma_f32 v111, -v18, v78, v111
	v_fma_f32 v111, -v19, v79, v111
	ds_read_b128 v[12:15], v2 offset:12192
	ds_read_b128 v[16:19], v2 offset:12208
	s_waitcnt lgkmcnt(6)
	v_fma_f32 v111, -v20, v80, v111
	v_fma_f32 v111, -v21, v81, v111
	v_fma_f32 v111, -v22, v82, v111
	v_fma_f32 v111, -v23, v83, v111
	v_fma_f32 v111, -v24, v84, v111
	v_fma_f32 v111, -v25, v85, v111
	v_fma_f32 v111, -v26, v86, v111
	v_fma_f32 v111, -v27, v87, v111
	ds_read_b128 v[20:23], v2 offset:12288
	ds_read_b128 v[24:27], v2 offset:12304
	s_waitcnt lgkmcnt(6)
	v_fma_f32 v111, -v28, v88, v111
	v_fma_f32 v111, -v29, v89, v111
	v_fma_f32 v111, -v30, v90, v111
	v_fma_f32 v111, -v31, v91, v111
	v_fma_f32 v111, -v32, v92, v111
	v_fma_f32 v111, -v33, v93, v111
	v_fma_f32 v111, -v34, v94, v111
	v_fma_f32 v111, -v35, v95, v111
	ds_read_b128 v[28:31], v2 offset:12320
	ds_read_b128 v[32:35], v2 offset:12336
	s_waitcnt lgkmcnt(6)
	v_fma_f32 v111, -v4, v96, v111
	v_fma_f32 v111, -v5, v97, v111
	v_fma_f32 v111, -v6, v98, v111
	v_fma_f32 v111, -v7, v99, v111
	v_fma_f32 v111, -v8, v100, v111
	v_fma_f32 v111, -v9, v101, v111
	v_fma_f32 v111, -v10, v102, v111
	v_fma_f32 v111, -v11, v103, v111
	ds_read_b128 v[4:7], v2 offset:12352
	ds_read_b128 v[8:11], v2 offset:12368
	s_waitcnt lgkmcnt(6)
	v_fma_f32 v111, -v12, v104, v111
	v_fma_f32 v111, -v13, v105, v111
	v_fma_f32 v111, -v14, v106, v111
	v_fma_f32 v111, -v15, v107, v111
	v_fma_f32 v111, -v16, v108, v111
	v_fma_f32 v111, -v17, v109, v111
	v_fma_f32 v111, -v18, v110, v111
	ds_read_b128 v[12:15], v2 offset:12384
	ds_read_b128 v[16:19], v2 offset:12400
	s_waitcnt lgkmcnt(6)
	s_lshl_b64 s[42:43], 1, 48
	v_cndmask_b32_e64 v112, 0, 1.0, s[42:43]
	v_fma_f32 v112, -v20, v64, v112
	v_fma_f32 v112, -v21, v65, v112
	v_fma_f32 v112, -v22, v66, v112
	v_fma_f32 v112, -v23, v67, v112
	v_fma_f32 v112, -v24, v68, v112
	v_fma_f32 v112, -v25, v69, v112
	v_fma_f32 v112, -v26, v70, v112
	v_fma_f32 v112, -v27, v71, v112
	ds_read_b128 v[20:23], v2 offset:12416
	ds_read_b128 v[24:27], v2 offset:12432
	s_waitcnt lgkmcnt(6)
	v_fma_f32 v112, -v28, v72, v112
	v_fma_f32 v112, -v29, v73, v112
	v_fma_f32 v112, -v30, v74, v112
	v_fma_f32 v112, -v31, v75, v112
	v_fma_f32 v112, -v32, v76, v112
	v_fma_f32 v112, -v33, v77, v112
	v_fma_f32 v112, -v34, v78, v112
	v_fma_f32 v112, -v35, v79, v112
	ds_read_b128 v[28:31], v2 offset:12448
	ds_read_b128 v[32:35], v2 offset:12464
	s_waitcnt lgkmcnt(6)
	v_fma_f32 v112, -v4, v80, v112
	v_fma_f32 v112, -v5, v81, v112
	v_fma_f32 v112, -v6, v82, v112
	v_fma_f32 v112, -v7, v83, v112
	v_fma_f32 v112, -v8, v84, v112
	v_fma_f32 v112, -v9, v85, v112
	v_fma_f32 v112, -v10, v86, v112
	v_fma_f32 v112, -v11, v87, v112
	ds_read_b128 v[4:7], v2 offset:12544
	ds_read_b128 v[8:11], v2 offset:12560
	s_waitcnt lgkmcnt(6)
	v_fma_f32 v112, -v12, v88, v112
	v_fma_f32 v112, -v13, v89, v112
	v_fma_f32 v112, -v14, v90, v112
	v_fma_f32 v112, -v15, v91, v112
	v_fma_f32 v112, -v16, v92, v112
	v_fma_f32 v112, -v17, v93, v112
	v_fma_f32 v112, -v18, v94, v112
	v_fma_f32 v112, -v19, v95, v112
	ds_read_b128 v[12:15], v2 offset:12576
	ds_read_b128 v[16:19], v2 offset:12592
	s_waitcnt lgkmcnt(6)
	v_fma_f32 v112, -v20, v96, v112
	v_fma_f32 v112, -v21, v97, v112
	v_fma_f32 v112, -v22, v98, v112
	v_fma_f32 v112, -v23, v99, v112
	v_fma_f32 v112, -v24, v100, v112
	v_fma_f32 v112, -v25, v101, v112
	v_fma_f32 v112, -v26, v102, v112
	v_fma_f32 v112, -v27, v103, v112
	ds_read_b128 v[20:23], v2 offset:12608
	ds_read_b128 v[24:27], v2 offset:12624
	s_waitcnt lgkmcnt(6)
	v_fma_f32 v112, -v28, v104, v112
	v_fma_f32 v112, -v29, v105, v112
	v_fma_f32 v112, -v30, v106, v112
	v_fma_f32 v112, -v31, v107, v112
	v_fma_f32 v112, -v32, v108, v112
	v_fma_f32 v112, -v33, v109, v112
	v_fma_f32 v112, -v34, v110, v112
	v_fma_f32 v112, -v35, v111, v112
	ds_read_b128 v[28:31], v2 offset:12640
	ds_read_b128 v[32:35], v2 offset:12656
	s_waitcnt lgkmcnt(6)
	s_lshl_b64 s[42:43], 1, 49
	v_cndmask_b32_e64 v113, 0, 1.0, s[42:43]
	v_fma_f32 v113, -v4, v64, v113
	v_fma_f32 v113, -v5, v65, v113
	v_fma_f32 v113, -v6, v66, v113
	v_fma_f32 v113, -v7, v67, v113
	v_fma_f32 v113, -v8, v68, v113
	v_fma_f32 v113, -v9, v69, v113
	v_fma_f32 v113, -v10, v70, v113
	v_fma_f32 v113, -v11, v71, v113
	ds_read_b128 v[4:7], v2 offset:12672
	ds_read_b128 v[8:11], v2 offset:12688
	s_waitcnt lgkmcnt(6)
	v_fma_f32 v113, -v12, v72, v113
	v_fma_f32 v113, -v13, v73, v113
	v_fma_f32 v113, -v14, v74, v113
	v_fma_f32 v113, -v15, v75, v113
	v_fma_f32 v113, -v16, v76, v113
	v_fma_f32 v113, -v17, v77, v113
	v_fma_f32 v113, -v18, v78, v113
	v_fma_f32 v113, -v19, v79, v113
	ds_read_b128 v[12:15], v2 offset:12704
	ds_read_b128 v[16:19], v2 offset:12720
	s_waitcnt lgkmcnt(6)
; #define LAS __attribute__((address_space(3)))
; __device__ __forceinline__ void dk_phase(const Frame& F, const bf16* QKrm, const unsigned char* KT, const unsigned char* VT, const float* BG, unsigned char* ITEMS) {
;     ...
;         float t[64];
; #pragma unroll
;         for (int r = 0; r < 64; ++r) {
;             float acc = (lane == r) ? 1.f : 0.f;
; #pragma unroll
;             for (int s4 = 0; s4 < (r + 3) / 4; ++s4) { const f32x4 a = *(const LAS f32x4*)(Amat + r * 64 + 4 * s4);
;                 if (4 * s4 + 0 < r) acc -= a.x * t[4 * s4 + 0]; if (4 * s4 + 1 < r) acc -= a.y * t[4 * s4 + 1];
;                 if (4 * s4 + 2 < r) acc -= a.z * t[4 * s4 + 2]; if (4 * s4 + 3 < r) acc -= a.w * t[4 * s4 + 3]; }
;             t[r] = acc;
;         }
	v_fma_f32 v113, -v20, v80, v113
	v_fma_f32 v113, -v21, v81, v113
	v_fma_f32 v113, -v22, v82, v113
	v_fma_f32 v113, -v23, v83, v113
	v_fma_f32 v113, -v24, v84, v113
	v_fma_f32 v113, -v25, v85, v113
	v_fma_f32 v113, -v26, v86, v113
	v_fma_f32 v113, -v27, v87, v113
	ds_read_b128 v[20:23], v2 offset:12736
	ds_read_b128 v[24:27], v2 offset:12800
	s_waitcnt lgkmcnt(6)
	v_fma_f32 v113, -v28, v88, v113
	v_fma_f32 v113, -v29, v89, v113
	v_fma_f32 v113, -v30, v90, v113
	v_fma_f32 v113, -v31, v91, v113
	v_fma_f32 v113, -v32, v92, v113
	v_fma_f32 v113, -v33, v93, v113
	v_fma_f32 v113, -v34, v94, v113
	v_fma_f32 v113, -v35, v95, v113
	ds_read_b128 v[28:31], v2 offset:12816
	ds_read_b128 v[32:35], v2 offset:12832
	s_waitcnt lgkmcnt(6)
	v_fma_f32 v113, -v4, v96, v113
	v_fma_f32 v113, -v5, v97, v113
	v_fma_f32 v113, -v6, v98, v113
	v_fma_f32 v113, -v7, v99, v113
	v_fma_f32 v113, -v8, v100, v113
	v_fma_f32 v113, -v9, v101, v113
	v_fma_f32 v113, -v10, v102, v113
	v_fma_f32 v113, -v11, v103, v113
	ds_read_b128 v[4:7], v2 offset:12848
	ds_read_b128 v[8:11], v2 offset:12864
	s_waitcnt lgkmcnt(6)
	v_fma_f32 v113, -v12, v104, v113
	v_fma_f32 v113, -v13, v105, v113
	v_fma_f32 v113, -v14, v106, v113
	v_fma_f32 v113, -v15, v107, v113
	v_fma_f32 v113, -v16, v108, v113
	v_fma_f32 v113, -v17, v109, v113
	v_fma_f32 v113, -v18, v110, v113
	v_fma_f32 v113, -v19, v111, v113
	ds_read_b128 v[12:15], v2 offset:12880
	ds_read_b128 v[16:19], v2 offset:12896
	s_waitcnt lgkmcnt(6)
	v_fma_f32 v113, -v20, v112, v113
	s_lshl_b64 s[42:43], 1, 50
	v_cndmask_b32_e64 v114, 0, 1.0, s[42:43]
	v_fma_f32 v114, -v24, v64, v114
	v_fma_f32 v114, -v25, v65, v114
	v_fma_f32 v114, -v26, v66, v114
	v_fma_f32 v114, -v27, v67, v114
	ds_read_b128 v[20:23], v2 offset:12912
	ds_read_b128 v[24:27], v2 offset:12928
	s_waitcnt lgkmcnt(6)
	v_fma_f32 v114, -v28, v68, v114
	v_fma_f32 v114, -v29, v69, v114
	v_fma_f32 v114, -v30, v70, v114
	v_fma_f32 v114, -v31, v71, v114
	v_fma_f32 v114, -v32, v72, v114
	v_fma_f32 v114, -v33, v73, v114
	v_fma_f32 v114, -v34, v74, v114
	v_fma_f32 v114, -v35, v75, v114
	ds_read_b128 v[28:31], v2 offset:12944
	ds_read_b128 v[32:35], v2 offset:12960
	s_waitcnt lgkmcnt(6)
	v_fma_f32 v114, -v4, v76, v114
	v_fma_f32 v114, -v5, v77, v114
	v_fma_f32 v114, -v6, v78, v114
	v_fma_f32 v114, -v7, v79, v114
	v_fma_f32 v114, -v8, v80, v114
	v_fma_f32 v114, -v9, v81, v114
	v_fma_f32 v114, -v10, v82, v114
	v_fma_f32 v114, -v11, v83, v114
	ds_read_b128 v[4:7], v2 offset:12976
	ds_read_b128 v[8:11], v2 offset:12992
	s_waitcnt lgkmcnt(6)
	v_fma_f32 v114, -v12, v84, v114
	v_fma_f32 v114, -v13, v85, v114
	v_fma_f32 v114, -v14, v86, v114
	v_fma_f32 v114, -v15, v87, v114
	v_fma_f32 v114, -v16, v88, v114
	v_fma_f32 v114, -v17, v89, v114
	v_fma_f32 v114, -v18, v90, v114
	v_fma_f32 v114, -v19, v91, v114
	ds_read_b128 v[12:15], v2 offset:13056
	ds_read_b128 v[16:19], v2 offset:13072
	s_waitcnt lgkmcnt(6)
	v_fma_f32 v114, -v20, v92, v114
	v_fma_f32 v114, -v21, v93, v114
	v_fma_f32 v114, -v22, v94, v114
	v_fma_f32 v114, -v23, v95, v114
	v_fma_f32 v114, -v24, v96, v114
	v_fma_f32 v114, -v25, v97, v114
	v_fma_f32 v114, -v26, v98, v114
	v_fma_f32 v114, -v27, v99, v114
	ds_read_b128 v[20:23], v2 offset:13088
	ds_read_b128 v[24:27], v2 offset:13104
	s_waitcnt lgkmcnt(6)
	v_fma_f32 v114, -v28, v100, v114
	v_fma_f32 v114, -v29, v101, v114
	v_fma_f32 v114, -v30, v102, v114
	v_fma_f32 v114, -v31, v103, v114
	v_fma_f32 v114, -v32, v104, v114
	v_fma_f32 v114, -v33, v105, v114
	v_fma_f32 v114, -v34, v106, v114
	v_fma_f32 v114, -v35, v107, v114
	ds_read_b128 v[28:31], v2 offset:13120
	ds_read_b128 v[32:35], v2 offset:13136
	s_waitcnt lgkmcnt(6)
	v_fma_f32 v114, -v4, v108, v114
	v_fma_f32 v114, -v5, v109, v114
	v_fma_f32 v114, -v6, v110, v114
	v_fma_f32 v114, -v7, v111, v114
	v_fma_f32 v114, -v8, v112, v114
	v_fma_f32 v114, -v9, v113, v114
	ds_read_b128 v[4:7], v2 offset:13152
	ds_read_b128 v[8:11], v2 offset:13168
	s_waitcnt lgkmcnt(6)
	s_lshl_b64 s[42:43], 1, 51
	v_cndmask_b32_e64 v115, 0, 1.0, s[42:43]
	v_fma_f32 v115, -v12, v64, v115
	v_fma_f32 v115, -v13, v65, v115
	v_fma_f32 v115, -v14, v66, v115
	v_fma_f32 v115, -v15, v67, v115
	v_fma_f32 v115, -v16, v68, v115
	v_fma_f32 v115, -v17, v69, v115
	v_fma_f32 v115, -v18, v70, v115
	v_fma_f32 v115, -v19, v71, v115
	ds_read_b128 v[12:15], v2 offset:13184
	ds_read_b128 v[16:19], v2 offset:13200
	s_waitcnt lgkmcnt(6)
	v_fma_f32 v115, -v20, v72, v115
	v_fma_f32 v115, -v21, v73, v115
	v_fma_f32 v115, -v22, v74, v115
	v_fma_f32 v115, -v23, v75, v115
	v_fma_f32 v115, -v24, v76, v115
	v_fma_f32 v115, -v25, v77, v115
	v_fma_f32 v115, -v26, v78, v115
	v_fma_f32 v115, -v27, v79, v115
	ds_read_b128 v[20:23], v2 offset:13216
	ds_read_b128 v[24:27], v2 offset:13232
	s_waitcnt lgkmcnt(6)
	v_fma_f32 v115, -v28, v80, v115
	v_fma_f32 v115, -v29, v81, v115
	v_fma_f32 v115, -v30, v82, v115
	v_fma_f32 v115, -v31, v83, v115
	v_fma_f32 v115, -v32, v84, v115
	v_fma_f32 v115, -v33, v85, v115
	v_fma_f32 v115, -v34, v86, v115
	v_fma_f32 v115, -v35, v87, v115
	ds_read_b128 v[28:31], v2 offset:13248
	ds_read_b128 v[32:35], v2 offset:13312
	s_waitcnt lgkmcnt(6)
	v_fma_f32 v115, -v4, v88, v115
	v_fma_f32 v115, -v5, v89, v115
	v_fma_f32 v115, -v6, v90, v115
	v_fma_f32 v115, -v7, v91, v115
	v_fma_f32 v115, -v8, v92, v115
	v_fma_f32 v115, -v9, v93, v115
	v_fma_f32 v115, -v10, v94, v115
	v_fma_f32 v115, -v11, v95, v115
	ds_read_b128 v[4:7], v2 offset:13328
	ds_read_b128 v[8:11], v2 offset:13344
	s_waitcnt lgkmcnt(6)
; #define LAS __attribute__((address_space(3)))
; __device__ __forceinline__ void dk_phase(const Frame& F, const bf16* QKrm, const unsigned char* KT, const unsigned char* VT, const float* BG, unsigned char* ITEMS) {
;     ...
;         float t[64];
; #pragma unroll
;         for (int r = 0; r < 64; ++r) {
;             float acc = (lane == r) ? 1.f : 0.f;
; #pragma unroll
;             for (int s4 = 0; s4 < (r + 3) / 4; ++s4) { const f32x4 a = *(const LAS f32x4*)(Amat + r * 64 + 4 * s4);
;                 if (4 * s4 + 0 < r) acc -= a.x * t[4 * s4 + 0]; if (4 * s4 + 1 < r) acc -= a.y * t[4 * s4 + 1];
;                 if (4 * s4 + 2 < r) acc -= a.z * t[4 * s4 + 2]; if (4 * s4 + 3 < r) acc -= a.w * t[4 * s4 + 3]; }
;             t[r] = acc;
;         }
	v_fma_f32 v115, -v12, v96, v115
	v_fma_f32 v115, -v13, v97, v115
	v_fma_f32 v115, -v14, v98, v115
	v_fma_f32 v115, -v15, v99, v115
	v_fma_f32 v115, -v16, v100, v115
	v_fma_f32 v115, -v17, v101, v115
	v_fma_f32 v115, -v18, v102, v115
	v_fma_f32 v115, -v19, v103, v115
	ds_read_b128 v[12:15], v2 offset:13360
	ds_read_b128 v[16:19], v2 offset:13376
	s_waitcnt lgkmcnt(6)
	v_fma_f32 v115, -v20, v104, v115
	v_fma_f32 v115, -v21, v105, v115
	v_fma_f32 v115, -v22, v106, v115
	v_fma_f32 v115, -v23, v107, v115
	v_fma_f32 v115, -v24, v108, v115
	v_fma_f32 v115, -v25, v109, v115
	v_fma_f32 v115, -v26, v110, v115
	v_fma_f32 v115, -v27, v111, v115
	ds_read_b128 v[20:23], v2 offset:13392
	ds_read_b128 v[24:27], v2 offset:13408
	s_waitcnt lgkmcnt(6)
	v_fma_f32 v115, -v28, v112, v115
	v_fma_f32 v115, -v29, v113, v115
	v_fma_f32 v115, -v30, v114, v115
	s_lshl_b64 s[42:43], 1, 52
	v_cndmask_b32_e64 v116, 0, 1.0, s[42:43]
	v_fma_f32 v116, -v32, v64, v116
	v_fma_f32 v116, -v33, v65, v116
	v_fma_f32 v116, -v34, v66, v116
	v_fma_f32 v116, -v35, v67, v116
	ds_read_b128 v[28:31], v2 offset:13424
	ds_read_b128 v[32:35], v2 offset:13440
	s_waitcnt lgkmcnt(6)
	v_fma_f32 v116, -v4, v68, v116
	v_fma_f32 v116, -v5, v69, v116
	v_fma_f32 v116, -v6, v70, v116
	v_fma_f32 v116, -v7, v71, v116
	v_fma_f32 v116, -v8, v72, v116
	v_fma_f32 v116, -v9, v73, v116
	v_fma_f32 v116, -v10, v74, v116
	v_fma_f32 v116, -v11, v75, v116
	ds_read_b128 v[4:7], v2 offset:13456
	ds_read_b128 v[8:11], v2 offset:13472
	s_waitcnt lgkmcnt(6)
	v_fma_f32 v116, -v12, v76, v116
	v_fma_f32 v116, -v13, v77, v116
	v_fma_f32 v116, -v14, v78, v116
	v_fma_f32 v116, -v15, v79, v116
	v_fma_f32 v116, -v16, v80, v116
	v_fma_f32 v116, -v17, v81, v116
	v_fma_f32 v116, -v18, v82, v116
	v_fma_f32 v116, -v19, v83, v116
	ds_read_b128 v[12:15], v2 offset:13488
	ds_read_b128 v[16:19], v2 offset:13504
	s_waitcnt lgkmcnt(6)
	v_fma_f32 v116, -v20, v84, v116
	v_fma_f32 v116, -v21, v85, v116
	v_fma_f32 v116, -v22, v86, v116
	v_fma_f32 v116, -v23, v87, v116
	v_fma_f32 v116, -v24, v88, v116
	v_fma_f32 v116, -v25, v89, v116
	v_fma_f32 v116, -v26, v90, v116
	v_fma_f32 v116, -v27, v91, v116
	ds_read_b128 v[20:23], v2 offset:13568
	ds_read_b128 v[24:27], v2 offset:13584
	s_waitcnt lgkmcnt(6)
	v_fma_f32 v116, -v28, v92, v116
	v_fma_f32 v116, -v29, v93, v116
	v_fma_f32 v116, -v30, v94, v116
	v_fma_f32 v116, -v31, v95, v116
	v_fma_f32 v116, -v32, v96, v116
	v_fma_f32 v116, -v33, v97, v116
	v_fma_f32 v116, -v34, v98, v116
	v_fma_f32 v116, -v35, v99, v116
	ds_read_b128 v[28:31], v2 offset:13600
	ds_read_b128 v[32:35], v2 offset:13616
	s_waitcnt lgkmcnt(6)
	v_fma_f32 v116, -v4, v100, v116
	v_fma_f32 v116, -v5, v101, v116
	v_fma_f32 v116, -v6, v102, v116
	v_fma_f32 v116, -v7, v103, v116
	v_fma_f32 v116, -v8, v104, v116
	v_fma_f32 v116, -v9, v105, v116
	v_fma_f32 v116, -v10, v106, v116
	v_fma_f32 v116, -v11, v107, v116
	ds_read_b128 v[4:7], v2 offset:13632
	ds_read_b128 v[8:11], v2 offset:13648
	s_waitcnt lgkmcnt(6)
	v_fma_f32 v116, -v12, v108, v116
	v_fma_f32 v116, -v13, v109, v116
	v_fma_f32 v116, -v14, v110, v116
	v_fma_f32 v116, -v15, v111, v116
	v_fma_f32 v116, -v16, v112, v116
	v_fma_f32 v116, -v17, v113, v116
	v_fma_f32 v116, -v18, v114, v116
	v_fma_f32 v116, -v19, v115, v116
	ds_read_b128 v[12:15], v2 offset:13664
	ds_read_b128 v[16:19], v2 offset:13680
	s_waitcnt lgkmcnt(6)
	s_lshl_b64 s[42:43], 1, 53
	v_cndmask_b32_e64 v117, 0, 1.0, s[42:43]
	v_fma_f32 v117, -v20, v64, v117
	v_fma_f32 v117, -v21, v65, v117
	v_fma_f32 v117, -v22, v66, v117
	v_fma_f32 v117, -v23, v67, v117
	v_fma_f32 v117, -v24, v68, v117
	v_fma_f32 v117, -v25, v69, v117
	v_fma_f32 v117, -v26, v70, v117
	v_fma_f32 v117, -v27, v71, v117
	ds_read_b128 v[20:23], v2 offset:13696
	ds_read_b128 v[24:27], v2 offset:13712
	s_waitcnt lgkmcnt(6)
	v_fma_f32 v117, -v28, v72, v117
	v_fma_f32 v117, -v29, v73, v117
	v_fma_f32 v117, -v30, v74, v117
	v_fma_f32 v117, -v31, v75, v117
	v_fma_f32 v117, -v32, v76, v117
	v_fma_f32 v117, -v33, v77, v117
	v_fma_f32 v117, -v34, v78, v117
	v_fma_f32 v117, -v35, v79, v117
	ds_read_b128 v[28:31], v2 offset:13728
	ds_read_b128 v[32:35], v2 offset:13744
	s_waitcnt lgkmcnt(6)
	v_fma_f32 v117, -v4, v80, v117
	v_fma_f32 v117, -v5, v81, v117
	v_fma_f32 v117, -v6, v82, v117
	v_fma_f32 v117, -v7, v83, v117
	v_fma_f32 v117, -v8, v84, v117
	v_fma_f32 v117, -v9, v85, v117
	v_fma_f32 v117, -v10, v86, v117
	v_fma_f32 v117, -v11, v87, v117
	ds_read_b128 v[4:7], v2 offset:13760
	ds_read_b128 v[8:11], v2 offset:13776
	s_waitcnt lgkmcnt(6)
	v_fma_f32 v117, -v12, v88, v117
	v_fma_f32 v117, -v13, v89, v117
	v_fma_f32 v117, -v14, v90, v117
	v_fma_f32 v117, -v15, v91, v117
	v_fma_f32 v117, -v16, v92, v117
	v_fma_f32 v117, -v17, v93, v117
	v_fma_f32 v117, -v18, v94, v117
	v_fma_f32 v117, -v19, v95, v117
	ds_read_b128 v[12:15], v2 offset:13824
	ds_read_b128 v[16:19], v2 offset:13840
	s_waitcnt lgkmcnt(6)
	v_fma_f32 v117, -v20, v96, v117
	v_fma_f32 v117, -v21, v97, v117
	v_fma_f32 v117, -v22, v98, v117
	v_fma_f32 v117, -v23, v99, v117
	v_fma_f32 v117, -v24, v100, v117
	v_fma_f32 v117, -v25, v101, v117
	v_fma_f32 v117, -v26, v102, v117
	v_fma_f32 v117, -v27, v103, v117
	ds_read_b128 v[20:23], v2 offset:13856
	ds_read_b128 v[24:27], v2 offset:13872
	s_waitcnt lgkmcnt(6)
	v_fma_f32 v117, -v28, v104, v117
	v_fma_f32 v117, -v29, v105, v117
	v_fma_f32 v117, -v30, v106, v117
	v_fma_f32 v117, -v31, v107, v117
	v_fma_f32 v117, -v32, v108, v117
	v_fma_f32 v117, -v33, v109, v117
	v_fma_f32 v117, -v34, v110, v117
	v_fma_f32 v117, -v35, v111, v117
	ds_read_b128 v[28:31], v2 offset:13888
	ds_read_b128 v[32:35], v2 offset:13904
	s_waitcnt lgkmcnt(6)
; #define LAS __attribute__((address_space(3)))
; __device__ __forceinline__ void dk_phase(const Frame& F, const bf16* QKrm, const unsigned char* KT, const unsigned char* VT, const float* BG, unsigned char* ITEMS) {
;     ...
;         float t[64];
; #pragma unroll
;         for (int r = 0; r < 64; ++r) {
;             float acc = (lane == r) ? 1.f : 0.f;
; #pragma unroll
;             for (int s4 = 0; s4 < (r + 3) / 4; ++s4) { const f32x4 a = *(const LAS f32x4*)(Amat + r * 64 + 4 * s4);
;                 if (4 * s4 + 0 < r) acc -= a.x * t[4 * s4 + 0]; if (4 * s4 + 1 < r) acc -= a.y * t[4 * s4 + 1];
;                 if (4 * s4 + 2 < r) acc -= a.z * t[4 * s4 + 2]; if (4 * s4 + 3 < r) acc -= a.w * t[4 * s4 + 3]; }
;             t[r] = acc;
;         }
	v_fma_f32 v117, -v4, v112, v117
	v_fma_f32 v117, -v5, v113, v117
	v_fma_f32 v117, -v6, v114, v117
	v_fma_f32 v117, -v7, v115, v117
	v_fma_f32 v117, -v8, v116, v117
	ds_read_b128 v[4:7], v2 offset:13920
	ds_read_b128 v[8:11], v2 offset:13936
	s_waitcnt lgkmcnt(6)
	s_lshl_b64 s[42:43], 1, 54
	v_cndmask_b32_e64 v118, 0, 1.0, s[42:43]
	v_fma_f32 v118, -v12, v64, v118
	v_fma_f32 v118, -v13, v65, v118
	v_fma_f32 v118, -v14, v66, v118
	v_fma_f32 v118, -v15, v67, v118
	v_fma_f32 v118, -v16, v68, v118
	v_fma_f32 v118, -v17, v69, v118
	v_fma_f32 v118, -v18, v70, v118
	v_fma_f32 v118, -v19, v71, v118
	ds_read_b128 v[12:15], v2 offset:13952
	ds_read_b128 v[16:19], v2 offset:13968
	s_waitcnt lgkmcnt(6)
	v_fma_f32 v118, -v20, v72, v118
	v_fma_f32 v118, -v21, v73, v118
	v_fma_f32 v118, -v22, v74, v118
	v_fma_f32 v118, -v23, v75, v118
	v_fma_f32 v118, -v24, v76, v118
	v_fma_f32 v118, -v25, v77, v118
	v_fma_f32 v118, -v26, v78, v118
	v_fma_f32 v118, -v27, v79, v118
	ds_read_b128 v[20:23], v2 offset:13984
	ds_read_b128 v[24:27], v2 offset:14000
	s_waitcnt lgkmcnt(6)
	v_fma_f32 v118, -v28, v80, v118
	v_fma_f32 v118, -v29, v81, v118
	v_fma_f32 v118, -v30, v82, v118
	v_fma_f32 v118, -v31, v83, v118
	v_fma_f32 v118, -v32, v84, v118
	v_fma_f32 v118, -v33, v85, v118
	v_fma_f32 v118, -v34, v86, v118
	v_fma_f32 v118, -v35, v87, v118
	ds_read_b128 v[28:31], v2 offset:14016
	ds_read_b128 v[32:35], v2 offset:14032
	s_waitcnt lgkmcnt(6)
	v_fma_f32 v118, -v4, v88, v118
	v_fma_f32 v118, -v5, v89, v118
	v_fma_f32 v118, -v6, v90, v118
	v_fma_f32 v118, -v7, v91, v118
	v_fma_f32 v118, -v8, v92, v118
	v_fma_f32 v118, -v9, v93, v118
	v_fma_f32 v118, -v10, v94, v118
	v_fma_f32 v118, -v11, v95, v118
	ds_read_b128 v[4:7], v2 offset:14080
	ds_read_b128 v[8:11], v2 offset:14096
	s_waitcnt lgkmcnt(6)
	v_fma_f32 v118, -v12, v96, v118
	v_fma_f32 v118, -v13, v97, v118
	v_fma_f32 v118, -v14, v98, v118
	v_fma_f32 v118, -v15, v99, v118
	v_fma_f32 v118, -v16, v100, v118
	v_fma_f32 v118, -v17, v101, v118
	v_fma_f32 v118, -v18, v102, v118
	v_fma_f32 v118, -v19, v103, v118
	ds_read_b128 v[12:15], v2 offset:14112
	ds_read_b128 v[16:19], v2 offset:14128
	s_waitcnt lgkmcnt(6)
	v_fma_f32 v118, -v20, v104, v118
	v_fma_f32 v118, -v21, v105, v118
	v_fma_f32 v118, -v22, v106, v118
	v_fma_f32 v118, -v23, v107, v118
	v_fma_f32 v118, -v24, v108, v118
	v_fma_f32 v118, -v25, v109, v118
	v_fma_f32 v118, -v26, v110, v118
	v_fma_f32 v118, -v27, v111, v118
	ds_read_b128 v[20:23], v2 offset:14144
	ds_read_b128 v[24:27], v2 offset:14160
	s_waitcnt lgkmcnt(6)
	v_fma_f32 v118, -v28, v112, v118
	v_fma_f32 v118, -v29, v113, v118
	v_fma_f32 v118, -v30, v114, v118
	v_fma_f32 v118, -v31, v115, v118
	v_fma_f32 v118, -v32, v116, v118
	v_fma_f32 v118, -v33, v117, v118
	ds_read_b128 v[28:31], v2 offset:14176
	ds_read_b128 v[32:35], v2 offset:14192
	s_waitcnt lgkmcnt(6)
	s_lshl_b64 s[42:43], 1, 55
	v_cndmask_b32_e64 v119, 0, 1.0, s[42:43]
	v_fma_f32 v119, -v4, v64, v119
	v_fma_f32 v119, -v5, v65, v119
	v_fma_f32 v119, -v6, v66, v119
	v_fma_f32 v119, -v7, v67, v119
	v_fma_f32 v119, -v8, v68, v119
	v_fma_f32 v119, -v9, v69, v119
	v_fma_f32 v119, -v10, v70, v119
	v_fma_f32 v119, -v11, v71, v119
	ds_read_b128 v[4:7], v2 offset:14208
	ds_read_b128 v[8:11], v2 offset:14224
	s_waitcnt lgkmcnt(6)
	v_fma_f32 v119, -v12, v72, v119
	v_fma_f32 v119, -v13, v73, v119
	v_fma_f32 v119, -v14, v74, v119
	v_fma_f32 v119, -v15, v75, v119
	v_fma_f32 v119, -v16, v76, v119
	v_fma_f32 v119, -v17, v77, v119
	v_fma_f32 v119, -v18, v78, v119
	v_fma_f32 v119, -v19, v79, v119
	ds_read_b128 v[12:15], v2 offset:14240
	ds_read_b128 v[16:19], v2 offset:14256
	s_waitcnt lgkmcnt(6)
	v_fma_f32 v119, -v20, v80, v119
	v_fma_f32 v119, -v21, v81, v119
	v_fma_f32 v119, -v22, v82, v119
	v_fma_f32 v119, -v23, v83, v119
	v_fma_f32 v119, -v24, v84, v119
	v_fma_f32 v119, -v25, v85, v119
	v_fma_f32 v119, -v26, v86, v119
	v_fma_f32 v119, -v27, v87, v119
	ds_read_b128 v[20:23], v2 offset:14272
	ds_read_b128 v[24:27], v2 offset:14288
	s_waitcnt lgkmcnt(6)
	v_fma_f32 v119, -v28, v88, v119
	v_fma_f32 v119, -v29, v89, v119
	v_fma_f32 v119, -v30, v90, v119
	v_fma_f32 v119, -v31, v91, v119
	v_fma_f32 v119, -v32, v92, v119
	v_fma_f32 v119, -v33, v93, v119
	v_fma_f32 v119, -v34, v94, v119
	v_fma_f32 v119, -v35, v95, v119
	ds_read_b128 v[28:31], v2 offset:14336
	ds_read_b128 v[32:35], v2 offset:14352
	s_waitcnt lgkmcnt(6)
	v_fma_f32 v119, -v4, v96, v119
	v_fma_f32 v119, -v5, v97, v119
	v_fma_f32 v119, -v6, v98, v119
	v_fma_f32 v119, -v7, v99, v119
	v_fma_f32 v119, -v8, v100, v119
	v_fma_f32 v119, -v9, v101, v119
	v_fma_f32 v119, -v10, v102, v119
	v_fma_f32 v119, -v11, v103, v119
	ds_read_b128 v[4:7], v2 offset:14368
	ds_read_b128 v[8:11], v2 offset:14384
	s_waitcnt lgkmcnt(6)
	v_fma_f32 v119, -v12, v104, v119
	v_fma_f32 v119, -v13, v105, v119
	v_fma_f32 v119, -v14, v106, v119
	v_fma_f32 v119, -v15, v107, v119
	v_fma_f32 v119, -v16, v108, v119
	v_fma_f32 v119, -v17, v109, v119
	v_fma_f32 v119, -v18, v110, v119
	v_fma_f32 v119, -v19, v111, v119
	ds_read_b128 v[12:15], v2 offset:14400
	ds_read_b128 v[16:19], v2 offset:14416
	s_waitcnt lgkmcnt(6)
	v_fma_f32 v119, -v20, v112, v119
	v_fma_f32 v119, -v21, v113, v119
	v_fma_f32 v119, -v22, v114, v119
	v_fma_f32 v119, -v23, v115, v119
	v_fma_f32 v119, -v24, v116, v119
	v_fma_f32 v119, -v25, v117, v119
	v_fma_f32 v119, -v26, v118, v119
	ds_read_b128 v[20:23], v2 offset:14432
	ds_read_b128 v[24:27], v2 offset:14448
	s_waitcnt lgkmcnt(6)
; #define LAS __attribute__((address_space(3)))
; __device__ __forceinline__ void dk_phase(const Frame& F, const bf16* QKrm, const unsigned char* KT, const unsigned char* VT, const float* BG, unsigned char* ITEMS) {
;     ...
;         float t[64];
; #pragma unroll
;         for (int r = 0; r < 64; ++r) {
;             float acc = (lane == r) ? 1.f : 0.f;
; #pragma unroll
;             for (int s4 = 0; s4 < (r + 3) / 4; ++s4) { const f32x4 a = *(const LAS f32x4*)(Amat + r * 64 + 4 * s4);
;                 if (4 * s4 + 0 < r) acc -= a.x * t[4 * s4 + 0]; if (4 * s4 + 1 < r) acc -= a.y * t[4 * s4 + 1];
;                 if (4 * s4 + 2 < r) acc -= a.z * t[4 * s4 + 2]; if (4 * s4 + 3 < r) acc -= a.w * t[4 * s4 + 3]; }
;             t[r] = acc;
;         }
	s_lshl_b64 s[42:43], 1, 56
	v_cndmask_b32_e64 v120, 0, 1.0, s[42:43]
	v_fma_f32 v120, -v28, v64, v120
	v_fma_f32 v120, -v29, v65, v120
	v_fma_f32 v120, -v30, v66, v120
	v_fma_f32 v120, -v31, v67, v120
	v_fma_f32 v120, -v32, v68, v120
	v_fma_f32 v120, -v33, v69, v120
	v_fma_f32 v120, -v34, v70, v120
	v_fma_f32 v120, -v35, v71, v120
	ds_read_b128 v[28:31], v2 offset:14464
	ds_read_b128 v[32:35], v2 offset:14480
	s_waitcnt lgkmcnt(6)
	v_fma_f32 v120, -v4, v72, v120
	v_fma_f32 v120, -v5, v73, v120
	v_fma_f32 v120, -v6, v74, v120
	v_fma_f32 v120, -v7, v75, v120
	v_fma_f32 v120, -v8, v76, v120
	v_fma_f32 v120, -v9, v77, v120
	v_fma_f32 v120, -v10, v78, v120
	v_fma_f32 v120, -v11, v79, v120
	ds_read_b128 v[4:7], v2 offset:14496
	ds_read_b128 v[8:11], v2 offset:14512
	s_waitcnt lgkmcnt(6)
	v_fma_f32 v120, -v12, v80, v120
	v_fma_f32 v120, -v13, v81, v120
	v_fma_f32 v120, -v14, v82, v120
	v_fma_f32 v120, -v15, v83, v120
	v_fma_f32 v120, -v16, v84, v120
	v_fma_f32 v120, -v17, v85, v120
	v_fma_f32 v120, -v18, v86, v120
	v_fma_f32 v120, -v19, v87, v120
	ds_read_b128 v[12:15], v2 offset:14528
	ds_read_b128 v[16:19], v2 offset:14544
	s_waitcnt lgkmcnt(6)
	v_fma_f32 v120, -v20, v88, v120
	v_fma_f32 v120, -v21, v89, v120
	v_fma_f32 v120, -v22, v90, v120
	v_fma_f32 v120, -v23, v91, v120
	v_fma_f32 v120, -v24, v92, v120
	v_fma_f32 v120, -v25, v93, v120
	v_fma_f32 v120, -v26, v94, v120
	v_fma_f32 v120, -v27, v95, v120
	ds_read_b128 v[20:23], v2 offset:14592
	ds_read_b128 v[24:27], v2 offset:14608
	s_waitcnt lgkmcnt(6)
	v_fma_f32 v120, -v28, v96, v120
	v_fma_f32 v120, -v29, v97, v120
	v_fma_f32 v120, -v30, v98, v120
	v_fma_f32 v120, -v31, v99, v120
	v_fma_f32 v120, -v32, v100, v120
	v_fma_f32 v120, -v33, v101, v120
	v_fma_f32 v120, -v34, v102, v120
	v_fma_f32 v120, -v35, v103, v120
	ds_read_b128 v[28:31], v2 offset:14624
	ds_read_b128 v[32:35], v2 offset:14640
	s_waitcnt lgkmcnt(6)
	v_fma_f32 v120, -v4, v104, v120
	v_fma_f32 v120, -v5, v105, v120
	v_fma_f32 v120, -v6, v106, v120
	v_fma_f32 v120, -v7, v107, v120
	v_fma_f32 v120, -v8, v108, v120
	v_fma_f32 v120, -v9, v109, v120
	v_fma_f32 v120, -v10, v110, v120
	v_fma_f32 v120, -v11, v111, v120
	ds_read_b128 v[4:7], v2 offset:14656
	ds_read_b128 v[8:11], v2 offset:14672
	s_waitcnt lgkmcnt(6)
	v_fma_f32 v120, -v12, v112, v120
	v_fma_f32 v120, -v13, v113, v120
	v_fma_f32 v120, -v14, v114, v120
	v_fma_f32 v120, -v15, v115, v120
	v_fma_f32 v120, -v16, v116, v120
	v_fma_f32 v120, -v17, v117, v120
	v_fma_f32 v120, -v18, v118, v120
	v_fma_f32 v120, -v19, v119, v120
	ds_read_b128 v[12:15], v2 offset:14688
	ds_read_b128 v[16:19], v2 offset:14704
	s_waitcnt lgkmcnt(6)
	s_lshl_b64 s[42:43], 1, 57
	v_cndmask_b32_e64 v121, 0, 1.0, s[42:43]
	v_fma_f32 v121, -v20, v64, v121
	v_fma_f32 v121, -v21, v65, v121
	v_fma_f32 v121, -v22, v66, v121
	v_fma_f32 v121, -v23, v67, v121
	v_fma_f32 v121, -v24, v68, v121
	v_fma_f32 v121, -v25, v69, v121
	v_fma_f32 v121, -v26, v70, v121
	v_fma_f32 v121, -v27, v71, v121
	ds_read_b128 v[20:23], v2 offset:14720
	ds_read_b128 v[24:27], v2 offset:14736
	s_waitcnt lgkmcnt(6)
	v_fma_f32 v121, -v28, v72, v121
	v_fma_f32 v121, -v29, v73, v121
	v_fma_f32 v121, -v30, v74, v121
	v_fma_f32 v121, -v31, v75, v121
	v_fma_f32 v121, -v32, v76, v121
	v_fma_f32 v121, -v33, v77, v121
	v_fma_f32 v121, -v34, v78, v121
	v_fma_f32 v121, -v35, v79, v121
	ds_read_b128 v[28:31], v2 offset:14752
	ds_read_b128 v[32:35], v2 offset:14768
	s_waitcnt lgkmcnt(6)
	v_fma_f32 v121, -v4, v80, v121
	v_fma_f32 v121, -v5, v81, v121
	v_fma_f32 v121, -v6, v82, v121
	v_fma_f32 v121, -v7, v83, v121
	v_fma_f32 v121, -v8, v84, v121
	v_fma_f32 v121, -v9, v85, v121
	v_fma_f32 v121, -v10, v86, v121
	v_fma_f32 v121, -v11, v87, v121
	ds_read_b128 v[4:7], v2 offset:14784
	ds_read_b128 v[8:11], v2 offset:14800
	s_waitcnt lgkmcnt(6)
	v_fma_f32 v121, -v12, v88, v121
	v_fma_f32 v121, -v13, v89, v121
	v_fma_f32 v121, -v14, v90, v121
	v_fma_f32 v121, -v15, v91, v121
	v_fma_f32 v121, -v16, v92, v121
	v_fma_f32 v121, -v17, v93, v121
	v_fma_f32 v121, -v18, v94, v121
	v_fma_f32 v121, -v19, v95, v121
	ds_read_b128 v[12:15], v2 offset:14816
	ds_read_b128 v[16:19], v2 offset:14848
	s_waitcnt lgkmcnt(6)
	v_fma_f32 v121, -v20, v96, v121
	v_fma_f32 v121, -v21, v97, v121
	v_fma_f32 v121, -v22, v98, v121
	v_fma_f32 v121, -v23, v99, v121
	v_fma_f32 v121, -v24, v100, v121
	v_fma_f32 v121, -v25, v101, v121
	v_fma_f32 v121, -v26, v102, v121
	v_fma_f32 v121, -v27, v103, v121
	ds_read_b128 v[20:23], v2 offset:14864
	ds_read_b128 v[24:27], v2 offset:14880
	s_waitcnt lgkmcnt(6)
	v_fma_f32 v121, -v28, v104, v121
	v_fma_f32 v121, -v29, v105, v121
	v_fma_f32 v121, -v30, v106, v121
	v_fma_f32 v121, -v31, v107, v121
	v_fma_f32 v121, -v32, v108, v121
	v_fma_f32 v121, -v33, v109, v121
	v_fma_f32 v121, -v34, v110, v121
	v_fma_f32 v121, -v35, v111, v121
	ds_read_b128 v[28:31], v2 offset:14896
	ds_read_b128 v[32:35], v2 offset:14912
	s_waitcnt lgkmcnt(6)
	v_fma_f32 v121, -v4, v112, v121
	v_fma_f32 v121, -v5, v113, v121
	v_fma_f32 v121, -v6, v114, v121
	v_fma_f32 v121, -v7, v115, v121
	v_fma_f32 v121, -v8, v116, v121
	v_fma_f32 v121, -v9, v117, v121
	v_fma_f32 v121, -v10, v118, v121
	v_fma_f32 v121, -v11, v119, v121
	ds_read_b128 v[4:7], v2 offset:14928
	ds_read_b128 v[8:11], v2 offset:14944
	s_waitcnt lgkmcnt(6)
	v_fma_f32 v121, -v12, v120, v121
	s_lshl_b64 s[42:43], 1, 58
	v_cndmask_b32_e64 v122, 0, 1.0, s[42:43]
	v_fma_f32 v122, -v16, v64, v122
	v_fma_f32 v122, -v17, v65, v122
	v_fma_f32 v122, -v18, v66, v122
	v_fma_f32 v122, -v19, v67, v122
	ds_read_b128 v[12:15], v2 offset:14960
	ds_read_b128 v[16:19], v2 offset:14976
	s_waitcnt lgkmcnt(6)
; #define LAS __attribute__((address_space(3)))
; __device__ __forceinline__ void dk_phase(const Frame& F, const bf16* QKrm, const unsigned char* KT, const unsigned char* VT, const float* BG, unsigned char* ITEMS) {
;     ...
;         float t[64];
; #pragma unroll
;         for (int r = 0; r < 64; ++r) {
;             float acc = (lane == r) ? 1.f : 0.f;
; #pragma unroll
;             for (int s4 = 0; s4 < (r + 3) / 4; ++s4) { const f32x4 a = *(const LAS f32x4*)(Amat + r * 64 + 4 * s4);
;                 if (4 * s4 + 0 < r) acc -= a.x * t[4 * s4 + 0]; if (4 * s4 + 1 < r) acc -= a.y * t[4 * s4 + 1];
;                 if (4 * s4 + 2 < r) acc -= a.z * t[4 * s4 + 2]; if (4 * s4 + 3 < r) acc -= a.w * t[4 * s4 + 3]; }
;             t[r] = acc;
;         }
	v_fma_f32 v122, -v20, v68, v122
	v_fma_f32 v122, -v21, v69, v122
	v_fma_f32 v122, -v22, v70, v122
	v_fma_f32 v122, -v23, v71, v122
	v_fma_f32 v122, -v24, v72, v122
	v_fma_f32 v122, -v25, v73, v122
	v_fma_f32 v122, -v26, v74, v122
	v_fma_f32 v122, -v27, v75, v122
	ds_read_b128 v[20:23], v2 offset:14992
	ds_read_b128 v[24:27], v2 offset:15008
	s_waitcnt lgkmcnt(6)
	v_fma_f32 v122, -v28, v76, v122
	v_fma_f32 v122, -v29, v77, v122
	v_fma_f32 v122, -v30, v78, v122
	v_fma_f32 v122, -v31, v79, v122
	v_fma_f32 v122, -v32, v80, v122
	v_fma_f32 v122, -v33, v81, v122
	v_fma_f32 v122, -v34, v82, v122
	v_fma_f32 v122, -v35, v83, v122
	ds_read_b128 v[28:31], v2 offset:15024
	ds_read_b128 v[32:35], v2 offset:15040
	s_waitcnt lgkmcnt(6)
	v_fma_f32 v122, -v4, v84, v122
	v_fma_f32 v122, -v5, v85, v122
	v_fma_f32 v122, -v6, v86, v122
	v_fma_f32 v122, -v7, v87, v122
	v_fma_f32 v122, -v8, v88, v122
	v_fma_f32 v122, -v9, v89, v122
	v_fma_f32 v122, -v10, v90, v122
	v_fma_f32 v122, -v11, v91, v122
	ds_read_b128 v[4:7], v2 offset:15056
	ds_read_b128 v[8:11], v2 offset:15072
	s_waitcnt lgkmcnt(6)
	v_fma_f32 v122, -v12, v92, v122
	v_fma_f32 v122, -v13, v93, v122
	v_fma_f32 v122, -v14, v94, v122
	v_fma_f32 v122, -v15, v95, v122
	v_fma_f32 v122, -v16, v96, v122
	v_fma_f32 v122, -v17, v97, v122
	v_fma_f32 v122, -v18, v98, v122
	v_fma_f32 v122, -v19, v99, v122
	ds_read_b128 v[12:15], v2 offset:15104
	ds_read_b128 v[16:19], v2 offset:15120
	s_waitcnt lgkmcnt(6)
	v_fma_f32 v122, -v20, v100, v122
	v_fma_f32 v122, -v21, v101, v122
	v_fma_f32 v122, -v22, v102, v122
	v_fma_f32 v122, -v23, v103, v122
	v_fma_f32 v122, -v24, v104, v122
	v_fma_f32 v122, -v25, v105, v122
	v_fma_f32 v122, -v26, v106, v122
	v_fma_f32 v122, -v27, v107, v122
	ds_read_b128 v[20:23], v2 offset:15136
	ds_read_b128 v[24:27], v2 offset:15152
	s_waitcnt lgkmcnt(6)
	v_fma_f32 v122, -v28, v108, v122
	v_fma_f32 v122, -v29, v109, v122
	v_fma_f32 v122, -v30, v110, v122
	v_fma_f32 v122, -v31, v111, v122
	v_fma_f32 v122, -v32, v112, v122
	v_fma_f32 v122, -v33, v113, v122
	v_fma_f32 v122, -v34, v114, v122
	v_fma_f32 v122, -v35, v115, v122
	ds_read_b128 v[28:31], v2 offset:15168
	ds_read_b128 v[32:35], v2 offset:15184
	s_waitcnt lgkmcnt(6)
	v_fma_f32 v122, -v4, v116, v122
	v_fma_f32 v122, -v5, v117, v122
	v_fma_f32 v122, -v6, v118, v122
	v_fma_f32 v122, -v7, v119, v122
	v_fma_f32 v122, -v8, v120, v122
	v_fma_f32 v122, -v9, v121, v122
	ds_read_b128 v[4:7], v2 offset:15200
	ds_read_b128 v[8:11], v2 offset:15216
	s_waitcnt lgkmcnt(6)
	s_lshl_b64 s[42:43], 1, 59
	v_cndmask_b32_e64 v123, 0, 1.0, s[42:43]
	v_fma_f32 v123, -v12, v64, v123
	v_fma_f32 v123, -v13, v65, v123
	v_fma_f32 v123, -v14, v66, v123
	v_fma_f32 v123, -v15, v67, v123
	v_fma_f32 v123, -v16, v68, v123
	v_fma_f32 v123, -v17, v69, v123
	v_fma_f32 v123, -v18, v70, v123
	v_fma_f32 v123, -v19, v71, v123
	ds_read_b128 v[12:15], v2 offset:15232
	ds_read_b128 v[16:19], v2 offset:15248
	s_waitcnt lgkmcnt(6)
	v_fma_f32 v123, -v20, v72, v123
	v_fma_f32 v123, -v21, v73, v123
	v_fma_f32 v123, -v22, v74, v123
	v_fma_f32 v123, -v23, v75, v123
	v_fma_f32 v123, -v24, v76, v123
	v_fma_f32 v123, -v25, v77, v123
	v_fma_f32 v123, -v26, v78, v123
	v_fma_f32 v123, -v27, v79, v123
	ds_read_b128 v[20:23], v2 offset:15264
	ds_read_b128 v[24:27], v2 offset:15280
	s_waitcnt lgkmcnt(6)
	v_fma_f32 v123, -v28, v80, v123
	v_fma_f32 v123, -v29, v81, v123
	v_fma_f32 v123, -v30, v82, v123
	v_fma_f32 v123, -v31, v83, v123
	v_fma_f32 v123, -v32, v84, v123
	v_fma_f32 v123, -v33, v85, v123
	v_fma_f32 v123, -v34, v86, v123
	v_fma_f32 v123, -v35, v87, v123
	ds_read_b128 v[28:31], v2 offset:15296
	ds_read_b128 v[32:35], v2 offset:15312
	s_waitcnt lgkmcnt(6)
	v_fma_f32 v123, -v4, v88, v123
	v_fma_f32 v123, -v5, v89, v123
	v_fma_f32 v123, -v6, v90, v123
	v_fma_f32 v123, -v7, v91, v123
	v_fma_f32 v123, -v8, v92, v123
	v_fma_f32 v123, -v9, v93, v123
	v_fma_f32 v123, -v10, v94, v123
	v_fma_f32 v123, -v11, v95, v123
	ds_read_b128 v[4:7], v2 offset:15328
	ds_read_b128 v[8:11], v2 offset:15360
	s_waitcnt lgkmcnt(6)
	v_fma_f32 v123, -v12, v96, v123
	v_fma_f32 v123, -v13, v97, v123
	v_fma_f32 v123, -v14, v98, v123
	v_fma_f32 v123, -v15, v99, v123
	v_fma_f32 v123, -v16, v100, v123
	v_fma_f32 v123, -v17, v101, v123
	v_fma_f32 v123, -v18, v102, v123
	v_fma_f32 v123, -v19, v103, v123
	ds_read_b128 v[12:15], v2 offset:15376
	ds_read_b128 v[16:19], v2 offset:15392
	s_waitcnt lgkmcnt(6)
	v_fma_f32 v123, -v20, v104, v123
	v_fma_f32 v123, -v21, v105, v123
	v_fma_f32 v123, -v22, v106, v123
	v_fma_f32 v123, -v23, v107, v123
	v_fma_f32 v123, -v24, v108, v123
	v_fma_f32 v123, -v25, v109, v123
	v_fma_f32 v123, -v26, v110, v123
	v_fma_f32 v123, -v27, v111, v123
	ds_read_b128 v[20:23], v2 offset:15408
	ds_read_b128 v[24:27], v2 offset:15424
	s_waitcnt lgkmcnt(6)
	v_fma_f32 v123, -v28, v112, v123
	v_fma_f32 v123, -v29, v113, v123
	v_fma_f32 v123, -v30, v114, v123
	v_fma_f32 v123, -v31, v115, v123
	v_fma_f32 v123, -v32, v116, v123
	v_fma_f32 v123, -v33, v117, v123
	v_fma_f32 v123, -v34, v118, v123
	v_fma_f32 v123, -v35, v119, v123
	ds_read_b128 v[28:31], v2 offset:15440
	ds_read_b128 v[32:35], v2 offset:15456
	s_waitcnt lgkmcnt(6)
	v_fma_f32 v123, -v4, v120, v123
	v_fma_f32 v123, -v5, v121, v123
	v_fma_f32 v123, -v6, v122, v123
	s_lshl_b64 s[42:43], 1, 60
	v_cndmask_b32_e64 v124, 0, 1.0, s[42:43]
	v_fma_f32 v124, -v8, v64, v124
	v_fma_f32 v124, -v9, v65, v124
	v_fma_f32 v124, -v10, v66, v124
	v_fma_f32 v124, -v11, v67, v124
	ds_read_b128 v[4:7], v2 offset:15472
	ds_read_b128 v[8:11], v2 offset:15488
	s_waitcnt lgkmcnt(6)
; #define LAS __attribute__((address_space(3)))
; __device__ __forceinline__ void dk_phase(const Frame& F, const bf16* QKrm, const unsigned char* KT, const unsigned char* VT, const float* BG, unsigned char* ITEMS) {
;     ...
;         float t[64];
; #pragma unroll
;         for (int r = 0; r < 64; ++r) {
;             float acc = (lane == r) ? 1.f : 0.f;
; #pragma unroll
;             for (int s4 = 0; s4 < (r + 3) / 4; ++s4) { const f32x4 a = *(const LAS f32x4*)(Amat + r * 64 + 4 * s4);
;                 if (4 * s4 + 0 < r) acc -= a.x * t[4 * s4 + 0]; if (4 * s4 + 1 < r) acc -= a.y * t[4 * s4 + 1];
;                 if (4 * s4 + 2 < r) acc -= a.z * t[4 * s4 + 2]; if (4 * s4 + 3 < r) acc -= a.w * t[4 * s4 + 3]; }
;             t[r] = acc;
;         }
	v_fma_f32 v124, -v12, v68, v124
	v_fma_f32 v124, -v13, v69, v124
	v_fma_f32 v124, -v14, v70, v124
	v_fma_f32 v124, -v15, v71, v124
	v_fma_f32 v124, -v16, v72, v124
	v_fma_f32 v124, -v17, v73, v124
	v_fma_f32 v124, -v18, v74, v124
	v_fma_f32 v124, -v19, v75, v124
	ds_read_b128 v[12:15], v2 offset:15504
	ds_read_b128 v[16:19], v2 offset:15520
	s_waitcnt lgkmcnt(6)
	v_fma_f32 v124, -v20, v76, v124
	v_fma_f32 v124, -v21, v77, v124
	v_fma_f32 v124, -v22, v78, v124
	v_fma_f32 v124, -v23, v79, v124
	v_fma_f32 v124, -v24, v80, v124
	v_fma_f32 v124, -v25, v81, v124
	v_fma_f32 v124, -v26, v82, v124
	v_fma_f32 v124, -v27, v83, v124
	ds_read_b128 v[20:23], v2 offset:15536
	ds_read_b128 v[24:27], v2 offset:15552
	s_waitcnt lgkmcnt(6)
	v_fma_f32 v124, -v28, v84, v124
	v_fma_f32 v124, -v29, v85, v124
	v_fma_f32 v124, -v30, v86, v124
	v_fma_f32 v124, -v31, v87, v124
	v_fma_f32 v124, -v32, v88, v124
	v_fma_f32 v124, -v33, v89, v124
	v_fma_f32 v124, -v34, v90, v124
	v_fma_f32 v124, -v35, v91, v124
	ds_read_b128 v[28:31], v2 offset:15568
	ds_read_b128 v[32:35], v2 offset:15584
	s_waitcnt lgkmcnt(6)
	v_fma_f32 v124, -v4, v92, v124
	v_fma_f32 v124, -v5, v93, v124
	v_fma_f32 v124, -v6, v94, v124
	v_fma_f32 v124, -v7, v95, v124
	v_fma_f32 v124, -v8, v96, v124
	v_fma_f32 v124, -v9, v97, v124
	v_fma_f32 v124, -v10, v98, v124
	v_fma_f32 v124, -v11, v99, v124
	ds_read_b128 v[4:7], v2 offset:15616
	ds_read_b128 v[8:11], v2 offset:15632
	s_waitcnt lgkmcnt(6)
	v_fma_f32 v124, -v12, v100, v124
	v_fma_f32 v124, -v13, v101, v124
	v_fma_f32 v124, -v14, v102, v124
	v_fma_f32 v124, -v15, v103, v124
	v_fma_f32 v124, -v16, v104, v124
	v_fma_f32 v124, -v17, v105, v124
	v_fma_f32 v124, -v18, v106, v124
	v_fma_f32 v124, -v19, v107, v124
	ds_read_b128 v[12:15], v2 offset:15648
	ds_read_b128 v[16:19], v2 offset:15664
	s_waitcnt lgkmcnt(6)
	v_fma_f32 v124, -v20, v108, v124
	v_fma_f32 v124, -v21, v109, v124
	v_fma_f32 v124, -v22, v110, v124
	v_fma_f32 v124, -v23, v111, v124
	v_fma_f32 v124, -v24, v112, v124
	v_fma_f32 v124, -v25, v113, v124
	v_fma_f32 v124, -v26, v114, v124
	v_fma_f32 v124, -v27, v115, v124
	ds_read_b128 v[20:23], v2 offset:15680
	ds_read_b128 v[24:27], v2 offset:15696
	s_waitcnt lgkmcnt(6)
	v_fma_f32 v124, -v28, v116, v124
	v_fma_f32 v124, -v29, v117, v124
	v_fma_f32 v124, -v30, v118, v124
	v_fma_f32 v124, -v31, v119, v124
	v_fma_f32 v124, -v32, v120, v124
	v_fma_f32 v124, -v33, v121, v124
	v_fma_f32 v124, -v34, v122, v124
	v_fma_f32 v124, -v35, v123, v124
	ds_read_b128 v[28:31], v2 offset:15712
	ds_read_b128 v[32:35], v2 offset:15728
	s_waitcnt lgkmcnt(6)
	s_lshl_b64 s[42:43], 1, 61
	v_cndmask_b32_e64 v125, 0, 1.0, s[42:43]
	v_fma_f32 v125, -v4, v64, v125
	v_fma_f32 v125, -v5, v65, v125
	v_fma_f32 v125, -v6, v66, v125
	v_fma_f32 v125, -v7, v67, v125
	v_fma_f32 v125, -v8, v68, v125
	v_fma_f32 v125, -v9, v69, v125
	v_fma_f32 v125, -v10, v70, v125
	v_fma_f32 v125, -v11, v71, v125
	ds_read_b128 v[4:7], v2 offset:15744
	ds_read_b128 v[8:11], v2 offset:15760
	s_waitcnt lgkmcnt(6)
	v_fma_f32 v125, -v12, v72, v125
	v_fma_f32 v125, -v13, v73, v125
	v_fma_f32 v125, -v14, v74, v125
	v_fma_f32 v125, -v15, v75, v125
	v_fma_f32 v125, -v16, v76, v125
	v_fma_f32 v125, -v17, v77, v125
	v_fma_f32 v125, -v18, v78, v125
	v_fma_f32 v125, -v19, v79, v125
	ds_read_b128 v[12:15], v2 offset:15776
	ds_read_b128 v[16:19], v2 offset:15792
	s_waitcnt lgkmcnt(6)
	v_fma_f32 v125, -v20, v80, v125
	v_fma_f32 v125, -v21, v81, v125
	v_fma_f32 v125, -v22, v82, v125
	v_fma_f32 v125, -v23, v83, v125
	v_fma_f32 v125, -v24, v84, v125
	v_fma_f32 v125, -v25, v85, v125
	v_fma_f32 v125, -v26, v86, v125
	v_fma_f32 v125, -v27, v87, v125
	ds_read_b128 v[20:23], v2 offset:15808
	ds_read_b128 v[24:27], v2 offset:15824
	s_waitcnt lgkmcnt(6)
	v_fma_f32 v125, -v28, v88, v125
	v_fma_f32 v125, -v29, v89, v125
	v_fma_f32 v125, -v30, v90, v125
	v_fma_f32 v125, -v31, v91, v125
	v_fma_f32 v125, -v32, v92, v125
	v_fma_f32 v125, -v33, v93, v125
	v_fma_f32 v125, -v34, v94, v125
	v_fma_f32 v125, -v35, v95, v125
	ds_read_b128 v[28:31], v2 offset:15840
	ds_read_b128 v[32:35], v2 offset:15856
	s_waitcnt lgkmcnt(6)
	v_fma_f32 v125, -v4, v96, v125
	v_fma_f32 v125, -v5, v97, v125
	v_fma_f32 v125, -v6, v98, v125
	v_fma_f32 v125, -v7, v99, v125
	v_fma_f32 v125, -v8, v100, v125
	v_fma_f32 v125, -v9, v101, v125
	v_fma_f32 v125, -v10, v102, v125
	v_fma_f32 v125, -v11, v103, v125
	ds_read_b128 v[4:7], v2 offset:15872
	ds_read_b128 v[8:11], v2 offset:15888
	s_waitcnt lgkmcnt(6)
	v_fma_f32 v125, -v12, v104, v125
	v_fma_f32 v125, -v13, v105, v125
	v_fma_f32 v125, -v14, v106, v125
	v_fma_f32 v125, -v15, v107, v125
	v_fma_f32 v125, -v16, v108, v125
	v_fma_f32 v125, -v17, v109, v125
	v_fma_f32 v125, -v18, v110, v125
	v_fma_f32 v125, -v19, v111, v125
	ds_read_b128 v[12:15], v2 offset:15904
	ds_read_b128 v[16:19], v2 offset:15920
	s_waitcnt lgkmcnt(6)
	v_fma_f32 v125, -v20, v112, v125
	v_fma_f32 v125, -v21, v113, v125
	v_fma_f32 v125, -v22, v114, v125
	v_fma_f32 v125, -v23, v115, v125
	v_fma_f32 v125, -v24, v116, v125
	v_fma_f32 v125, -v25, v117, v125
	v_fma_f32 v125, -v26, v118, v125
	v_fma_f32 v125, -v27, v119, v125
	ds_read_b128 v[20:23], v2 offset:15936
	ds_read_b128 v[24:27], v2 offset:15952
	s_waitcnt lgkmcnt(6)
	v_fma_f32 v125, -v28, v120, v125
	v_fma_f32 v125, -v29, v121, v125
	v_fma_f32 v125, -v30, v122, v125
	v_fma_f32 v125, -v31, v123, v125
	v_fma_f32 v125, -v32, v124, v125
	ds_read_b128 v[28:31], v2 offset:15968
	ds_read_b128 v[32:35], v2 offset:15984
	s_waitcnt lgkmcnt(6)
; #define LAS __attribute__((address_space(3)))
; __device__ __forceinline__ unsigned pk2(float lo, float hi) { const f32x2_cv v = {lo, hi}; const bf16x2_cv b = __builtin_convertvector(v, bf16x2_cv); return __builtin_bit_cast(unsigned, b); }
; __device__ __forceinline__ void dk_phase(const Frame& F, const bf16* QKrm, const unsigned char* KT, const unsigned char* VT, const float* BG, unsigned char* ITEMS) {
;     ...
;         float t[64];
; #pragma unroll
;         for (int r = 0; r < 64; ++r) {
;             float acc = (lane == r) ? 1.f : 0.f;
; #pragma unroll
;             for (int s4 = 0; s4 < (r + 3) / 4; ++s4) { const f32x4 a = *(const LAS f32x4*)(Amat + r * 64 + 4 * s4);
;                 if (4 * s4 + 0 < r) acc -= a.x * t[4 * s4 + 0]; if (4 * s4 + 1 < r) acc -= a.y * t[4 * s4 + 1];
;                 if (4 * s4 + 2 < r) acc -= a.z * t[4 * s4 + 2]; if (4 * s4 + 3 < r) acc -= a.w * t[4 * s4 + 3]; }
;             t[r] = acc;
;         }
;         asm volatile("" ::: "memory"); __builtin_amdgcn_sched_barrier(0);
;         {
;             const int c = dir ? 63 - lane : lane; const float bc = betaL[c], wc = bc * __expf(gamL[c]);
;             asm volatile("s_waitcnt lgkmcnt(0)" ::: "memory");
; #pragma unroll
;             for (int rp = 0; rp < 64; ++rp) { const int r = dir ? 63 - rp : rp;
;                 const unsigned w2 = pk2(t[rp] * wc, t[rp] * bc);
;                 *(LAS unsigned short*)(TW + r * TROW + c * 2) = (unsigned short)(w2 & 0xffffu);
;                 *(LAS unsigned short*)(TU + r * TROW + c * 2) = (unsigned short)(w2 >> 16); }
;         }
	s_lshl_b64 s[42:43], 1, 62
	v_cndmask_b32_e64 v126, 0, 1.0, s[42:43]
	v_fma_f32 v126, -v4, v64, v126
	v_fma_f32 v126, -v5, v65, v126
	v_fma_f32 v126, -v6, v66, v126
	v_fma_f32 v126, -v7, v67, v126
	v_fma_f32 v126, -v8, v68, v126
	v_fma_f32 v126, -v9, v69, v126
	v_fma_f32 v126, -v10, v70, v126
	v_fma_f32 v126, -v11, v71, v126
	ds_read_b128 v[4:7], v2 offset:16000
	ds_read_b128 v[8:11], v2 offset:16016
	s_waitcnt lgkmcnt(6)
	v_fma_f32 v126, -v12, v72, v126
	v_fma_f32 v126, -v13, v73, v126
	v_fma_f32 v126, -v14, v74, v126
	v_fma_f32 v126, -v15, v75, v126
	v_fma_f32 v126, -v16, v76, v126
	v_fma_f32 v126, -v17, v77, v126
	v_fma_f32 v126, -v18, v78, v126
	v_fma_f32 v126, -v19, v79, v126
	ds_read_b128 v[12:15], v2 offset:16032
	ds_read_b128 v[16:19], v2 offset:16048
	s_waitcnt lgkmcnt(6)
	v_fma_f32 v126, -v20, v80, v126
	v_fma_f32 v126, -v21, v81, v126
	v_fma_f32 v126, -v22, v82, v126
	v_fma_f32 v126, -v23, v83, v126
	v_fma_f32 v126, -v24, v84, v126
	v_fma_f32 v126, -v25, v85, v126
	v_fma_f32 v126, -v26, v86, v126
	v_fma_f32 v126, -v27, v87, v126
	ds_read_b128 v[20:23], v2 offset:16064
	ds_read_b128 v[24:27], v2 offset:16080
	s_waitcnt lgkmcnt(6)
	v_fma_f32 v126, -v28, v88, v126
	v_fma_f32 v126, -v29, v89, v126
	v_fma_f32 v126, -v30, v90, v126
	v_fma_f32 v126, -v31, v91, v126
	v_fma_f32 v126, -v32, v92, v126
	v_fma_f32 v126, -v33, v93, v126
	v_fma_f32 v126, -v34, v94, v126
	v_fma_f32 v126, -v35, v95, v126
	ds_read_b128 v[28:31], v2 offset:16096
	ds_read_b128 v[32:35], v2 offset:16112
	s_waitcnt lgkmcnt(6)
	v_fma_f32 v126, -v4, v96, v126
	v_fma_f32 v126, -v5, v97, v126
	v_fma_f32 v126, -v6, v98, v126
	v_fma_f32 v126, -v7, v99, v126
	v_fma_f32 v126, -v8, v100, v126
	v_fma_f32 v126, -v9, v101, v126
	v_fma_f32 v126, -v10, v102, v126
	v_fma_f32 v126, -v11, v103, v126
	ds_read_b128 v[4:7], v2 offset:16128
	ds_read_b128 v[8:11], v2 offset:16144
	s_waitcnt lgkmcnt(6)
	v_fma_f32 v126, -v12, v104, v126
	v_fma_f32 v126, -v13, v105, v126
	v_fma_f32 v126, -v14, v106, v126
	v_fma_f32 v126, -v15, v107, v126
	v_fma_f32 v126, -v16, v108, v126
	v_fma_f32 v126, -v17, v109, v126
	v_fma_f32 v126, -v18, v110, v126
	v_fma_f32 v126, -v19, v111, v126
	ds_read_b128 v[12:15], v2 offset:16160
	ds_read_b128 v[16:19], v2 offset:16176
	s_waitcnt lgkmcnt(6)
	v_fma_f32 v126, -v20, v112, v126
	v_fma_f32 v126, -v21, v113, v126
	v_fma_f32 v126, -v22, v114, v126
	v_fma_f32 v126, -v23, v115, v126
	v_fma_f32 v126, -v24, v116, v126
	v_fma_f32 v126, -v25, v117, v126
	v_fma_f32 v126, -v26, v118, v126
	v_fma_f32 v126, -v27, v119, v126
	ds_read_b128 v[20:23], v2 offset:16192
	ds_read_b128 v[24:27], v2 offset:16208
	s_waitcnt lgkmcnt(6)
	v_fma_f32 v126, -v28, v120, v126
	v_fma_f32 v126, -v29, v121, v126
	v_fma_f32 v126, -v30, v122, v126
	v_fma_f32 v126, -v31, v123, v126
	v_fma_f32 v126, -v32, v124, v126
	v_fma_f32 v126, -v33, v125, v126
	ds_read_b128 v[28:31], v2 offset:16224
	ds_read_b128 v[32:35], v2 offset:16240
	s_waitcnt lgkmcnt(6)
	s_lshl_b64 s[42:43], 1, 63
	v_cndmask_b32_e64 v127, 0, 1.0, s[42:43]
	v_fma_f32 v127, -v4, v64, v127
	v_fma_f32 v127, -v5, v65, v127
	v_fma_f32 v127, -v6, v66, v127
	v_fma_f32 v127, -v7, v67, v127
	v_fma_f32 v127, -v8, v68, v127
	v_fma_f32 v127, -v9, v69, v127
	v_fma_f32 v127, -v10, v70, v127
	v_fma_f32 v127, -v11, v71, v127
	ds_read_b128 v[4:7], v2 offset:16256
	ds_read_b128 v[8:11], v2 offset:16272
	s_waitcnt lgkmcnt(6)
	v_fma_f32 v127, -v12, v72, v127
	v_fma_f32 v127, -v13, v73, v127
	v_fma_f32 v127, -v14, v74, v127
	v_fma_f32 v127, -v15, v75, v127
	v_fma_f32 v127, -v16, v76, v127
	v_fma_f32 v127, -v17, v77, v127
	v_fma_f32 v127, -v18, v78, v127
	v_fma_f32 v127, -v19, v79, v127
	ds_read_b128 v[12:15], v2 offset:16288
	ds_read_b128 v[16:19], v2 offset:16304
	s_waitcnt lgkmcnt(6)
	v_fma_f32 v127, -v20, v80, v127
	v_fma_f32 v127, -v21, v81, v127
	v_fma_f32 v127, -v22, v82, v127
	v_fma_f32 v127, -v23, v83, v127
	v_fma_f32 v127, -v24, v84, v127
	v_fma_f32 v127, -v25, v85, v127
	v_fma_f32 v127, -v26, v86, v127
	v_fma_f32 v127, -v27, v87, v127
	ds_read_b128 v[20:23], v2 offset:16320
	ds_read_b128 v[24:27], v2 offset:16336
	s_waitcnt lgkmcnt(6)
	v_fma_f32 v127, -v28, v88, v127
	v_fma_f32 v127, -v29, v89, v127
	v_fma_f32 v127, -v30, v90, v127
	v_fma_f32 v127, -v31, v91, v127
	v_fma_f32 v127, -v32, v92, v127
	v_fma_f32 v127, -v33, v93, v127
	v_fma_f32 v127, -v34, v94, v127
	v_fma_f32 v127, -v35, v95, v127
	ds_read_b128 v[28:31], v2 offset:16352
	ds_read_b128 v[32:35], v2 offset:16368
	s_waitcnt lgkmcnt(6)
	v_fma_f32 v127, -v4, v96, v127
	v_fma_f32 v127, -v5, v97, v127
	v_fma_f32 v127, -v6, v98, v127
	v_fma_f32 v127, -v7, v99, v127
	v_fma_f32 v127, -v8, v100, v127
	v_fma_f32 v127, -v9, v101, v127
	v_fma_f32 v127, -v10, v102, v127
	v_fma_f32 v127, -v11, v103, v127
	s_waitcnt lgkmcnt(4)
	v_fma_f32 v127, -v12, v104, v127
	v_fma_f32 v127, -v13, v105, v127
	v_fma_f32 v127, -v14, v106, v127
	v_fma_f32 v127, -v15, v107, v127
	v_fma_f32 v127, -v16, v108, v127
	v_fma_f32 v127, -v17, v109, v127
	v_fma_f32 v127, -v18, v110, v127
	v_fma_f32 v127, -v19, v111, v127
	s_waitcnt lgkmcnt(2)
	v_fma_f32 v127, -v20, v112, v127
	v_fma_f32 v127, -v21, v113, v127
	v_fma_f32 v127, -v22, v114, v127
	v_fma_f32 v127, -v23, v115, v127
	v_fma_f32 v127, -v24, v116, v127
	v_fma_f32 v127, -v25, v117, v127
	v_fma_f32 v127, -v26, v118, v127
	v_fma_f32 v127, -v27, v119, v127
	s_waitcnt lgkmcnt(0)
	v_fma_f32 v127, -v28, v120, v127
	v_fma_f32 v127, -v29, v121, v127
	v_fma_f32 v127, -v30, v122, v127
	v_fma_f32 v127, -v31, v123, v127
	v_fma_f32 v127, -v32, v124, v127
	v_fma_f32 v127, -v33, v125, v127
	v_fma_f32 v127, -v34, v126, v127
	v_sub_u32_e32 v36, 63, v185
	v_cndmask_b32_e64 v36, v36, v185, s[40:41]
	v_lshl_add_u32 v37, v36, 2, s53
	ds_read2st64_b32 v[38:39], v37 offset0:68 offset1:69
	v_lshl_add_u32 v36, v36, 1, s53
	s_waitcnt lgkmcnt(0)
	v_mul_f32_e32 v40, 0x3fb8aa3b, v38
	v_exp_f32_e32 v40, v40
	s_nop 0
	v_mul_f32_e32 v38, v39, v40
	s_cmp_lg_u64 s[40:41], 0
	s_cbranch_scc0 .Ldk_rev
; #define LAS __attribute__((address_space(3)))
; __device__ __forceinline__ unsigned pk2(float lo, float hi) { const f32x2_cv v = {lo, hi}; const bf16x2_cv b = __builtin_convertvector(v, bf16x2_cv); return __builtin_bit_cast(unsigned, b); }
; __device__ __forceinline__ void dk_phase(const Frame& F, const bf16* QKrm, const unsigned char* KT, const unsigned char* VT, const float* BG, unsigned char* ITEMS) {
;     ...
;         {
;             const int c = dir ? 63 - lane : lane; const float bc = betaL[c], wc = bc * __expf(gamL[c]);
;             asm volatile("s_waitcnt lgkmcnt(0)" ::: "memory");
; #pragma unroll
;             for (int rp = 0; rp < 64; ++rp) { const int r = dir ? 63 - rp : rp;
;                 const unsigned w2 = pk2(t[rp] * wc, t[rp] * bc);
;                 *(LAS unsigned short*)(TW + r * TROW + c * 2) = (unsigned short)(w2 & 0xffffu);
;                 *(LAS unsigned short*)(TU + r * TROW + c * 2) = (unsigned short)(w2 >> 16); }
;         }
	v_pk_mul_f32 v[40:41], v[64:65], v[38:39] op_sel_hi:[0,1]
	v_cvt_pk_bf16_f32 v42, v40, v41
	v_pk_mul_f32 v[44:45], v[64:65], v[38:39] op_sel:[1,0]
	ds_write_b16 v36, v42
	ds_write_b16_d16_hi v36, v42 offset:8704
	v_cvt_pk_bf16_f32 v46, v44, v45
	v_pk_mul_f32 v[40:41], v[66:67], v[38:39] op_sel_hi:[0,1]
	ds_write_b16 v36, v46 offset:136
	ds_write_b16_d16_hi v36, v46 offset:8840
	v_cvt_pk_bf16_f32 v42, v40, v41
	v_pk_mul_f32 v[44:45], v[66:67], v[38:39] op_sel:[1,0]
	ds_write_b16 v36, v42 offset:272
	ds_write_b16_d16_hi v36, v42 offset:8976
	v_cvt_pk_bf16_f32 v46, v44, v45
	v_pk_mul_f32 v[40:41], v[68:69], v[38:39] op_sel_hi:[0,1]
	ds_write_b16 v36, v46 offset:408
	ds_write_b16_d16_hi v36, v46 offset:9112
	v_cvt_pk_bf16_f32 v42, v40, v41
	v_pk_mul_f32 v[44:45], v[68:69], v[38:39] op_sel:[1,0]
	ds_write_b16 v36, v42 offset:544
	ds_write_b16_d16_hi v36, v42 offset:9248
	v_cvt_pk_bf16_f32 v46, v44, v45
	v_pk_mul_f32 v[40:41], v[70:71], v[38:39] op_sel_hi:[0,1]
	ds_write_b16 v36, v46 offset:680
	ds_write_b16_d16_hi v36, v46 offset:9384
	v_cvt_pk_bf16_f32 v42, v40, v41
	v_pk_mul_f32 v[44:45], v[70:71], v[38:39] op_sel:[1,0]
	ds_write_b16 v36, v42 offset:816
	ds_write_b16_d16_hi v36, v42 offset:9520
	v_cvt_pk_bf16_f32 v46, v44, v45
	v_pk_mul_f32 v[40:41], v[72:73], v[38:39] op_sel_hi:[0,1]
	ds_write_b16 v36, v46 offset:952
	ds_write_b16_d16_hi v36, v46 offset:9656
	v_cvt_pk_bf16_f32 v42, v40, v41
	v_pk_mul_f32 v[44:45], v[72:73], v[38:39] op_sel:[1,0]
	ds_write_b16 v36, v42 offset:1088
	ds_write_b16_d16_hi v36, v42 offset:9792
	v_cvt_pk_bf16_f32 v46, v44, v45
	v_pk_mul_f32 v[40:41], v[74:75], v[38:39] op_sel_hi:[0,1]
	ds_write_b16 v36, v46 offset:1224
	ds_write_b16_d16_hi v36, v46 offset:9928
	v_cvt_pk_bf16_f32 v42, v40, v41
	v_pk_mul_f32 v[44:45], v[74:75], v[38:39] op_sel:[1,0]
	ds_write_b16 v36, v42 offset:1360
	ds_write_b16_d16_hi v36, v42 offset:10064
	v_cvt_pk_bf16_f32 v46, v44, v45
	v_pk_mul_f32 v[40:41], v[76:77], v[38:39] op_sel_hi:[0,1]
	ds_write_b16 v36, v46 offset:1496
	ds_write_b16_d16_hi v36, v46 offset:10200
	v_cvt_pk_bf16_f32 v42, v40, v41
	v_pk_mul_f32 v[44:45], v[76:77], v[38:39] op_sel:[1,0]
	ds_write_b16 v36, v42 offset:1632
	ds_write_b16_d16_hi v36, v42 offset:10336
	v_cvt_pk_bf16_f32 v46, v44, v45
	v_pk_mul_f32 v[40:41], v[78:79], v[38:39] op_sel_hi:[0,1]
	ds_write_b16 v36, v46 offset:1768
	ds_write_b16_d16_hi v36, v46 offset:10472
	v_cvt_pk_bf16_f32 v42, v40, v41
	v_pk_mul_f32 v[44:45], v[78:79], v[38:39] op_sel:[1,0]
	ds_write_b16 v36, v42 offset:1904
	ds_write_b16_d16_hi v36, v42 offset:10608
	v_cvt_pk_bf16_f32 v46, v44, v45
	v_pk_mul_f32 v[40:41], v[80:81], v[38:39] op_sel_hi:[0,1]
	ds_write_b16 v36, v46 offset:2040
	ds_write_b16_d16_hi v36, v46 offset:10744
	v_cvt_pk_bf16_f32 v42, v40, v41
	v_pk_mul_f32 v[44:45], v[80:81], v[38:39] op_sel:[1,0]
	ds_write_b16 v36, v42 offset:2176
	ds_write_b16_d16_hi v36, v42 offset:10880
	v_cvt_pk_bf16_f32 v46, v44, v45
	v_pk_mul_f32 v[40:41], v[82:83], v[38:39] op_sel_hi:[0,1]
	ds_write_b16 v36, v46 offset:2312
	ds_write_b16_d16_hi v36, v46 offset:11016
	v_cvt_pk_bf16_f32 v42, v40, v41
	v_pk_mul_f32 v[44:45], v[82:83], v[38:39] op_sel:[1,0]
	ds_write_b16 v36, v42 offset:2448
	ds_write_b16_d16_hi v36, v42 offset:11152
	v_cvt_pk_bf16_f32 v46, v44, v45
	v_pk_mul_f32 v[40:41], v[84:85], v[38:39] op_sel_hi:[0,1]
	ds_write_b16 v36, v46 offset:2584
	ds_write_b16_d16_hi v36, v46 offset:11288
	v_cvt_pk_bf16_f32 v42, v40, v41
	v_pk_mul_f32 v[44:45], v[84:85], v[38:39] op_sel:[1,0]
	ds_write_b16 v36, v42 offset:2720
	ds_write_b16_d16_hi v36, v42 offset:11424
	v_cvt_pk_bf16_f32 v46, v44, v45
	v_pk_mul_f32 v[40:41], v[86:87], v[38:39] op_sel_hi:[0,1]
	ds_write_b16 v36, v46 offset:2856
	ds_write_b16_d16_hi v36, v46 offset:11560
	v_cvt_pk_bf16_f32 v42, v40, v41
	v_pk_mul_f32 v[44:45], v[86:87], v[38:39] op_sel:[1,0]
	ds_write_b16 v36, v42 offset:2992
	ds_write_b16_d16_hi v36, v42 offset:11696
	v_cvt_pk_bf16_f32 v46, v44, v45
	v_pk_mul_f32 v[40:41], v[88:89], v[38:39] op_sel_hi:[0,1]
	ds_write_b16 v36, v46 offset:3128
	ds_write_b16_d16_hi v36, v46 offset:11832
	v_cvt_pk_bf16_f32 v42, v40, v41
	v_pk_mul_f32 v[44:45], v[88:89], v[38:39] op_sel:[1,0]
	ds_write_b16 v36, v42 offset:3264
	ds_write_b16_d16_hi v36, v42 offset:11968
	v_cvt_pk_bf16_f32 v46, v44, v45
	v_pk_mul_f32 v[40:41], v[90:91], v[38:39] op_sel_hi:[0,1]
	ds_write_b16 v36, v46 offset:3400
	ds_write_b16_d16_hi v36, v46 offset:12104
	v_cvt_pk_bf16_f32 v42, v40, v41
	v_pk_mul_f32 v[44:45], v[90:91], v[38:39] op_sel:[1,0]
	ds_write_b16 v36, v42 offset:3536
	ds_write_b16_d16_hi v36, v42 offset:12240
	v_cvt_pk_bf16_f32 v46, v44, v45
	v_pk_mul_f32 v[40:41], v[92:93], v[38:39] op_sel_hi:[0,1]
	ds_write_b16 v36, v46 offset:3672
	ds_write_b16_d16_hi v36, v46 offset:12376
	v_cvt_pk_bf16_f32 v42, v40, v41
	v_pk_mul_f32 v[44:45], v[92:93], v[38:39] op_sel:[1,0]
	ds_write_b16 v36, v42 offset:3808
	ds_write_b16_d16_hi v36, v42 offset:12512
	v_cvt_pk_bf16_f32 v46, v44, v45
	v_pk_mul_f32 v[40:41], v[94:95], v[38:39] op_sel_hi:[0,1]
	ds_write_b16 v36, v46 offset:3944
	ds_write_b16_d16_hi v36, v46 offset:12648
	v_cvt_pk_bf16_f32 v42, v40, v41
	v_pk_mul_f32 v[44:45], v[94:95], v[38:39] op_sel:[1,0]
	ds_write_b16 v36, v42 offset:4080
	ds_write_b16_d16_hi v36, v42 offset:12784
	v_cvt_pk_bf16_f32 v46, v44, v45
	v_pk_mul_f32 v[40:41], v[96:97], v[38:39] op_sel_hi:[0,1]
	ds_write_b16 v36, v46 offset:4216
	ds_write_b16_d16_hi v36, v46 offset:12920
	v_cvt_pk_bf16_f32 v42, v40, v41
	v_pk_mul_f32 v[44:45], v[96:97], v[38:39] op_sel:[1,0]
	ds_write_b16 v36, v42 offset:4352
	ds_write_b16_d16_hi v36, v42 offset:13056
	v_cvt_pk_bf16_f32 v46, v44, v45
; #define LAS __attribute__((address_space(3)))
; __device__ __forceinline__ unsigned pk2(float lo, float hi) { const f32x2_cv v = {lo, hi}; const bf16x2_cv b = __builtin_convertvector(v, bf16x2_cv); return __builtin_bit_cast(unsigned, b); }
; __device__ __forceinline__ void dk_phase(const Frame& F, const bf16* QKrm, const unsigned char* KT, const unsigned char* VT, const float* BG, unsigned char* ITEMS) {
;     ...
;         {
;             const int c = dir ? 63 - lane : lane; const float bc = betaL[c], wc = bc * __expf(gamL[c]);
;             asm volatile("s_waitcnt lgkmcnt(0)" ::: "memory");
; #pragma unroll
;             for (int rp = 0; rp < 64; ++rp) { const int r = dir ? 63 - rp : rp;
;                 const unsigned w2 = pk2(t[rp] * wc, t[rp] * bc);
;                 *(LAS unsigned short*)(TW + r * TROW + c * 2) = (unsigned short)(w2 & 0xffffu);
;                 *(LAS unsigned short*)(TU + r * TROW + c * 2) = (unsigned short)(w2 >> 16); }
;         }
	v_pk_mul_f32 v[40:41], v[98:99], v[38:39] op_sel_hi:[0,1]
	ds_write_b16 v36, v46 offset:4488
	ds_write_b16_d16_hi v36, v46 offset:13192
	v_cvt_pk_bf16_f32 v42, v40, v41
	v_pk_mul_f32 v[44:45], v[98:99], v[38:39] op_sel:[1,0]
	ds_write_b16 v36, v42 offset:4624
	ds_write_b16_d16_hi v36, v42 offset:13328
	v_cvt_pk_bf16_f32 v46, v44, v45
	v_pk_mul_f32 v[40:41], v[100:101], v[38:39] op_sel_hi:[0,1]
	ds_write_b16 v36, v46 offset:4760
	ds_write_b16_d16_hi v36, v46 offset:13464
	v_cvt_pk_bf16_f32 v42, v40, v41
	v_pk_mul_f32 v[44:45], v[100:101], v[38:39] op_sel:[1,0]
	ds_write_b16 v36, v42 offset:4896
	ds_write_b16_d16_hi v36, v42 offset:13600
	v_cvt_pk_bf16_f32 v46, v44, v45
	v_pk_mul_f32 v[40:41], v[102:103], v[38:39] op_sel_hi:[0,1]
	ds_write_b16 v36, v46 offset:5032
	ds_write_b16_d16_hi v36, v46 offset:13736
	v_cvt_pk_bf16_f32 v42, v40, v41
	v_pk_mul_f32 v[44:45], v[102:103], v[38:39] op_sel:[1,0]
	ds_write_b16 v36, v42 offset:5168
	ds_write_b16_d16_hi v36, v42 offset:13872
	v_cvt_pk_bf16_f32 v46, v44, v45
	v_pk_mul_f32 v[40:41], v[104:105], v[38:39] op_sel_hi:[0,1]
	ds_write_b16 v36, v46 offset:5304
	ds_write_b16_d16_hi v36, v46 offset:14008
	v_cvt_pk_bf16_f32 v42, v40, v41
	v_pk_mul_f32 v[44:45], v[104:105], v[38:39] op_sel:[1,0]
	ds_write_b16 v36, v42 offset:5440
	ds_write_b16_d16_hi v36, v42 offset:14144
	v_cvt_pk_bf16_f32 v46, v44, v45
	v_pk_mul_f32 v[40:41], v[106:107], v[38:39] op_sel_hi:[0,1]
	ds_write_b16 v36, v46 offset:5576
	ds_write_b16_d16_hi v36, v46 offset:14280
	v_cvt_pk_bf16_f32 v42, v40, v41
	v_pk_mul_f32 v[44:45], v[106:107], v[38:39] op_sel:[1,0]
	ds_write_b16 v36, v42 offset:5712
	ds_write_b16_d16_hi v36, v42 offset:14416
	v_cvt_pk_bf16_f32 v46, v44, v45
	v_pk_mul_f32 v[40:41], v[108:109], v[38:39] op_sel_hi:[0,1]
	ds_write_b16 v36, v46 offset:5848
	ds_write_b16_d16_hi v36, v46 offset:14552
	v_cvt_pk_bf16_f32 v42, v40, v41
	v_pk_mul_f32 v[44:45], v[108:109], v[38:39] op_sel:[1,0]
	ds_write_b16 v36, v42 offset:5984
	ds_write_b16_d16_hi v36, v42 offset:14688
	v_cvt_pk_bf16_f32 v46, v44, v45
	v_pk_mul_f32 v[40:41], v[110:111], v[38:39] op_sel_hi:[0,1]
	ds_write_b16 v36, v46 offset:6120
	ds_write_b16_d16_hi v36, v46 offset:14824
	v_cvt_pk_bf16_f32 v42, v40, v41
	v_pk_mul_f32 v[44:45], v[110:111], v[38:39] op_sel:[1,0]
	ds_write_b16 v36, v42 offset:6256
	ds_write_b16_d16_hi v36, v42 offset:14960
	v_cvt_pk_bf16_f32 v46, v44, v45
	v_pk_mul_f32 v[40:41], v[112:113], v[38:39] op_sel_hi:[0,1]
	ds_write_b16 v36, v46 offset:6392
	ds_write_b16_d16_hi v36, v46 offset:15096
	v_cvt_pk_bf16_f32 v42, v40, v41
	v_pk_mul_f32 v[44:45], v[112:113], v[38:39] op_sel:[1,0]
	ds_write_b16 v36, v42 offset:6528
	ds_write_b16_d16_hi v36, v42 offset:15232
	v_cvt_pk_bf16_f32 v46, v44, v45
	v_pk_mul_f32 v[40:41], v[114:115], v[38:39] op_sel_hi:[0,1]
	ds_write_b16 v36, v46 offset:6664
	ds_write_b16_d16_hi v36, v46 offset:15368
	v_cvt_pk_bf16_f32 v42, v40, v41
	v_pk_mul_f32 v[44:45], v[114:115], v[38:39] op_sel:[1,0]
	ds_write_b16 v36, v42 offset:6800
	ds_write_b16_d16_hi v36, v42 offset:15504
	v_cvt_pk_bf16_f32 v46, v44, v45
	v_pk_mul_f32 v[40:41], v[116:117], v[38:39] op_sel_hi:[0,1]
	ds_write_b16 v36, v46 offset:6936
	ds_write_b16_d16_hi v36, v46 offset:15640
	v_cvt_pk_bf16_f32 v42, v40, v41
	v_pk_mul_f32 v[44:45], v[116:117], v[38:39] op_sel:[1,0]
	ds_write_b16 v36, v42 offset:7072
	ds_write_b16_d16_hi v36, v42 offset:15776
	v_cvt_pk_bf16_f32 v46, v44, v45
	v_pk_mul_f32 v[40:41], v[118:119], v[38:39] op_sel_hi:[0,1]
	ds_write_b16 v36, v46 offset:7208
	ds_write_b16_d16_hi v36, v46 offset:15912
	v_cvt_pk_bf16_f32 v42, v40, v41
	v_pk_mul_f32 v[44:45], v[118:119], v[38:39] op_sel:[1,0]
	ds_write_b16 v36, v42 offset:7344
	ds_write_b16_d16_hi v36, v42 offset:16048
	v_cvt_pk_bf16_f32 v46, v44, v45
	v_pk_mul_f32 v[40:41], v[120:121], v[38:39] op_sel_hi:[0,1]
	ds_write_b16 v36, v46 offset:7480
	ds_write_b16_d16_hi v36, v46 offset:16184
	v_cvt_pk_bf16_f32 v42, v40, v41
	v_pk_mul_f32 v[44:45], v[120:121], v[38:39] op_sel:[1,0]
	ds_write_b16 v36, v42 offset:7616
	ds_write_b16_d16_hi v36, v42 offset:16320
	v_cvt_pk_bf16_f32 v46, v44, v45
	v_pk_mul_f32 v[40:41], v[122:123], v[38:39] op_sel_hi:[0,1]
	ds_write_b16 v36, v46 offset:7752
	ds_write_b16_d16_hi v36, v46 offset:16456
	v_cvt_pk_bf16_f32 v42, v40, v41
	v_pk_mul_f32 v[44:45], v[122:123], v[38:39] op_sel:[1,0]
	ds_write_b16 v36, v42 offset:7888
	ds_write_b16_d16_hi v36, v42 offset:16592
	v_cvt_pk_bf16_f32 v46, v44, v45
	v_pk_mul_f32 v[40:41], v[124:125], v[38:39] op_sel_hi:[0,1]
	ds_write_b16 v36, v46 offset:8024
	ds_write_b16_d16_hi v36, v46 offset:16728
	v_cvt_pk_bf16_f32 v42, v40, v41
	v_pk_mul_f32 v[44:45], v[124:125], v[38:39] op_sel:[1,0]
	ds_write_b16 v36, v42 offset:8160
	ds_write_b16_d16_hi v36, v42 offset:16864
	v_cvt_pk_bf16_f32 v46, v44, v45
	v_pk_mul_f32 v[40:41], v[126:127], v[38:39] op_sel_hi:[0,1]
	ds_write_b16 v36, v46 offset:8296
	ds_write_b16_d16_hi v36, v46 offset:17000
	v_cvt_pk_bf16_f32 v42, v40, v41
	v_pk_mul_f32 v[44:45], v[126:127], v[38:39] op_sel:[1,0]
	ds_write_b16 v36, v42 offset:8432
	ds_write_b16_d16_hi v36, v42 offset:17136
	v_cvt_pk_bf16_f32 v46, v44, v45
	ds_write_b16 v36, v46 offset:8568
	ds_write_b16_d16_hi v36, v46 offset:17272
	s_branch .Ldk_st_done
; #define LAS __attribute__((address_space(3)))
; __device__ __forceinline__ unsigned pk2(float lo, float hi) { const f32x2_cv v = {lo, hi}; const bf16x2_cv b = __builtin_convertvector(v, bf16x2_cv); return __builtin_bit_cast(unsigned, b); }
; __device__ __forceinline__ void dk_phase(const Frame& F, const bf16* QKrm, const unsigned char* KT, const unsigned char* VT, const float* BG, unsigned char* ITEMS) {
;     ...
;         {
;             const int c = dir ? 63 - lane : lane; const float bc = betaL[c], wc = bc * __expf(gamL[c]);
;             asm volatile("s_waitcnt lgkmcnt(0)" ::: "memory");
; #pragma unroll
;             for (int rp = 0; rp < 64; ++rp) { const int r = dir ? 63 - rp : rp;
;                 const unsigned w2 = pk2(t[rp] * wc, t[rp] * bc);
;                 *(LAS unsigned short*)(TW + r * TROW + c * 2) = (unsigned short)(w2 & 0xffffu);
;                 *(LAS unsigned short*)(TU + r * TROW + c * 2) = (unsigned short)(w2 >> 16); }
;         }
.Ldk_rev:
	v_pk_mul_f32 v[40:41], v[64:65], v[38:39] op_sel_hi:[0,1]
	v_cvt_pk_bf16_f32 v42, v40, v41
	v_pk_mul_f32 v[44:45], v[64:65], v[38:39] op_sel:[1,0]
	ds_write_b16 v36, v42 offset:8568
	ds_write_b16_d16_hi v36, v42 offset:17272
	v_cvt_pk_bf16_f32 v46, v44, v45
	v_pk_mul_f32 v[40:41], v[66:67], v[38:39] op_sel_hi:[0,1]
	ds_write_b16 v36, v46 offset:8432
	ds_write_b16_d16_hi v36, v46 offset:17136
	v_cvt_pk_bf16_f32 v42, v40, v41
	v_pk_mul_f32 v[44:45], v[66:67], v[38:39] op_sel:[1,0]
	ds_write_b16 v36, v42 offset:8296
	ds_write_b16_d16_hi v36, v42 offset:17000
	v_cvt_pk_bf16_f32 v46, v44, v45
	v_pk_mul_f32 v[40:41], v[68:69], v[38:39] op_sel_hi:[0,1]
	ds_write_b16 v36, v46 offset:8160
	ds_write_b16_d16_hi v36, v46 offset:16864
	v_cvt_pk_bf16_f32 v42, v40, v41
	v_pk_mul_f32 v[44:45], v[68:69], v[38:39] op_sel:[1,0]
	ds_write_b16 v36, v42 offset:8024
	ds_write_b16_d16_hi v36, v42 offset:16728
	v_cvt_pk_bf16_f32 v46, v44, v45
	v_pk_mul_f32 v[40:41], v[70:71], v[38:39] op_sel_hi:[0,1]
	ds_write_b16 v36, v46 offset:7888
	ds_write_b16_d16_hi v36, v46 offset:16592
	v_cvt_pk_bf16_f32 v42, v40, v41
	v_pk_mul_f32 v[44:45], v[70:71], v[38:39] op_sel:[1,0]
	ds_write_b16 v36, v42 offset:7752
	ds_write_b16_d16_hi v36, v42 offset:16456
	v_cvt_pk_bf16_f32 v46, v44, v45
	v_pk_mul_f32 v[40:41], v[72:73], v[38:39] op_sel_hi:[0,1]
	ds_write_b16 v36, v46 offset:7616
	ds_write_b16_d16_hi v36, v46 offset:16320
	v_cvt_pk_bf16_f32 v42, v40, v41
	v_pk_mul_f32 v[44:45], v[72:73], v[38:39] op_sel:[1,0]
	ds_write_b16 v36, v42 offset:7480
	ds_write_b16_d16_hi v36, v42 offset:16184
	v_cvt_pk_bf16_f32 v46, v44, v45
	v_pk_mul_f32 v[40:41], v[74:75], v[38:39] op_sel_hi:[0,1]
	ds_write_b16 v36, v46 offset:7344
	ds_write_b16_d16_hi v36, v46 offset:16048
	v_cvt_pk_bf16_f32 v42, v40, v41
	v_pk_mul_f32 v[44:45], v[74:75], v[38:39] op_sel:[1,0]
	ds_write_b16 v36, v42 offset:7208
	ds_write_b16_d16_hi v36, v42 offset:15912
	v_cvt_pk_bf16_f32 v46, v44, v45
	v_pk_mul_f32 v[40:41], v[76:77], v[38:39] op_sel_hi:[0,1]
	ds_write_b16 v36, v46 offset:7072
	ds_write_b16_d16_hi v36, v46 offset:15776
	v_cvt_pk_bf16_f32 v42, v40, v41
	v_pk_mul_f32 v[44:45], v[76:77], v[38:39] op_sel:[1,0]
	ds_write_b16 v36, v42 offset:6936
	ds_write_b16_d16_hi v36, v42 offset:15640
	v_cvt_pk_bf16_f32 v46, v44, v45
	v_pk_mul_f32 v[40:41], v[78:79], v[38:39] op_sel_hi:[0,1]
	ds_write_b16 v36, v46 offset:6800
	ds_write_b16_d16_hi v36, v46 offset:15504
	v_cvt_pk_bf16_f32 v42, v40, v41
	v_pk_mul_f32 v[44:45], v[78:79], v[38:39] op_sel:[1,0]
	ds_write_b16 v36, v42 offset:6664
	ds_write_b16_d16_hi v36, v42 offset:15368
	v_cvt_pk_bf16_f32 v46, v44, v45
	v_pk_mul_f32 v[40:41], v[80:81], v[38:39] op_sel_hi:[0,1]
	ds_write_b16 v36, v46 offset:6528
	ds_write_b16_d16_hi v36, v46 offset:15232
	v_cvt_pk_bf16_f32 v42, v40, v41
	v_pk_mul_f32 v[44:45], v[80:81], v[38:39] op_sel:[1,0]
	ds_write_b16 v36, v42 offset:6392
	ds_write_b16_d16_hi v36, v42 offset:15096
	v_cvt_pk_bf16_f32 v46, v44, v45
	v_pk_mul_f32 v[40:41], v[82:83], v[38:39] op_sel_hi:[0,1]
	ds_write_b16 v36, v46 offset:6256
	ds_write_b16_d16_hi v36, v46 offset:14960
	v_cvt_pk_bf16_f32 v42, v40, v41
	v_pk_mul_f32 v[44:45], v[82:83], v[38:39] op_sel:[1,0]
	ds_write_b16 v36, v42 offset:6120
	ds_write_b16_d16_hi v36, v42 offset:14824
	v_cvt_pk_bf16_f32 v46, v44, v45
	v_pk_mul_f32 v[40:41], v[84:85], v[38:39] op_sel_hi:[0,1]
	ds_write_b16 v36, v46 offset:5984
	ds_write_b16_d16_hi v36, v46 offset:14688
	v_cvt_pk_bf16_f32 v42, v40, v41
	v_pk_mul_f32 v[44:45], v[84:85], v[38:39] op_sel:[1,0]
	ds_write_b16 v36, v42 offset:5848
	ds_write_b16_d16_hi v36, v42 offset:14552
	v_cvt_pk_bf16_f32 v46, v44, v45
	v_pk_mul_f32 v[40:41], v[86:87], v[38:39] op_sel_hi:[0,1]
	ds_write_b16 v36, v46 offset:5712
	ds_write_b16_d16_hi v36, v46 offset:14416
	v_cvt_pk_bf16_f32 v42, v40, v41
	v_pk_mul_f32 v[44:45], v[86:87], v[38:39] op_sel:[1,0]
	ds_write_b16 v36, v42 offset:5576
	ds_write_b16_d16_hi v36, v42 offset:14280
	v_cvt_pk_bf16_f32 v46, v44, v45
	v_pk_mul_f32 v[40:41], v[88:89], v[38:39] op_sel_hi:[0,1]
	ds_write_b16 v36, v46 offset:5440
	ds_write_b16_d16_hi v36, v46 offset:14144
	v_cvt_pk_bf16_f32 v42, v40, v41
	v_pk_mul_f32 v[44:45], v[88:89], v[38:39] op_sel:[1,0]
	ds_write_b16 v36, v42 offset:5304
	ds_write_b16_d16_hi v36, v42 offset:14008
	v_cvt_pk_bf16_f32 v46, v44, v45
	v_pk_mul_f32 v[40:41], v[90:91], v[38:39] op_sel_hi:[0,1]
	ds_write_b16 v36, v46 offset:5168
	ds_write_b16_d16_hi v36, v46 offset:13872
	v_cvt_pk_bf16_f32 v42, v40, v41
	v_pk_mul_f32 v[44:45], v[90:91], v[38:39] op_sel:[1,0]
	ds_write_b16 v36, v42 offset:5032
	ds_write_b16_d16_hi v36, v42 offset:13736
	v_cvt_pk_bf16_f32 v46, v44, v45
	v_pk_mul_f32 v[40:41], v[92:93], v[38:39] op_sel_hi:[0,1]
	ds_write_b16 v36, v46 offset:4896
	ds_write_b16_d16_hi v36, v46 offset:13600
	v_cvt_pk_bf16_f32 v42, v40, v41
	v_pk_mul_f32 v[44:45], v[92:93], v[38:39] op_sel:[1,0]
	ds_write_b16 v36, v42 offset:4760
	ds_write_b16_d16_hi v36, v42 offset:13464
	v_cvt_pk_bf16_f32 v46, v44, v45
	v_pk_mul_f32 v[40:41], v[94:95], v[38:39] op_sel_hi:[0,1]
	ds_write_b16 v36, v46 offset:4624
	ds_write_b16_d16_hi v36, v46 offset:13328
	v_cvt_pk_bf16_f32 v42, v40, v41
	v_pk_mul_f32 v[44:45], v[94:95], v[38:39] op_sel:[1,0]
	ds_write_b16 v36, v42 offset:4488
	ds_write_b16_d16_hi v36, v42 offset:13192
	v_cvt_pk_bf16_f32 v46, v44, v45
	v_pk_mul_f32 v[40:41], v[96:97], v[38:39] op_sel_hi:[0,1]
	ds_write_b16 v36, v46 offset:4352
	ds_write_b16_d16_hi v36, v46 offset:13056
	v_cvt_pk_bf16_f32 v42, v40, v41
	v_pk_mul_f32 v[44:45], v[96:97], v[38:39] op_sel:[1,0]
	ds_write_b16 v36, v42 offset:4216
	ds_write_b16_d16_hi v36, v42 offset:12920
; #define LAS __attribute__((address_space(3)))
; __device__ __forceinline__ unsigned pk2(float lo, float hi) { const f32x2_cv v = {lo, hi}; const bf16x2_cv b = __builtin_convertvector(v, bf16x2_cv); return __builtin_bit_cast(unsigned, b); }
; __device__ __forceinline__ void dk_phase(const Frame& F, const bf16* QKrm, const unsigned char* KT, const unsigned char* VT, const float* BG, unsigned char* ITEMS) {
;     ...
;         {
;             const int c = dir ? 63 - lane : lane; const float bc = betaL[c], wc = bc * __expf(gamL[c]);
;             asm volatile("s_waitcnt lgkmcnt(0)" ::: "memory");
; #pragma unroll
;             for (int rp = 0; rp < 64; ++rp) { const int r = dir ? 63 - rp : rp;
;                 const unsigned w2 = pk2(t[rp] * wc, t[rp] * bc);
;                 *(LAS unsigned short*)(TW + r * TROW + c * 2) = (unsigned short)(w2 & 0xffffu);
;                 *(LAS unsigned short*)(TU + r * TROW + c * 2) = (unsigned short)(w2 >> 16); }
;         }
	v_cvt_pk_bf16_f32 v46, v44, v45
	v_pk_mul_f32 v[40:41], v[98:99], v[38:39] op_sel_hi:[0,1]
	ds_write_b16 v36, v46 offset:4080
	ds_write_b16_d16_hi v36, v46 offset:12784
	v_cvt_pk_bf16_f32 v42, v40, v41
	v_pk_mul_f32 v[44:45], v[98:99], v[38:39] op_sel:[1,0]
	ds_write_b16 v36, v42 offset:3944
	ds_write_b16_d16_hi v36, v42 offset:12648
	v_cvt_pk_bf16_f32 v46, v44, v45
	v_pk_mul_f32 v[40:41], v[100:101], v[38:39] op_sel_hi:[0,1]
	ds_write_b16 v36, v46 offset:3808
	ds_write_b16_d16_hi v36, v46 offset:12512
	v_cvt_pk_bf16_f32 v42, v40, v41
	v_pk_mul_f32 v[44:45], v[100:101], v[38:39] op_sel:[1,0]
	ds_write_b16 v36, v42 offset:3672
	ds_write_b16_d16_hi v36, v42 offset:12376
	v_cvt_pk_bf16_f32 v46, v44, v45
	v_pk_mul_f32 v[40:41], v[102:103], v[38:39] op_sel_hi:[0,1]
	ds_write_b16 v36, v46 offset:3536
	ds_write_b16_d16_hi v36, v46 offset:12240
	v_cvt_pk_bf16_f32 v42, v40, v41
	v_pk_mul_f32 v[44:45], v[102:103], v[38:39] op_sel:[1,0]
	ds_write_b16 v36, v42 offset:3400
	ds_write_b16_d16_hi v36, v42 offset:12104
	v_cvt_pk_bf16_f32 v46, v44, v45
	v_pk_mul_f32 v[40:41], v[104:105], v[38:39] op_sel_hi:[0,1]
	ds_write_b16 v36, v46 offset:3264
	ds_write_b16_d16_hi v36, v46 offset:11968
	v_cvt_pk_bf16_f32 v42, v40, v41
	v_pk_mul_f32 v[44:45], v[104:105], v[38:39] op_sel:[1,0]
	ds_write_b16 v36, v42 offset:3128
	ds_write_b16_d16_hi v36, v42 offset:11832
	v_cvt_pk_bf16_f32 v46, v44, v45
	v_pk_mul_f32 v[40:41], v[106:107], v[38:39] op_sel_hi:[0,1]
	ds_write_b16 v36, v46 offset:2992
	ds_write_b16_d16_hi v36, v46 offset:11696
	v_cvt_pk_bf16_f32 v42, v40, v41
	v_pk_mul_f32 v[44:45], v[106:107], v[38:39] op_sel:[1,0]
	ds_write_b16 v36, v42 offset:2856
	ds_write_b16_d16_hi v36, v42 offset:11560
	v_cvt_pk_bf16_f32 v46, v44, v45
	v_pk_mul_f32 v[40:41], v[108:109], v[38:39] op_sel_hi:[0,1]
	ds_write_b16 v36, v46 offset:2720
	ds_write_b16_d16_hi v36, v46 offset:11424
	v_cvt_pk_bf16_f32 v42, v40, v41
	v_pk_mul_f32 v[44:45], v[108:109], v[38:39] op_sel:[1,0]
	ds_write_b16 v36, v42 offset:2584
	ds_write_b16_d16_hi v36, v42 offset:11288
	v_cvt_pk_bf16_f32 v46, v44, v45
	v_pk_mul_f32 v[40:41], v[110:111], v[38:39] op_sel_hi:[0,1]
	ds_write_b16 v36, v46 offset:2448
	ds_write_b16_d16_hi v36, v46 offset:11152
	v_cvt_pk_bf16_f32 v42, v40, v41
	v_pk_mul_f32 v[44:45], v[110:111], v[38:39] op_sel:[1,0]
	ds_write_b16 v36, v42 offset:2312
	ds_write_b16_d16_hi v36, v42 offset:11016
	v_cvt_pk_bf16_f32 v46, v44, v45
	v_pk_mul_f32 v[40:41], v[112:113], v[38:39] op_sel_hi:[0,1]
	ds_write_b16 v36, v46 offset:2176
	ds_write_b16_d16_hi v36, v46 offset:10880
	v_cvt_pk_bf16_f32 v42, v40, v41
	v_pk_mul_f32 v[44:45], v[112:113], v[38:39] op_sel:[1,0]
	ds_write_b16 v36, v42 offset:2040
	ds_write_b16_d16_hi v36, v42 offset:10744
	v_cvt_pk_bf16_f32 v46, v44, v45
	v_pk_mul_f32 v[40:41], v[114:115], v[38:39] op_sel_hi:[0,1]
	ds_write_b16 v36, v46 offset:1904
	ds_write_b16_d16_hi v36, v46 offset:10608
	v_cvt_pk_bf16_f32 v42, v40, v41
	v_pk_mul_f32 v[44:45], v[114:115], v[38:39] op_sel:[1,0]
	ds_write_b16 v36, v42 offset:1768
	ds_write_b16_d16_hi v36, v42 offset:10472
	v_cvt_pk_bf16_f32 v46, v44, v45
	v_pk_mul_f32 v[40:41], v[116:117], v[38:39] op_sel_hi:[0,1]
	ds_write_b16 v36, v46 offset:1632
	ds_write_b16_d16_hi v36, v46 offset:10336
	v_cvt_pk_bf16_f32 v42, v40, v41
	v_pk_mul_f32 v[44:45], v[116:117], v[38:39] op_sel:[1,0]
	ds_write_b16 v36, v42 offset:1496
	ds_write_b16_d16_hi v36, v42 offset:10200
	v_cvt_pk_bf16_f32 v46, v44, v45
	v_pk_mul_f32 v[40:41], v[118:119], v[38:39] op_sel_hi:[0,1]
	ds_write_b16 v36, v46 offset:1360
	ds_write_b16_d16_hi v36, v46 offset:10064
	v_cvt_pk_bf16_f32 v42, v40, v41
	v_pk_mul_f32 v[44:45], v[118:119], v[38:39] op_sel:[1,0]
	ds_write_b16 v36, v42 offset:1224
	ds_write_b16_d16_hi v36, v42 offset:9928
	v_cvt_pk_bf16_f32 v46, v44, v45
	v_pk_mul_f32 v[40:41], v[120:121], v[38:39] op_sel_hi:[0,1]
	ds_write_b16 v36, v46 offset:1088
	ds_write_b16_d16_hi v36, v46 offset:9792
	v_cvt_pk_bf16_f32 v42, v40, v41
	v_pk_mul_f32 v[44:45], v[120:121], v[38:39] op_sel:[1,0]
	ds_write_b16 v36, v42 offset:952
	ds_write_b16_d16_hi v36, v42 offset:9656
	v_cvt_pk_bf16_f32 v46, v44, v45
	v_pk_mul_f32 v[40:41], v[122:123], v[38:39] op_sel_hi:[0,1]
	ds_write_b16 v36, v46 offset:816
	ds_write_b16_d16_hi v36, v46 offset:9520
	v_cvt_pk_bf16_f32 v42, v40, v41
	v_pk_mul_f32 v[44:45], v[122:123], v[38:39] op_sel:[1,0]
	ds_write_b16 v36, v42 offset:680
	ds_write_b16_d16_hi v36, v42 offset:9384
	v_cvt_pk_bf16_f32 v46, v44, v45
	v_pk_mul_f32 v[40:41], v[124:125], v[38:39] op_sel_hi:[0,1]
	ds_write_b16 v36, v46 offset:544
	ds_write_b16_d16_hi v36, v46 offset:9248
	v_cvt_pk_bf16_f32 v42, v40, v41
	v_pk_mul_f32 v[44:45], v[124:125], v[38:39] op_sel:[1,0]
	ds_write_b16 v36, v42 offset:408
	ds_write_b16_d16_hi v36, v42 offset:9112
	v_cvt_pk_bf16_f32 v46, v44, v45
	v_pk_mul_f32 v[40:41], v[126:127], v[38:39] op_sel_hi:[0,1]
	ds_write_b16 v36, v46 offset:272
	ds_write_b16_d16_hi v36, v46 offset:8976
	v_cvt_pk_bf16_f32 v42, v40, v41
	v_pk_mul_f32 v[44:45], v[126:127], v[38:39] op_sel:[1,0]
	ds_write_b16 v36, v42 offset:136
	ds_write_b16_d16_hi v36, v42 offset:8840
	v_cvt_pk_bf16_f32 v46, v44, v45
	ds_write_b16 v36, v46
	ds_write_b16_d16_hi v36, v46 offset:8704
; #define LAS __attribute__((address_space(3)))
; #define LDS_WAIT() asm volatile("s_waitcnt lgkmcnt(0)" ::: "memory")
; __device__ __forceinline__ unsigned pk2(float lo, float hi) { const f32x2_cv v = {lo, hi}; const bf16x2_cv b = __builtin_convertvector(v, bf16x2_cv); return __builtin_bit_cast(unsigned, b); }
; __device__ __forceinline__ void dk_phase(const Frame& F, const bf16* QKrm, const unsigned char* KT, const unsigned char* VT, const float* BG, unsigned char* ITEMS) {
;     ...
;         LDS_WAIT();
;         asm volatile("" ::: "memory"); __builtin_amdgcn_sched_barrier(0);
;         const unsigned char* ktb = KT + ((size_t)cb * 16 + hk) * 16384;
;         const unsigned char* vtb = VT + ((size_t)cb * 32 + hv) * 16384;
; #pragma unroll
;         for (int mt = 0; mt < 2; ++mt) {
;             bf16x8_t tb[2][2];
; #pragma unroll
;             for (int tt = 0; tt < 2; ++tt)
; #pragma unroll
;                 for (int s = 0; s < 2; ++s) { const LAS unsigned char* p = TW + (32 * mt + r32) * TROW + (32 * tt + 16 * s + 4 * hi) * 2;
;                     const v2u lo = *(const LAS v2u*)p, hi2 = *(const LAS v2u*)(p + 16); tb[tt][s] = as_frag((v4u){lo.x, lo.y, hi2.x, hi2.y}); }
;             bf16x8_t gf[16];
; #pragma unroll
;             for (int k = 0; k < 16; ++k) gf[k] = as_frag(*(const v4u*)(ktb + k * 1024 + lane * 16));
;             asm volatile("s_waitcnt vmcnt(0)" ::: "memory"); __builtin_amdgcn_sched_barrier(0);
; #pragma unroll
;             for (int dt = 0; dt < 4; ++dt) { f32x16_t acc = f32x16_t{};
; #pragma unroll
;                 for (int tt = 0; tt < 2; ++tt)
; #pragma unroll
;                     for (int s = 0; s < 2; ++s) { const bf16x8_t a = gf[(dt * 2 + tt) * 2 + s];
;                         acc = __builtin_amdgcn_mfma_f32_32x32x16_bf16(a, tb[tt][s], acc, 0, 0, 0); }
; #pragma unroll
;                 for (int st = 0; st < 2; ++st) { v4u wv; wv.x = pk2(acc[8 * st + 0], acc[8 * st + 1]); wv.y = pk2(acc[8 * st + 2], acc[8 * st + 3]); wv.z = pk2(acc[8 * st + 4], acc[8 * st + 5]); wv.w = pk2(acc[8 * st + 6], acc[8 * st + 7]);
;                     *(v4u*)(item + ITEM_W + ((mt * 4 + dt) * 2 + st) * 1024 + lane * 16) = wv; } }
.Ldk_st_done:
	s_waitcnt lgkmcnt(0)
	s_ashr_i32 s21, s20, 31
	s_lshl_b64 s[42:43], s[20:21], 18
	s_lshl_b32 s44, s84, 14
	s_mov_b64 s[46:47], s[86:87]
	s_add_u32 s42, s46, s42
	s_addc_u32 s43, s47, s43
	s_add_u32 s42, s42, s44
	s_addc_u32 s43, s43, 0
	v_lshl_add_u64 v[56:57], s[42:43], 0, v[168:169]
	v_add_co_u32_e32 v60, vcc, s3, v56
	global_load_dwordx4 v[4:7], v[56:57], off
	global_load_dwordx4 v[8:11], v[56:57], off offset:1024
	global_load_dwordx4 v[12:15], v[56:57], off offset:2048
	global_load_dwordx4 v[16:19], v[56:57], off offset:3072
	v_addc_co_u32_e32 v61, vcc, 0, v57, vcc
	v_add_co_u32_e32 v58, vcc, s16, v56
	s_lshl_b64 s[20:21], s[20:21], 19
	s_nop 0
	v_addc_co_u32_e32 v59, vcc, 0, v57, vcc
	v_add_co_u32_e32 v62, vcc, s17, v56
	global_load_dwordx4 v[20:23], v[60:61], off offset:1024
	global_load_dwordx4 v[24:27], v[60:61], off offset:2048
	global_load_dwordx4 v[28:31], v[58:59], off
	global_load_dwordx4 v[64:67], v[58:59], off offset:1024
	global_load_dwordx4 v[68:71], v[58:59], off offset:2048
	global_load_dwordx4 v[72:75], v[58:59], off offset:3072
	v_addc_co_u32_e32 v63, vcc, 0, v57, vcc
	global_load_dwordx4 v[32:35], v[60:61], off offset:3072
	global_load_dwordx4 v[76:79], v[62:63], off
	global_load_dwordx4 v[80:83], v[62:63], off offset:1024
	global_load_dwordx4 v[84:87], v[62:63], off offset:2048
	global_load_dwordx4 v[88:91], v[58:59], off offset:-4096
	global_load_dwordx4 v[92:95], v[62:63], off offset:3072
	s_lshl_b32 s42, s83, 14
	s_add_u32 s20, s81, s20
	s_addc_u32 s21, s89, s21
	s_add_u32 s20, s20, s42
	s_addc_u32 s21, s21, 0
	v_add_u32_e32 v2, s53, v164
	v_lshl_add_u64 v[54:55], s[20:21], 0, v[168:169]
	s_movk_i32 s21, 0x88
	v_mad_u32_u24 v112, v186, s21, v2
	ds_read2_b64 v[96:99], v112 offset1:2
	ds_read2_b64 v[100:103], v112 offset0:4 offset1:6
	ds_read2_b64 v[104:107], v112 offset0:8 offset1:10
	ds_read2_b64 v[108:111], v112 offset0:12 offset1:14
	s_waitcnt vmcnt(0)
	v_lshlrev_b32_e32 v36, 5, v185
	v_ashrrev_i32_e32 v37, 31, v36
	v_lshl_add_u64 v[52:53], s[18:19], 0, v[36:37]
	s_waitcnt vmcnt(15) lgkmcnt(3)
	v_mfma_f32_32x32x16_bf16 v[36:51], v[4:7], v[96:99], 0
	s_mov_b32 s20, 0xffff6000
	s_waitcnt vmcnt(14) lgkmcnt(2)
	v_mfma_f32_32x32x16_bf16 v[36:51], v[8:11], v[100:103], v[36:51]
	s_waitcnt vmcnt(13) lgkmcnt(1)
	v_mfma_f32_32x32x16_bf16 v[36:51], v[12:15], v[104:107], v[36:51]
	s_waitcnt vmcnt(12) lgkmcnt(0)
	v_mfma_f32_32x32x16_bf16 v[36:51], v[16:19], v[108:111], v[36:51]
	s_waitcnt vmcnt(1)
	v_mfma_f32_32x32x16_bf16 v[4:19], v[88:91], v[96:99], 0
	s_nop 9
	v_cvt_pk_bf16_f32 v36, v36, v37
	v_cvt_pk_bf16_f32 v37, v38, v39
	v_cvt_pk_bf16_f32 v38, v40, v41
	v_add_co_u32_e32 v40, vcc, s20, v166
	s_mov_b32 s20, 0xffff7000
	s_nop 0
	v_addc_co_u32_e32 v41, vcc, -1, v167, vcc
	v_mfma_f32_32x32x16_bf16 v[4:19], v[20:23], v[100:103], v[4:19]
	v_cvt_pk_bf16_f32 v39, v42, v43
	global_store_dwordx4 v[40:41], v[36:39], off offset:-512
	s_nop 1
	v_cvt_pk_bf16_f32 v36, v44, v45
	v_cvt_pk_bf16_f32 v37, v46, v47
	v_cvt_pk_bf16_f32 v38, v48, v49
	v_mfma_f32_32x32x16_bf16 v[4:19], v[24:27], v[104:107], v[4:19]
	v_cvt_pk_bf16_f32 v39, v50, v51
	v_mfma_f32_32x32x16_bf16 v[4:19], v[32:35], v[108:111], v[4:19]
	v_mfma_f32_32x32x16_bf16 v[20:35], v[28:31], v[96:99], 0
	s_nop 10
	v_cvt_pk_bf16_f32 v4, v4, v5
	v_cvt_pk_bf16_f32 v5, v6, v7
	v_cvt_pk_bf16_f32 v6, v8, v9
	v_cvt_pk_bf16_f32 v7, v10, v11
	v_mfma_f32_32x32x16_bf16 v[20:35], v[64:67], v[100:103], v[20:35]
	v_add_co_u32_e32 v64, vcc, s20, v166
	s_movk_i32 s20, 0x8000
	s_nop 0
	v_addc_co_u32_e32 v65, vcc, -1, v167, vcc
	global_store_dwordx4 v[64:65], v[36:39], off offset:-3584
	global_store_dwordx4 v[64:65], v[4:7], off offset:-2560
	v_mfma_f32_32x32x16_bf16 v[20:35], v[68:71], v[104:107], v[20:35]
	s_nop 0
	v_cvt_pk_bf16_f32 v4, v12, v13
	v_cvt_pk_bf16_f32 v5, v14, v15
	v_cvt_pk_bf16_f32 v6, v16, v17
	v_cvt_pk_bf16_f32 v7, v18, v19
	global_store_dwordx4 v[64:65], v[4:7], off offset:-1536
	v_mfma_f32_32x32x16_bf16 v[36:51], v[76:79], v[96:99], 0
	v_mfma_f32_32x32x16_bf16 v[36:51], v[80:83], v[100:103], v[36:51]
	v_mfma_f32_32x32x16_bf16 v[36:51], v[84:87], v[104:107], v[36:51]
	v_mfma_f32_32x32x16_bf16 v[20:35], v[72:75], v[108:111], v[20:35]
	v_add_co_u32_e32 v72, vcc, s20, v166
	s_nop 1
	v_addc_co_u32_e32 v73, vcc, -1, v167, vcc
	v_add_co_u32_e32 v66, vcc, s3, v54
	s_waitcnt vmcnt(4)
	v_mfma_f32_32x32x16_bf16 v[36:51], v[92:95], v[108:111], v[36:51]
	s_nop 4
	v_cvt_pk_bf16_f32 v4, v20, v21
	v_cvt_pk_bf16_f32 v5, v22, v23
	v_cvt_pk_bf16_f32 v6, v24, v25
	v_cvt_pk_bf16_f32 v7, v26, v27
	global_store_dwordx4 v[64:65], v[4:7], off offset:-512
	v_addc_co_u32_e32 v67, vcc, 0, v55, vcc
	s_nop 0
	v_cvt_pk_bf16_f32 v4, v28, v29
	v_cvt_pk_bf16_f32 v5, v30, v31
	v_cvt_pk_bf16_f32 v6, v32, v33
	v_cvt_pk_bf16_f32 v7, v34, v35
	global_store_dwordx4 v[72:73], v[4:7], off offset:-3584
	v_add_co_u32_e32 v64, vcc, s16, v54
	s_nop 0
	v_cvt_pk_bf16_f32 v4, v36, v37
	v_cvt_pk_bf16_f32 v5, v38, v39
	v_cvt_pk_bf16_f32 v6, v40, v41
	v_cvt_pk_bf16_f32 v7, v42, v43
	global_store_dwordx4 v[72:73], v[4:7], off offset:-2560
	v_addc_co_u32_e32 v65, vcc, 0, v55, vcc
	s_nop 0
	v_cvt_pk_bf16_f32 v4, v44, v45
	v_cvt_pk_bf16_f32 v5, v46, v47
	v_cvt_pk_bf16_f32 v6, v48, v49
	v_cvt_pk_bf16_f32 v7, v50, v51
	global_store_dwordx4 v[72:73], v[4:7], off offset:-1536
	v_add_co_u32_e32 v68, vcc, s17, v54
	global_load_dwordx4 v[4:7], v[54:55], off
	global_load_dwordx4 v[8:11], v[54:55], off offset:1024
	global_load_dwordx4 v[12:15], v[54:55], off offset:2048
	global_load_dwordx4 v[16:19], v[54:55], off offset:3072
	global_load_dwordx4 v[20:23], v[66:67], off offset:1024
	global_load_dwordx4 v[24:27], v[66:67], off offset:2048
	global_load_dwordx4 v[28:31], v[64:65], off
	global_load_dwordx4 v[74:77], v[64:65], off offset:1024
	global_load_dwordx4 v[78:81], v[64:65], off offset:2048
	global_load_dwordx4 v[82:85], v[64:65], off offset:3072
	v_addc_co_u32_e32 v69, vcc, 0, v55, vcc
	global_load_dwordx4 v[32:35], v[66:67], off offset:3072
	global_load_dwordx4 v[86:89], v[68:69], off
	global_load_dwordx4 v[90:93], v[68:69], off offset:1024
	global_load_dwordx4 v[94:97], v[68:69], off offset:2048
	global_load_dwordx4 v[98:101], v[64:65], off offset:-4096
	global_load_dwordx4 v[102:105], v[68:69], off offset:3072
	v_add_u32_e32 v36, 0x2000, v112
	ds_read2_b64 v[106:109], v36 offset0:64 offset1:66
	ds_read2_b64 v[110:113], v36 offset0:68 offset1:70
	ds_read2_b64 v[114:117], v36 offset0:72 offset1:74
	ds_read2_b64 v[118:121], v36 offset0:76 offset1:78
	s_waitcnt vmcnt(0)
; __device__ __forceinline__ void dk_phase(const Frame& F, const bf16* QKrm, const unsigned char* KT, const unsigned char* VT, const float* BG, unsigned char* ITEMS) {
;     ...
;         for (int mt = 0; mt < 2; ++mt) {
;             bf16x8_t tb[2][2];
; #pragma unroll
;             for (int tt = 0; tt < 2; ++tt)
; #pragma unroll
;                 for (int s = 0; s < 2; ++s) { const LAS unsigned char* p = TW + (32 * mt + r32) * TROW + (32 * tt + 16 * s + 4 * hi) * 2;
;                     const v2u lo = *(const LAS v2u*)p, hi2 = *(const LAS v2u*)(p + 16); tb[tt][s] = as_frag((v4u){lo.x, lo.y, hi2.x, hi2.y}); }
;             bf16x8_t gf[16];
; #pragma unroll
;             for (int k = 0; k < 16; ++k) gf[k] = as_frag(*(const v4u*)(ktb + k * 1024 + lane * 16));
;             asm volatile("s_waitcnt vmcnt(0)" ::: "memory"); __builtin_amdgcn_sched_barrier(0);
; #pragma unroll
;             for (int dt = 0; dt < 4; ++dt) { f32x16_t acc = f32x16_t{};
; #pragma unroll
;                 for (int tt = 0; tt < 2; ++tt)
; #pragma unroll
;                     for (int s = 0; s < 2; ++s) { const bf16x8_t a = gf[(dt * 2 + tt) * 2 + s];
;                         acc = __builtin_amdgcn_mfma_f32_32x32x16_bf16(a, tb[tt][s], acc, 0, 0, 0); }
; #pragma unroll
;                 for (int st = 0; st < 2; ++st) { v4u wv; wv.x = pk2(acc[8 * st + 0], acc[8 * st + 1]); wv.y = pk2(acc[8 * st + 2], acc[8 * st + 3]); wv.z = pk2(acc[8 * st + 4], acc[8 * st + 5]); wv.w = pk2(acc[8 * st + 6], acc[8 * st + 7]);
;                     *(v4u*)(item + ITEM_W + ((mt * 4 + dt) * 2 + st) * 1024 + lane * 16) = wv; } }
;             bf16x8_t ta[2][2];
; #pragma unroll
;             for (int tt = 0; tt < 2; ++tt)
; #pragma unroll
;                 for (int s = 0; s < 2; ++s) { const LAS unsigned char* p = TU + (32 * mt + r32) * TROW + (32 * tt + 16 * s + 4 * hi) * 2;
;                     const v2u lo = *(const LAS v2u*)p, hi2 = *(const LAS v2u*)(p + 16); ta[tt][s] = as_frag((v4u){lo.x, lo.y, hi2.x, hi2.y}); }
; #pragma unroll
;             for (int k = 0; k < 16; ++k) gf[k] = as_frag(*(const v4u*)(vtb + k * 1024 + lane * 16));
;             asm volatile("s_waitcnt vmcnt(0)" ::: "memory"); __builtin_amdgcn_sched_barrier(0);
; #pragma unroll
;             for (int vt = 0; vt < 4; ++vt) { f32x16_t acc = f32x16_t{};
; #pragma unroll
;                 for (int tt = 0; tt < 2; ++tt)
; #pragma unroll
	s_waitcnt vmcnt(15) lgkmcnt(3)
	v_mfma_f32_32x32x16_bf16 v[36:51], v[106:109], v[4:7], 0
	s_movk_i32 s20, 0xd000
	v_mad_u32_u24 v2, v187, s21, v2
	s_waitcnt vmcnt(14) lgkmcnt(2)
	v_mfma_f32_32x32x16_bf16 v[36:51], v[110:113], v[8:11], v[36:51]
	s_waitcnt vmcnt(13) lgkmcnt(1)
	v_mfma_f32_32x32x16_bf16 v[36:51], v[114:117], v[12:15], v[36:51]
	s_waitcnt vmcnt(12) lgkmcnt(0)
	v_mfma_f32_32x32x16_bf16 v[36:51], v[118:121], v[16:19], v[36:51]
	s_waitcnt vmcnt(1)
	v_mfma_f32_32x32x16_bf16 v[4:19], v[106:109], v[98:101], 0
	s_nop 9
	v_cvt_pk_bf16_f32 v36, v36, v37
	v_cvt_pk_bf16_f32 v37, v38, v39
	v_cvt_pk_bf16_f32 v38, v40, v41
	v_cvt_pk_bf16_f32 v40, v44, v45
	v_add_co_u32_e32 v44, vcc, s90, v52
	v_cvt_pk_bf16_f32 v39, v42, v43
	v_mfma_f32_32x32x16_bf16 v[4:19], v[110:113], v[20:23], v[4:19]
	v_cvt_pk_bf16_f32 v41, v46, v47
	v_cvt_pk_bf16_f32 v42, v48, v49
	v_cvt_pk_bf16_f32 v43, v50, v51
	v_addc_co_u32_e32 v45, vcc, -1, v53, vcc
	global_store_dwordx4 v[44:45], v[36:39], off offset:-512
	global_store_dwordx4 v[44:45], v[40:43], off offset:-496
	v_add_co_u32_e32 v70, vcc, s20, v52
	v_mfma_f32_32x32x16_bf16 v[4:19], v[114:117], v[24:27], v[4:19]
	s_nop 0
	v_addc_co_u32_e32 v71, vcc, -1, v53, vcc
	s_movk_i32 s20, 0xe000
	v_mfma_f32_32x32x16_bf16 v[4:19], v[118:121], v[32:35], v[4:19]
	v_mfma_f32_32x32x16_bf16 v[20:35], v[106:109], v[28:31], 0
	s_nop 10
	v_cvt_pk_bf16_f32 v4, v4, v5
	v_cvt_pk_bf16_f32 v5, v6, v7
	v_cvt_pk_bf16_f32 v6, v8, v9
	v_cvt_pk_bf16_f32 v7, v10, v11
	v_cvt_pk_bf16_f32 v8, v12, v13
	v_cvt_pk_bf16_f32 v9, v14, v15
	v_cvt_pk_bf16_f32 v10, v16, v17
	v_mfma_f32_32x32x16_bf16 v[36:51], v[106:109], v[86:89], 0
	v_cvt_pk_bf16_f32 v11, v18, v19
	global_store_dwordx4 v[70:71], v[4:7], off offset:-512
	global_store_dwordx4 v[70:71], v[8:11], off offset:-496
	v_mfma_f32_32x32x16_bf16 v[20:35], v[110:113], v[74:77], v[20:35]
	v_add_co_u32_e32 v74, vcc, s20, v52
	s_movk_i32 s20, 0xf000
	s_nop 0
	v_addc_co_u32_e32 v75, vcc, -1, v53, vcc
	v_add_co_u32_e32 v76, vcc, s20, v52
	v_mfma_f32_32x32x16_bf16 v[36:51], v[110:113], v[90:93], v[36:51]
	s_nop 0
	v_addc_co_u32_e32 v77, vcc, -1, v53, vcc
	v_mfma_f32_32x32x16_bf16 v[20:35], v[114:117], v[78:81], v[20:35]
	v_mfma_f32_32x32x16_bf16 v[36:51], v[114:117], v[94:97], v[36:51]
	v_mfma_f32_32x32x16_bf16 v[20:35], v[118:121], v[82:85], v[20:35]
	s_waitcnt vmcnt(4)
	v_mfma_f32_32x32x16_bf16 v[36:51], v[118:121], v[102:105], v[36:51]
	s_nop 9
	v_cvt_pk_bf16_f32 v4, v20, v21
	v_cvt_pk_bf16_f32 v5, v22, v23
	v_cvt_pk_bf16_f32 v6, v24, v25
	v_cvt_pk_bf16_f32 v7, v26, v27
	v_cvt_pk_bf16_f32 v8, v28, v29
	v_cvt_pk_bf16_f32 v9, v30, v31
	v_cvt_pk_bf16_f32 v10, v32, v33
	v_cvt_pk_bf16_f32 v11, v34, v35
	global_store_dwordx4 v[74:75], v[4:7], off offset:-512
	global_store_dwordx4 v[74:75], v[8:11], off offset:-496
	s_nop 0
	v_cvt_pk_bf16_f32 v4, v36, v37
	v_cvt_pk_bf16_f32 v5, v38, v39
	v_cvt_pk_bf16_f32 v6, v40, v41
	v_cvt_pk_bf16_f32 v7, v42, v43
	v_cvt_pk_bf16_f32 v8, v44, v45
	v_cvt_pk_bf16_f32 v9, v46, v47
	v_cvt_pk_bf16_f32 v10, v48, v49
	v_cvt_pk_bf16_f32 v11, v50, v51
	global_store_dwordx4 v[76:77], v[4:7], off offset:-512
	global_store_dwordx4 v[76:77], v[8:11], off offset:-496
	global_load_dwordx4 v[4:7], v[56:57], off
	s_nop 0
	global_load_dwordx4 v[8:11], v[56:57], off offset:1024
	global_load_dwordx4 v[12:15], v[56:57], off offset:2048
	global_load_dwordx4 v[16:19], v[56:57], off offset:3072
	global_load_dwordx4 v[36:39], v[60:61], off offset:1024
	global_load_dwordx4 v[40:43], v[60:61], off offset:2048
	global_load_dwordx4 v[44:47], v[60:61], off offset:3072
	global_load_dwordx4 v[48:51], v[62:63], off offset:-4096
	global_load_dwordx4 v[78:81], v[58:59], off offset:-4096
	global_load_dwordx4 v[82:85], v[58:59], off offset:1024
	global_load_dwordx4 v[86:89], v[58:59], off offset:2048
	s_nop 0
	global_load_dwordx4 v[56:59], v[58:59], off offset:3072
	s_nop 0
	global_load_dwordx4 v[90:93], v[62:63], off
	global_load_dwordx4 v[94:97], v[62:63], off offset:1024
	global_load_dwordx4 v[98:101], v[62:63], off offset:2048
	s_nop 0
	global_load_dwordx4 v[60:63], v[62:63], off offset:3072
	ds_read2_b64 v[102:105], v2 offset1:2
	ds_read2_b64 v[106:109], v2 offset0:4 offset1:6
	ds_read2_b64 v[110:113], v2 offset0:8 offset1:10
	ds_read2_b64 v[114:117], v2 offset0:12 offset1:14
	s_waitcnt vmcnt(0)
	s_waitcnt vmcnt(15) lgkmcnt(3)
	v_mfma_f32_32x32x16_bf16 v[20:35], v[4:7], v[102:105], 0
	s_movk_i32 s20, 0x9000
	v_add_u32_e32 v2, 0x2000, v2
	s_waitcnt vmcnt(14) lgkmcnt(2)
	v_mfma_f32_32x32x16_bf16 v[20:35], v[8:11], v[106:109], v[20:35]
	s_waitcnt vmcnt(13) lgkmcnt(1)
	v_mfma_f32_32x32x16_bf16 v[20:35], v[12:15], v[110:113], v[20:35]
	s_waitcnt vmcnt(12) lgkmcnt(0)
	v_mfma_f32_32x32x16_bf16 v[20:35], v[16:19], v[114:117], v[20:35]
	s_waitcnt vmcnt(7)
	v_mfma_f32_32x32x16_bf16 v[4:19], v[78:81], v[102:105], 0
	s_nop 9
	v_cvt_pk_bf16_f32 v20, v20, v21
	v_cvt_pk_bf16_f32 v21, v22, v23
	v_cvt_pk_bf16_f32 v22, v24, v25
	v_cvt_pk_bf16_f32 v23, v26, v27
	global_store_dwordx4 v[72:73], v[20:23], off offset:-512
	v_cvt_pk_bf16_f32 v78, v28, v29
	v_cvt_pk_bf16_f32 v79, v30, v31
	v_mfma_f32_32x32x16_bf16 v[4:19], v[36:39], v[106:109], v[4:19]
	v_cvt_pk_bf16_f32 v80, v32, v33
	v_cvt_pk_bf16_f32 v81, v34, v35
	v_mfma_f32_32x32x16_bf16 v[4:19], v[40:43], v[110:113], v[4:19]
	v_mfma_f32_32x32x16_bf16 v[4:19], v[44:47], v[114:117], v[4:19]
	v_mfma_f32_32x32x16_bf16 v[36:51], v[48:51], v[102:105], 0
	s_nop 10
	v_cvt_pk_bf16_f32 v4, v4, v5
	v_cvt_pk_bf16_f32 v5, v6, v7
	v_cvt_pk_bf16_f32 v6, v8, v9
	v_cvt_pk_bf16_f32 v7, v10, v11
	s_waitcnt vmcnt(4)
; #define LAS __attribute__((address_space(3)))
; #define LDS_WAIT() asm volatile("s_waitcnt lgkmcnt(0)" ::: "memory")
; __device__ __forceinline__ unsigned pk2(float lo, float hi) { const f32x2_cv v = {lo, hi}; const bf16x2_cv b = __builtin_convertvector(v, bf16x2_cv); return __builtin_bit_cast(unsigned, b); }
; __device__ __forceinline__ void dk_phase(const Frame& F, const bf16* QKrm, const unsigned char* KT, const unsigned char* VT, const float* BG, unsigned char* ITEMS) {
;     ...
;             bf16x8_t ta[2][2];
; #pragma unroll
;             for (int tt = 0; tt < 2; ++tt)
; #pragma unroll
;                 for (int s = 0; s < 2; ++s) { const LAS unsigned char* p = TU + (32 * mt + r32) * TROW + (32 * tt + 16 * s + 4 * hi) * 2;
;                     const v2u lo = *(const LAS v2u*)p, hi2 = *(const LAS v2u*)(p + 16); ta[tt][s] = as_frag((v4u){lo.x, lo.y, hi2.x, hi2.y}); }
; #pragma unroll
;             for (int k = 0; k < 16; ++k) gf[k] = as_frag(*(const v4u*)(vtb + k * 1024 + lane * 16));
;             asm volatile("s_waitcnt vmcnt(0)" ::: "memory"); __builtin_amdgcn_sched_barrier(0);
; #pragma unroll
;             for (int vt = 0; vt < 4; ++vt) { f32x16_t acc = f32x16_t{};
; #pragma unroll
;                 for (int tt = 0; tt < 2; ++tt)
; #pragma unroll
;                     for (int s = 0; s < 2; ++s) { const bf16x8_t b = gf[(vt * 2 + tt) * 2 + s];
;                         acc = __builtin_amdgcn_mfma_f32_32x32x16_bf16(ta[tt][s], b, acc, 0, 0, 0); }
;                 v4u w0, w1; w0.x = pk2(acc[0], acc[1]); w0.y = pk2(acc[2], acc[3]); w0.z = pk2(acc[4], acc[5]); w0.w = pk2(acc[6], acc[7]);
;                 w1.x = pk2(acc[8], acc[9]); w1.y = pk2(acc[10], acc[11]); w1.z = pk2(acc[12], acc[13]); w1.w = pk2(acc[14], acc[15]);
;                 unsigned char* d = item + ITEM_U + (vt * 2 + mt) * 2048 + lane * 32;
;                 *(v4u*)d = w0; *(v4u*)(d + 16) = w1; }
;         }
;         LDS_WAIT();
;     }
	v_mfma_f32_32x32x16_bf16 v[20:35], v[90:93], v[102:105], 0
	v_mfma_f32_32x32x16_bf16 v[36:51], v[82:85], v[106:109], v[36:51]
	s_waitcnt vmcnt(3)
	v_mfma_f32_32x32x16_bf16 v[20:35], v[94:97], v[106:109], v[20:35]
	v_mfma_f32_32x32x16_bf16 v[36:51], v[86:89], v[110:113], v[36:51]
	s_waitcnt vmcnt(2)
	v_mfma_f32_32x32x16_bf16 v[20:35], v[98:101], v[110:113], v[20:35]
	v_mfma_f32_32x32x16_bf16 v[36:51], v[56:59], v[114:117], v[36:51]
	v_add_co_u32_e32 v56, vcc, s20, v166
	s_nop 1
	v_addc_co_u32_e32 v57, vcc, -1, v167, vcc
	global_store_dwordx4 v[56:57], v[4:7], off offset:-2560
	global_store_dwordx4 v[56:57], v[78:81], off offset:-3584
	s_waitcnt vmcnt(3)
	v_mfma_f32_32x32x16_bf16 v[20:35], v[60:63], v[114:117], v[20:35]
	v_cvt_pk_bf16_f32 v4, v12, v13
	v_cvt_pk_bf16_f32 v5, v14, v15
	v_cvt_pk_bf16_f32 v6, v16, v17
	v_cvt_pk_bf16_f32 v7, v18, v19
	global_store_dwordx4 v[56:57], v[4:7], off offset:-1536
	s_nop 1
	v_cvt_pk_bf16_f32 v4, v36, v37
	v_cvt_pk_bf16_f32 v5, v38, v39
	v_cvt_pk_bf16_f32 v6, v40, v41
	v_cvt_pk_bf16_f32 v7, v42, v43
	global_store_dwordx4 v[56:57], v[4:7], off offset:-512
	s_nop 1
	v_cvt_pk_bf16_f32 v4, v44, v45
	v_cvt_pk_bf16_f32 v5, v46, v47
	v_cvt_pk_bf16_f32 v6, v48, v49
	v_cvt_pk_bf16_f32 v7, v50, v51
	global_store_dwordx4 v[170:171], v[4:7], off offset:-3584
	s_nop 1
	v_cvt_pk_bf16_f32 v4, v20, v21
	v_cvt_pk_bf16_f32 v5, v22, v23
	v_cvt_pk_bf16_f32 v6, v24, v25
	v_cvt_pk_bf16_f32 v7, v26, v27
	global_store_dwordx4 v[170:171], v[4:7], off offset:-2560
	s_nop 1
	v_cvt_pk_bf16_f32 v4, v28, v29
	v_cvt_pk_bf16_f32 v5, v30, v31
	v_cvt_pk_bf16_f32 v6, v32, v33
	v_cvt_pk_bf16_f32 v7, v34, v35
	global_store_dwordx4 v[170:171], v[4:7], off offset:-1536
	global_load_dwordx4 v[4:7], v[54:55], off
	s_nop 0
	global_load_dwordx4 v[8:11], v[54:55], off offset:1024
	global_load_dwordx4 v[12:15], v[54:55], off offset:2048
	global_load_dwordx4 v[16:19], v[54:55], off offset:3072
	global_load_dwordx4 v[36:39], v[66:67], off offset:1024
	global_load_dwordx4 v[40:43], v[66:67], off offset:2048
	global_load_dwordx4 v[44:47], v[66:67], off offset:3072
	global_load_dwordx4 v[48:51], v[68:69], off offset:-4096
	s_nop 0
	global_load_dwordx4 v[54:57], v[64:65], off offset:-4096
	global_load_dwordx4 v[58:61], v[64:65], off offset:1024
	global_load_dwordx4 v[78:81], v[64:65], off offset:2048
	s_nop 0
	global_load_dwordx4 v[62:65], v[64:65], off offset:3072
	s_nop 0
	global_load_dwordx4 v[82:85], v[68:69], off
	global_load_dwordx4 v[86:89], v[68:69], off offset:1024
	global_load_dwordx4 v[90:93], v[68:69], off offset:2048
	s_nop 0
	global_load_dwordx4 v[66:69], v[68:69], off offset:3072
	ds_read2_b64 v[94:97], v2 offset0:64 offset1:66
	ds_read2_b64 v[98:101], v2 offset0:68 offset1:70
	ds_read2_b64 v[102:105], v2 offset0:72 offset1:74
	ds_read2_b64 v[106:109], v2 offset0:76 offset1:78
	s_waitcnt vmcnt(0)
	s_waitcnt vmcnt(15) lgkmcnt(3)
	v_mfma_f32_32x32x16_bf16 v[20:35], v[94:97], v[4:7], 0
	s_add_i32 s52, s52, s64
	s_mul_i32 s20, s50, 0x52000
	s_add_u32 s18, s18, s20
	s_mul_hi_i32 s20, s64, 0xa400
	s_addc_u32 s19, s19, s20
	s_cmpk_lt_i32 s52, 0x4100
	s_waitcnt vmcnt(14) lgkmcnt(2)
	v_mfma_f32_32x32x16_bf16 v[20:35], v[98:101], v[8:11], v[20:35]
	s_waitcnt vmcnt(13) lgkmcnt(1)
	v_mfma_f32_32x32x16_bf16 v[20:35], v[102:105], v[12:15], v[20:35]
	s_waitcnt vmcnt(12) lgkmcnt(0)
	v_mfma_f32_32x32x16_bf16 v[20:35], v[106:109], v[16:19], v[20:35]
	s_waitcnt vmcnt(7)
	v_mfma_f32_32x32x16_bf16 v[4:19], v[94:97], v[54:57], 0
	s_nop 9
	v_cvt_pk_bf16_f32 v20, v20, v21
	v_cvt_pk_bf16_f32 v21, v22, v23
	v_cvt_pk_bf16_f32 v22, v24, v25
	v_cvt_pk_bf16_f32 v23, v26, v27
	v_cvt_pk_bf16_f32 v54, v28, v29
	v_cvt_pk_bf16_f32 v55, v30, v31
	v_cvt_pk_bf16_f32 v56, v32, v33
	v_mfma_f32_32x32x16_bf16 v[4:19], v[98:101], v[36:39], v[4:19]
	v_cvt_pk_bf16_f32 v57, v34, v35
	global_store_dwordx4 v[70:71], v[20:23], off offset:-2560
	global_store_dwordx4 v[70:71], v[54:57], off offset:-2544
	v_mfma_f32_32x32x16_bf16 v[4:19], v[102:105], v[40:43], v[4:19]
	v_mfma_f32_32x32x16_bf16 v[4:19], v[106:109], v[44:47], v[4:19]
	v_mfma_f32_32x32x16_bf16 v[36:51], v[94:97], v[48:51], 0
	s_nop 10
	v_cvt_pk_bf16_f32 v4, v4, v5
	v_cvt_pk_bf16_f32 v5, v6, v7
	v_cvt_pk_bf16_f32 v6, v8, v9
	v_cvt_pk_bf16_f32 v7, v10, v11
	v_cvt_pk_bf16_f32 v8, v12, v13
	v_cvt_pk_bf16_f32 v9, v14, v15
	v_cvt_pk_bf16_f32 v10, v16, v17
	s_waitcnt vmcnt(5)
	v_mfma_f32_32x32x16_bf16 v[20:35], v[94:97], v[82:85], 0
	v_cvt_pk_bf16_f32 v11, v18, v19
	global_store_dwordx4 v[74:75], v[4:7], off offset:-2560
	global_store_dwordx4 v[74:75], v[8:11], off offset:-2544
	v_mfma_f32_32x32x16_bf16 v[36:51], v[98:101], v[58:61], v[36:51]
	s_waitcnt vmcnt(6)
	v_mfma_f32_32x32x16_bf16 v[20:35], v[98:101], v[86:89], v[20:35]
	v_mfma_f32_32x32x16_bf16 v[36:51], v[102:105], v[78:81], v[36:51]
	s_waitcnt vmcnt(5)
	v_mfma_f32_32x32x16_bf16 v[20:35], v[102:105], v[90:93], v[20:35]
	v_mfma_f32_32x32x16_bf16 v[36:51], v[106:109], v[62:65], v[36:51]
	s_waitcnt vmcnt(4)
	v_mfma_f32_32x32x16_bf16 v[20:35], v[106:109], v[66:69], v[20:35]
	s_nop 9
	v_cvt_pk_bf16_f32 v4, v36, v37
	v_cvt_pk_bf16_f32 v5, v38, v39
	v_cvt_pk_bf16_f32 v6, v40, v41
	v_cvt_pk_bf16_f32 v7, v42, v43
	v_cvt_pk_bf16_f32 v8, v44, v45
	v_cvt_pk_bf16_f32 v9, v46, v47
	v_cvt_pk_bf16_f32 v10, v48, v49
	v_cvt_pk_bf16_f32 v11, v50, v51
	global_store_dwordx4 v[76:77], v[4:7], off offset:-2560
	global_store_dwordx4 v[76:77], v[8:11], off offset:-2544
	s_nop 0
	v_cvt_pk_bf16_f32 v4, v20, v21
	v_cvt_pk_bf16_f32 v5, v22, v23
	v_cvt_pk_bf16_f32 v6, v24, v25
	v_cvt_pk_bf16_f32 v7, v26, v27
	v_cvt_pk_bf16_f32 v8, v28, v29
	v_cvt_pk_bf16_f32 v9, v30, v31
	v_cvt_pk_bf16_f32 v10, v32, v33
	v_cvt_pk_bf16_f32 v11, v34, v35
	global_store_dwordx4 v[52:53], v[4:7], off offset:-2560
	global_store_dwordx4 v[52:53], v[8:11], off offset:-2544
	s_waitcnt lgkmcnt(0)
	s_cbranch_scc0 .LBB0_595
